# GEMM K-loops: accumulate-chain MFMA order - the two k-step MFMAs of each accumulator issued back to back (D forwarded into the next C), accumulators visited in snake order; replaces the plain snake or
# speedup vs baseline: 1.0155x; 1.0155x over previous
; #define PG8_STAGE(bufoff, gbase, voff) do { _Pragma("unroll") for (int _i = 0; _i < 2; ++_i) \
;         __builtin_amdgcn_global_load_lds((const unsigned*)((const char*)(gbase) + (voff)[_i]), (PG8_LAS unsigned*)(lds + (bufoff) + ldsw + _i * 8192), 16, 0, 0); } while (0)
; #define PG8_LDA(dst, b, h) do { _Pragma("unroll") for (int m = 0; m < 4; ++m) _Pragma("unroll") for (int k = 0; k < 2; ++k) dst[m][k] = *(const PG8_LAS bf16x8*)(lds + PG8_SA(b, h) + aoff + m * 2048 + k * 1024); } while (0)
; #define PG8_LDB(dst, b, h) do { _Pragma("unroll") for (int n = 0; n < 2; ++n) _Pragma("unroll") for (int k = 0; k < 2; ++k) dst[n][k] = *(const PG8_LAS bf16x8*)(lds + PG8_SB(b, h) + boff + n * 2048 + k * 1024); } while (0)
; #define PG8_MMA(ai, bj, At, Bt) do { __builtin_amdgcn_s_setprio(1); _Pragma("unroll") for (int m = 0; m < 4; ++m) _Pragma("unroll") for (int n = 0; n < 2; ++n) _Pragma("unroll") for (int k = 0; k < 2; ++k) \
;         acc[ai][bj][m][n] = __builtin_amdgcn_mfma_f32_16x16x32_bf16(Bt[n][k], At[m][k], acc[ai][bj][m][n], 0, 0, 0); __builtin_amdgcn_s_setprio(0); } while (0)
; #define PG8_WAIT_V(n) asm volatile("s_waitcnt vmcnt(" #n ")" ::: "memory")
; #define PG8_WAIT_L(n) asm volatile("s_waitcnt lgkmcnt(" #n ")" ::: "memory")
; #define PG8_BAR __builtin_amdgcn_s_barrier()
; #define PG8_SCHED __builtin_amdgcn_sched_barrier(0)
; template <class Epi, class Sched, bool ALIGN_EPI = false, bool SP2 = false>
; __device__ __forceinline__ void gemm_phase(PG8_LAS unsigned char* lds, const Gemm g, const Sched& S, const Epi& E) {
;     ...
;             const bool last = (t == nt - 2);
;             const char* a1 = cA + (size_t)(t + 1) * kstep;
;             const char* a2 = last ? nA : cA + (size_t)(t + 2) * kstep; const char* b2 = last ? nB : cB + (size_t)(t + 2) * kstep;
;             const char* a3 = a2 + kstep; const char* b3 = b2 + kstep;
;             if (last && has_next) S.a_ready(nxt);
;             if constexpr (SP2) {
;             PG8_LDB(B0, 0, 0); PG8_LDB(B1, 0, 1); PG8_SCHED; PG8_LDA(At, 0, 0); PG8_STAGE(PG8_SA(1, 1), a1 + hstep, voffA);
;             PG8_WAIT_V(8); PG8_WAIT_L(0); PG8_BAR; PG8_MMA(0, 0, At, B0); PG8_MMA(0, 1, At, B1); PG8_BAR; PG8_SCHED;
;             PG8_LDA(At, 0, 1); PG8_STAGE(PG8_SB(0, 0), b2, voffB); PG8_STAGE(PG8_SB(0, 1), b2 + hstep, voffB); PG8_STAGE(PG8_SA(0, 0), a2, voffA);
.LBB0_162:
	s_add_u32 s10, s44, 0xfffc0080
	s_addc_u32 s11, s45, -1
	s_add_i32 s60, 16, 0x10000
	s_cmp_eq_u32 s59, 12
	s_cselect_b32 s49, s27, s11
	s_cselect_b32 s48, s34, s10
	s_cselect_b32 s47, s25, s58
	s_cselect_b32 s46, s35, s57
	s_add_i32 s10, 16, 0x14000
	v_add_u32_e32 v102, s60, v183
	v_add_u32_e32 v180, s10, v183
	ds_read_b128 v[90:93], v102
	ds_read_b128 v[94:97], v102 offset:1024
	ds_read_b128 v[98:101], v102 offset:2048
	ds_read_b128 v[102:105], v102 offset:3072
	ds_read_b128 v[158:161], v180
	ds_read_b128 v[176:179], v180 offset:1024
	ds_read_b128 v[186:189], v180 offset:2048
	ds_read_b128 v[190:193], v180 offset:3072
	v_lshl_add_u64 v[180:181], s[44:45], 0, v[156:157]
	s_add_i32 m0, s7, 0xc000
	ds_read_b128 v[194:197], v185
	ds_read_b128 v[198:201], v185 offset:1024
	ds_read_b128 v[202:205], v185 offset:2048
	ds_read_b128 v[206:209], v185 offset:3072
	ds_read_b128 v[210:213], v185 offset:4096
	ds_read_b128 v[214:217], v185 offset:5120
	ds_read_b128 v[218:221], v185 offset:6144
	ds_read_b128 v[222:225], v185 offset:7168
	global_load_lds_dwordx4 v[180:181], off
	v_lshl_add_u64 v[180:181], s[44:45], 0, v[154:155]
	s_add_i32 m0, s7, 0xe000
	s_nop 0
	global_load_lds_dwordx4 v[180:181], off
	s_waitcnt vmcnt(8)
	s_waitcnt lgkmcnt(0)
	s_setprio 1
	s_barrier
	v_mfma_f32_16x16x32_bf16 v[142:145], v[90:93], v[194:197], v[142:145]
	v_mfma_f32_16x16x32_bf16 v[142:145], v[94:97], v[198:201], v[142:145]
	v_mfma_f32_16x16x32_bf16 v[138:141], v[98:101], v[194:197], v[138:141]
	v_mfma_f32_16x16x32_bf16 v[138:141], v[102:105], v[198:201], v[138:141]
	v_mfma_f32_16x16x32_bf16 v[122:125], v[98:101], v[202:205], v[122:125]
	v_mfma_f32_16x16x32_bf16 v[122:125], v[102:105], v[206:209], v[122:125]
	v_mfma_f32_16x16x32_bf16 v[126:129], v[90:93], v[202:205], v[126:129]
	v_mfma_f32_16x16x32_bf16 v[126:129], v[94:97], v[206:209], v[126:129]
	v_mfma_f32_16x16x32_bf16 v[110:113], v[90:93], v[210:213], v[110:113]
	v_mfma_f32_16x16x32_bf16 v[110:113], v[94:97], v[214:217], v[110:113]
	v_mfma_f32_16x16x32_bf16 v[106:109], v[98:101], v[210:213], v[106:109]
	v_mfma_f32_16x16x32_bf16 v[106:109], v[102:105], v[214:217], v[106:109]
	v_mfma_f32_16x16x32_bf16 v[74:77], v[98:101], v[218:221], v[74:77]
	v_mfma_f32_16x16x32_bf16 v[74:77], v[102:105], v[222:225], v[74:77]
	v_mfma_f32_16x16x32_bf16 v[78:81], v[90:93], v[218:221], v[78:81]
	v_mfma_f32_16x16x32_bf16 v[78:81], v[94:97], v[222:225], v[78:81]
	v_mfma_f32_16x16x32_bf16 v[134:137], v[158:161], v[194:197], v[134:137]
	v_mfma_f32_16x16x32_bf16 v[134:137], v[176:179], v[198:201], v[134:137]
	v_mfma_f32_16x16x32_bf16 v[130:133], v[186:189], v[194:197], v[130:133]
	v_mfma_f32_16x16x32_bf16 v[130:133], v[190:193], v[198:201], v[130:133]
	v_mfma_f32_16x16x32_bf16 v[114:117], v[186:189], v[202:205], v[114:117]
	v_mfma_f32_16x16x32_bf16 v[114:117], v[190:193], v[206:209], v[114:117]
	v_mfma_f32_16x16x32_bf16 v[118:121], v[158:161], v[202:205], v[118:121]
	v_mfma_f32_16x16x32_bf16 v[118:121], v[176:179], v[206:209], v[118:121]
	v_mfma_f32_16x16x32_bf16 v[86:89], v[158:161], v[210:213], v[86:89]
	v_mfma_f32_16x16x32_bf16 v[86:89], v[176:179], v[214:217], v[86:89]
	v_mfma_f32_16x16x32_bf16 v[82:85], v[186:189], v[210:213], v[82:85]
	v_mfma_f32_16x16x32_bf16 v[82:85], v[190:193], v[214:217], v[82:85]
	v_mfma_f32_16x16x32_bf16 v[66:69], v[186:189], v[218:221], v[66:69]
	v_mfma_f32_16x16x32_bf16 v[66:69], v[190:193], v[222:225], v[66:69]
	v_mfma_f32_16x16x32_bf16 v[70:73], v[158:161], v[218:221], v[70:73]
	v_mfma_f32_16x16x32_bf16 v[70:73], v[176:179], v[222:225], v[70:73]
	s_barrier
	s_setprio 0
	s_add_i32 s11, s60, s6
	v_lshl_add_u64 v[180:181], s[46:47], 0, v[0:1]
	s_mov_b32 m0, s11
	ds_read_b128 v[194:197], v185 offset:16384
	ds_read_b128 v[198:201], v185 offset:17408
	ds_read_b128 v[202:205], v185 offset:18432
	ds_read_b128 v[206:209], v185 offset:19456
	ds_read_b128 v[210:213], v185 offset:20480
	ds_read_b128 v[214:217], v185 offset:21504
	ds_read_b128 v[218:221], v185 offset:22528
	ds_read_b128 v[222:225], v185 offset:23552
	global_load_lds_dwordx4 v[180:181], off
	s_add_i32 m0, s11, 0x2000
	s_add_u32 s60, s46, 0x40000
	v_lshl_add_u64 v[226:227], s[46:47], 0, v[146:147]
	s_addc_u32 s61, s47, 0
	s_add_i32 s10, s10, s6
	global_load_lds_dwordx4 v[226:227], off
	v_lshl_add_u64 v[238:239], s[60:61], 0, v[0:1]
	s_mov_b32 m0, s10
	v_lshl_add_u64 v[240:241], s[48:49], 0, v[148:149]
	global_load_lds_dwordx4 v[238:239], off
	v_lshl_add_u64 v[238:239], s[60:61], 0, v[146:147]
	s_add_i32 m0, s10, 0x2000
	s_nop 0
	global_load_lds_dwordx4 v[238:239], off
	v_lshl_add_u64 v[238:239], s[48:49], 0, v[150:151]
	s_mov_b32 m0, s7
	s_nop 0
	global_load_lds_dwordx4 v[238:239], off
	s_mov_b32 m0, s8
	s_nop 0
	global_load_lds_dwordx4 v[240:241], off
	s_waitcnt vmcnt(8)
	s_waitcnt lgkmcnt(0)
	s_setprio 1
	s_barrier
; #define PG8_STAGE(bufoff, gbase, voff) do { _Pragma("unroll") for (int _i = 0; _i < 2; ++_i) \
;         __builtin_amdgcn_global_load_lds((const unsigned*)((const char*)(gbase) + (voff)[_i]), (PG8_LAS unsigned*)(lds + (bufoff) + ldsw + _i * 8192), 16, 0, 0); } while (0)
; #define PG8_LDA(dst, b, h) do { _Pragma("unroll") for (int m = 0; m < 4; ++m) _Pragma("unroll") for (int k = 0; k < 2; ++k) dst[m][k] = *(const PG8_LAS bf16x8*)(lds + PG8_SA(b, h) + aoff + m * 2048 + k * 1024); } while (0)
; #define PG8_LDB(dst, b, h) do { _Pragma("unroll") for (int n = 0; n < 2; ++n) _Pragma("unroll") for (int k = 0; k < 2; ++k) dst[n][k] = *(const PG8_LAS bf16x8*)(lds + PG8_SB(b, h) + boff + n * 2048 + k * 1024); } while (0)
; #define PG8_MMA(ai, bj, At, Bt) do { __builtin_amdgcn_s_setprio(1); _Pragma("unroll") for (int m = 0; m < 4; ++m) _Pragma("unroll") for (int n = 0; n < 2; ++n) _Pragma("unroll") for (int k = 0; k < 2; ++k) \
;         acc[ai][bj][m][n] = __builtin_amdgcn_mfma_f32_16x16x32_bf16(Bt[n][k], At[m][k], acc[ai][bj][m][n], 0, 0, 0); __builtin_amdgcn_s_setprio(0); } while (0)
; #define PG8_WAIT_V(n) asm volatile("s_waitcnt vmcnt(" #n ")" ::: "memory")
; #define PG8_WAIT_L(n) asm volatile("s_waitcnt lgkmcnt(" #n ")" ::: "memory")
; #define PG8_BAR __builtin_amdgcn_s_barrier()
; #define PG8_SCHED __builtin_amdgcn_sched_barrier(0)
; template <class Epi, class Sched, bool ALIGN_EPI = false, bool SP2 = false>
; __device__ __forceinline__ void gemm_phase(PG8_LAS unsigned char* lds, const Gemm g, const Sched& S, const Epi& E) {
;     ...
;             PG8_WAIT_V(8); PG8_WAIT_L(0); PG8_BAR; PG8_MMA(1, 0, At, B0); PG8_MMA(1, 1, At, B1); PG8_BAR; PG8_SCHED;
;             PG8_LDB(B0, 1, 0); PG8_LDB(B1, 1, 1); PG8_SCHED; PG8_LDA(At, 1, 0); PG8_STAGE(PG8_SA(0, 1), a2 + hstep, voffA);
;             PG8_WAIT_V(8); PG8_WAIT_L(0); PG8_BAR; PG8_MMA(0, 0, At, B0); PG8_MMA(0, 1, At, B1); PG8_BAR; PG8_SCHED;
	v_mfma_f32_16x16x32_bf16 v[62:65], v[90:93], v[194:197], v[62:65]
	v_mfma_f32_16x16x32_bf16 v[62:65], v[94:97], v[198:201], v[62:65]
	v_mfma_f32_16x16x32_bf16 v[58:61], v[98:101], v[194:197], v[58:61]
	v_mfma_f32_16x16x32_bf16 v[58:61], v[102:105], v[198:201], v[58:61]
	v_mfma_f32_16x16x32_bf16 v[42:45], v[98:101], v[202:205], v[42:45]
	v_mfma_f32_16x16x32_bf16 v[42:45], v[102:105], v[206:209], v[42:45]
	v_mfma_f32_16x16x32_bf16 v[46:49], v[90:93], v[202:205], v[46:49]
	v_mfma_f32_16x16x32_bf16 v[46:49], v[94:97], v[206:209], v[46:49]
	v_mfma_f32_16x16x32_bf16 v[30:33], v[90:93], v[210:213], v[30:33]
	v_mfma_f32_16x16x32_bf16 v[30:33], v[94:97], v[214:217], v[30:33]
	v_mfma_f32_16x16x32_bf16 v[26:29], v[98:101], v[210:213], v[26:29]
	v_mfma_f32_16x16x32_bf16 v[26:29], v[102:105], v[214:217], v[26:29]
	v_mfma_f32_16x16x32_bf16 v[10:13], v[98:101], v[218:221], v[10:13]
	v_mfma_f32_16x16x32_bf16 v[10:13], v[102:105], v[222:225], v[10:13]
	v_mfma_f32_16x16x32_bf16 v[14:17], v[90:93], v[218:221], v[14:17]
	v_mfma_f32_16x16x32_bf16 v[14:17], v[94:97], v[222:225], v[14:17]
	v_mfma_f32_16x16x32_bf16 v[54:57], v[158:161], v[194:197], v[54:57]
	v_mfma_f32_16x16x32_bf16 v[54:57], v[176:179], v[198:201], v[54:57]
	v_mfma_f32_16x16x32_bf16 v[50:53], v[186:189], v[194:197], v[50:53]
	v_mfma_f32_16x16x32_bf16 v[50:53], v[190:193], v[198:201], v[50:53]
	v_mfma_f32_16x16x32_bf16 v[34:37], v[186:189], v[202:205], v[34:37]
	v_mfma_f32_16x16x32_bf16 v[34:37], v[190:193], v[206:209], v[34:37]
	v_mfma_f32_16x16x32_bf16 v[38:41], v[158:161], v[202:205], v[38:41]
	v_mfma_f32_16x16x32_bf16 v[38:41], v[176:179], v[206:209], v[38:41]
	v_mfma_f32_16x16x32_bf16 v[22:25], v[158:161], v[210:213], v[22:25]
	v_mfma_f32_16x16x32_bf16 v[22:25], v[176:179], v[214:217], v[22:25]
	v_mfma_f32_16x16x32_bf16 v[18:21], v[186:189], v[210:213], v[18:21]
	v_mfma_f32_16x16x32_bf16 v[18:21], v[190:193], v[214:217], v[18:21]
	v_mfma_f32_16x16x32_bf16 v[2:5], v[186:189], v[218:221], v[2:5]
	v_mfma_f32_16x16x32_bf16 v[2:5], v[190:193], v[222:225], v[2:5]
	v_mfma_f32_16x16x32_bf16 v[6:9], v[158:161], v[218:221], v[6:9]
	v_mfma_f32_16x16x32_bf16 v[6:9], v[176:179], v[222:225], v[6:9]
	s_barrier
	s_setprio 0
	s_add_i32 s10, 16, 0x18000
	s_add_i32 s11, 16, 0x1c000
	v_add_u32_e32 v102, s10, v183
	v_add_u32_e32 v190, s11, v183
	ds_read_b128 v[90:93], v102
	ds_read_b128 v[94:97], v102 offset:1024
	ds_read_b128 v[98:101], v102 offset:2048
	ds_read_b128 v[102:105], v102 offset:3072
	ds_read_b128 v[158:161], v190
	ds_read_b128 v[176:179], v190 offset:1024
	ds_read_b128 v[186:189], v190 offset:2048
	ds_read_b128 v[190:193], v190 offset:3072
	s_add_u32 s48, s48, 0x40000
	s_addc_u32 s49, s49, 0
	s_mov_b32 m0, s9
	v_lshl_add_u64 v[242:243], s[48:49], 0, v[150:151]
	ds_read_b128 v[194:197], v185 offset:32768
	ds_read_b128 v[198:201], v185 offset:33792
	ds_read_b128 v[202:205], v185 offset:34816
	ds_read_b128 v[206:209], v185 offset:35840
	ds_read_b128 v[210:213], v185 offset:36864
	ds_read_b128 v[214:217], v185 offset:37888
	ds_read_b128 v[218:221], v185 offset:38912
	ds_read_b128 v[222:225], v185 offset:39936
	global_load_lds_dwordx4 v[242:243], off
	v_lshl_add_u64 v[242:243], s[48:49], 0, v[148:149]
	s_mov_b32 m0, s50
	s_nop 0
	global_load_lds_dwordx4 v[242:243], off
	s_waitcnt vmcnt(8)
	s_waitcnt lgkmcnt(0)
	s_setprio 1
	s_barrier
	v_mfma_f32_16x16x32_bf16 v[142:145], v[90:93], v[194:197], v[142:145]
	v_mfma_f32_16x16x32_bf16 v[142:145], v[94:97], v[198:201], v[142:145]
	v_mfma_f32_16x16x32_bf16 v[138:141], v[98:101], v[194:197], v[138:141]
	v_mfma_f32_16x16x32_bf16 v[138:141], v[102:105], v[198:201], v[138:141]
	v_mfma_f32_16x16x32_bf16 v[122:125], v[98:101], v[202:205], v[122:125]
	v_mfma_f32_16x16x32_bf16 v[122:125], v[102:105], v[206:209], v[122:125]
	v_mfma_f32_16x16x32_bf16 v[126:129], v[90:93], v[202:205], v[126:129]
	v_mfma_f32_16x16x32_bf16 v[126:129], v[94:97], v[206:209], v[126:129]
	v_mfma_f32_16x16x32_bf16 v[110:113], v[90:93], v[210:213], v[110:113]
	v_mfma_f32_16x16x32_bf16 v[110:113], v[94:97], v[214:217], v[110:113]
	v_mfma_f32_16x16x32_bf16 v[106:109], v[98:101], v[210:213], v[106:109]
	v_mfma_f32_16x16x32_bf16 v[106:109], v[102:105], v[214:217], v[106:109]
	v_mfma_f32_16x16x32_bf16 v[74:77], v[98:101], v[218:221], v[74:77]
	v_mfma_f32_16x16x32_bf16 v[74:77], v[102:105], v[222:225], v[74:77]
	v_mfma_f32_16x16x32_bf16 v[78:81], v[90:93], v[218:221], v[78:81]
	v_mfma_f32_16x16x32_bf16 v[78:81], v[94:97], v[222:225], v[78:81]
	v_mfma_f32_16x16x32_bf16 v[134:137], v[158:161], v[194:197], v[134:137]
	v_mfma_f32_16x16x32_bf16 v[134:137], v[176:179], v[198:201], v[134:137]
	v_mfma_f32_16x16x32_bf16 v[130:133], v[186:189], v[194:197], v[130:133]
	v_mfma_f32_16x16x32_bf16 v[130:133], v[190:193], v[198:201], v[130:133]
	v_mfma_f32_16x16x32_bf16 v[114:117], v[186:189], v[202:205], v[114:117]
	v_mfma_f32_16x16x32_bf16 v[114:117], v[190:193], v[206:209], v[114:117]
	v_mfma_f32_16x16x32_bf16 v[118:121], v[158:161], v[202:205], v[118:121]
	v_mfma_f32_16x16x32_bf16 v[118:121], v[176:179], v[206:209], v[118:121]
	v_mfma_f32_16x16x32_bf16 v[86:89], v[158:161], v[210:213], v[86:89]
	v_mfma_f32_16x16x32_bf16 v[86:89], v[176:179], v[214:217], v[86:89]
	v_mfma_f32_16x16x32_bf16 v[82:85], v[186:189], v[210:213], v[82:85]
	v_mfma_f32_16x16x32_bf16 v[82:85], v[190:193], v[214:217], v[82:85]
	v_mfma_f32_16x16x32_bf16 v[66:69], v[186:189], v[218:221], v[66:69]
	v_mfma_f32_16x16x32_bf16 v[66:69], v[190:193], v[222:225], v[66:69]
	v_mfma_f32_16x16x32_bf16 v[70:73], v[158:161], v[218:221], v[70:73]
	v_mfma_f32_16x16x32_bf16 v[70:73], v[176:179], v[222:225], v[70:73]
	s_barrier
; #define PG8_STAGE(bufoff, gbase, voff) do { _Pragma("unroll") for (int _i = 0; _i < 2; ++_i) \
;         __builtin_amdgcn_global_load_lds((const unsigned*)((const char*)(gbase) + (voff)[_i]), (PG8_LAS unsigned*)(lds + (bufoff) + ldsw + _i * 8192), 16, 0, 0); } while (0)
; #define PG8_LDA(dst, b, h) do { _Pragma("unroll") for (int m = 0; m < 4; ++m) _Pragma("unroll") for (int k = 0; k < 2; ++k) dst[m][k] = *(const PG8_LAS bf16x8*)(lds + PG8_SA(b, h) + aoff + m * 2048 + k * 1024); } while (0)
; #define PG8_MMA(ai, bj, At, Bt) do { __builtin_amdgcn_s_setprio(1); _Pragma("unroll") for (int m = 0; m < 4; ++m) _Pragma("unroll") for (int n = 0; n < 2; ++n) _Pragma("unroll") for (int k = 0; k < 2; ++k) \
;         acc[ai][bj][m][n] = __builtin_amdgcn_mfma_f32_16x16x32_bf16(Bt[n][k], At[m][k], acc[ai][bj][m][n], 0, 0, 0); __builtin_amdgcn_s_setprio(0); } while (0)
; #define PG8_WAIT_V(n) asm volatile("s_waitcnt vmcnt(" #n ")" ::: "memory")
; #define PG8_WAIT_L(n) asm volatile("s_waitcnt lgkmcnt(" #n ")" ::: "memory")
; #define PG8_BAR __builtin_amdgcn_s_barrier()
; #define PG8_SCHED __builtin_amdgcn_sched_barrier(0)
; template <class Epi, class Sched, bool ALIGN_EPI = false, bool SP2 = false>
; __device__ __forceinline__ void gemm_phase(PG8_LAS unsigned char* lds, const Gemm g, const Sched& S, const Epi& E) {
;     ...
;         for (int t = 0; t < nt; t += 2) {
;     ...
;             PG8_LDA(At, 1, 1); PG8_STAGE(PG8_SB(1, 0), b3, voffB); PG8_STAGE(PG8_SB(1, 1), b3 + hstep, voffB); PG8_STAGE(PG8_SA(1, 0), a3, voffA);
;             PG8_WAIT_V(8); PG8_WAIT_L(0); PG8_BAR; PG8_MMA(1, 0, At, B0); PG8_MMA(1, 1, At, B1); PG8_BAR; PG8_SCHED;
	s_setprio 0
	s_add_i32 s10, s10, s6
	v_lshl_add_u64 v[180:181], v[180:181], 0, s[28:29]
	s_mov_b32 m0, s10
	ds_read_b128 v[194:197], v185 offset:49152
	ds_read_b128 v[198:201], v185 offset:50176
	ds_read_b128 v[202:205], v185 offset:51200
	ds_read_b128 v[206:209], v185 offset:52224
	ds_read_b128 v[210:213], v185 offset:53248
	ds_read_b128 v[214:217], v185 offset:54272
	ds_read_b128 v[218:221], v185 offset:55296
	ds_read_b128 v[222:225], v185 offset:56320
	global_load_lds_dwordx4 v[180:181], off
	s_add_i32 m0, s10, 0x2000
	s_add_u32 s46, s46, 0x40080
	v_lshl_add_u64 v[180:181], v[226:227], 0, s[28:29]
	s_addc_u32 s47, s47, 0
	s_add_i32 s10, s11, s6
	global_load_lds_dwordx4 v[180:181], off
	v_lshl_add_u64 v[180:181], s[46:47], 0, v[0:1]
	s_mov_b32 m0, s10
	s_nop 0
	global_load_lds_dwordx4 v[180:181], off
	v_lshl_add_u64 v[180:181], s[46:47], 0, v[146:147]
	s_add_i32 m0, s10, 0x2000
	s_nop 0
	global_load_lds_dwordx4 v[180:181], off
	v_lshl_add_u64 v[180:181], v[238:239], 0, s[28:29]
	s_mov_b32 m0, s52
	s_nop 0
	global_load_lds_dwordx4 v[180:181], off
	v_lshl_add_u64 v[180:181], v[240:241], 0, s[28:29]
	s_mov_b32 m0, s53
	s_nop 0
	global_load_lds_dwordx4 v[180:181], off
	s_waitcnt vmcnt(8)
	s_waitcnt lgkmcnt(0)
	s_setprio 1
	s_barrier
	v_mfma_f32_16x16x32_bf16 v[62:65], v[90:93], v[194:197], v[62:65]
	v_mfma_f32_16x16x32_bf16 v[62:65], v[94:97], v[198:201], v[62:65]
	v_mfma_f32_16x16x32_bf16 v[58:61], v[98:101], v[194:197], v[58:61]
	v_mfma_f32_16x16x32_bf16 v[58:61], v[102:105], v[198:201], v[58:61]
	v_mfma_f32_16x16x32_bf16 v[42:45], v[98:101], v[202:205], v[42:45]
	v_mfma_f32_16x16x32_bf16 v[42:45], v[102:105], v[206:209], v[42:45]
	v_mfma_f32_16x16x32_bf16 v[46:49], v[90:93], v[202:205], v[46:49]
	v_mfma_f32_16x16x32_bf16 v[46:49], v[94:97], v[206:209], v[46:49]
	v_mfma_f32_16x16x32_bf16 v[30:33], v[90:93], v[210:213], v[30:33]
	v_mfma_f32_16x16x32_bf16 v[30:33], v[94:97], v[214:217], v[30:33]
	v_mfma_f32_16x16x32_bf16 v[26:29], v[98:101], v[210:213], v[26:29]
	v_mfma_f32_16x16x32_bf16 v[26:29], v[102:105], v[214:217], v[26:29]
	v_mfma_f32_16x16x32_bf16 v[10:13], v[98:101], v[218:221], v[10:13]
	v_mfma_f32_16x16x32_bf16 v[10:13], v[102:105], v[222:225], v[10:13]
	v_mfma_f32_16x16x32_bf16 v[14:17], v[90:93], v[218:221], v[14:17]
	v_mfma_f32_16x16x32_bf16 v[14:17], v[94:97], v[222:225], v[14:17]
	v_mfma_f32_16x16x32_bf16 v[54:57], v[158:161], v[194:197], v[54:57]
	v_mfma_f32_16x16x32_bf16 v[54:57], v[176:179], v[198:201], v[54:57]
	v_mfma_f32_16x16x32_bf16 v[50:53], v[186:189], v[194:197], v[50:53]
	v_mfma_f32_16x16x32_bf16 v[50:53], v[190:193], v[198:201], v[50:53]
	v_mfma_f32_16x16x32_bf16 v[34:37], v[186:189], v[202:205], v[34:37]
	v_mfma_f32_16x16x32_bf16 v[34:37], v[190:193], v[206:209], v[34:37]
	v_mfma_f32_16x16x32_bf16 v[38:41], v[158:161], v[202:205], v[38:41]
	v_mfma_f32_16x16x32_bf16 v[38:41], v[176:179], v[206:209], v[38:41]
	v_mfma_f32_16x16x32_bf16 v[22:25], v[158:161], v[210:213], v[22:25]
	v_mfma_f32_16x16x32_bf16 v[22:25], v[176:179], v[214:217], v[22:25]
	v_mfma_f32_16x16x32_bf16 v[18:21], v[186:189], v[210:213], v[18:21]
	v_mfma_f32_16x16x32_bf16 v[18:21], v[190:193], v[214:217], v[18:21]
	v_mfma_f32_16x16x32_bf16 v[2:5], v[186:189], v[218:221], v[2:5]
	v_mfma_f32_16x16x32_bf16 v[2:5], v[190:193], v[222:225], v[2:5]
	v_mfma_f32_16x16x32_bf16 v[6:9], v[158:161], v[218:221], v[6:9]
	v_mfma_f32_16x16x32_bf16 v[6:9], v[176:179], v[222:225], v[6:9]
	s_barrier
	s_setprio 0
	s_add_i32 s59, s59, 2
	s_add_u32 s57, s57, 0x100
	s_addc_u32 s58, s58, 0
	s_add_u32 s44, s44, 0x100
	s_addc_u32 s45, s45, 0
	s_cmp_gt_u32 s59, 13
	s_cbranch_scc0 .LBB0_162
	s_and_b64 vcc, exec, s[22:23]
	s_cbranch_vccz .LBB0_165
	s_barrier

; #define PG8_STAGE(bufoff, gbase, voff) do { _Pragma("unroll") for (int _i = 0; _i < 2; ++_i) \
;         __builtin_amdgcn_global_load_lds((const unsigned*)((const char*)(gbase) + (voff)[_i]), (PG8_LAS unsigned*)(lds + (bufoff) + ldsw + _i * 8192), 16, 0, 0); } while (0)
; #define PG8_LDA(dst, b, h) do { _Pragma("unroll") for (int m = 0; m < 4; ++m) _Pragma("unroll") for (int k = 0; k < 2; ++k) dst[m][k] = *(const PG8_LAS bf16x8*)(lds + PG8_SA(b, h) + aoff + m * 2048 + k * 1024); } while (0)
; #define PG8_LDB(dst, b, h) do { _Pragma("unroll") for (int n = 0; n < 2; ++n) _Pragma("unroll") for (int k = 0; k < 2; ++k) dst[n][k] = *(const PG8_LAS bf16x8*)(lds + PG8_SB(b, h) + boff + n * 2048 + k * 1024); } while (0)
; #define PG8_MMA(ai, bj, At, Bt) do { __builtin_amdgcn_s_setprio(1); _Pragma("unroll") for (int m = 0; m < 4; ++m) _Pragma("unroll") for (int n = 0; n < 2; ++n) _Pragma("unroll") for (int k = 0; k < 2; ++k) \
;         acc[ai][bj][m][n] = __builtin_amdgcn_mfma_f32_16x16x32_bf16(Bt[n][k], At[m][k], acc[ai][bj][m][n], 0, 0, 0); __builtin_amdgcn_s_setprio(0); } while (0)
; #define PG8_WAIT_V(n) asm volatile("s_waitcnt vmcnt(" #n ")" ::: "memory")
; #define PG8_WAIT_L(n) asm volatile("s_waitcnt lgkmcnt(" #n ")" ::: "memory")
; #define PG8_BAR __builtin_amdgcn_s_barrier()
; #define PG8_SCHED __builtin_amdgcn_sched_barrier(0)
; template <class Epi, class Sched, bool ALIGN_EPI = false, bool SP2 = false>
; __device__ __forceinline__ void gemm_phase(PG8_LAS unsigned char* lds, const Gemm g, const Sched& S, const Epi& E) {
;     ...
;             const bool last = (t == nt - 2);
;             const char* a1 = cA + (size_t)(t + 1) * kstep;
;             const char* a2 = last ? nA : cA + (size_t)(t + 2) * kstep; const char* b2 = last ? nB : cB + (size_t)(t + 2) * kstep;
;             const char* a3 = a2 + kstep; const char* b3 = b2 + kstep;
;             if (last && has_next) S.a_ready(nxt);
;             if constexpr (SP2) {
;             PG8_LDB(B0, 0, 0); PG8_LDB(B1, 0, 1); PG8_SCHED; PG8_LDA(At, 0, 0); PG8_STAGE(PG8_SA(1, 1), a1 + hstep, voffA);
;             PG8_WAIT_V(8); PG8_WAIT_L(0); PG8_BAR; PG8_MMA(0, 0, At, B0); PG8_MMA(0, 1, At, B1); PG8_BAR; PG8_SCHED;
;             PG8_LDA(At, 0, 1); PG8_STAGE(PG8_SB(0, 0), b2, voffB); PG8_STAGE(PG8_SB(0, 1), b2 + hstep, voffB); PG8_STAGE(PG8_SA(0, 0), a2, voffA);
.LBB0_243:
	s_add_u32 s10, s46, 0xfffc0080
	s_addc_u32 s11, s47, -1
	s_add_i32 s58, 16, 0x10000
	s_cmp_eq_u32 s57, 12
	s_cselect_b32 s51, s34, s11
	s_cselect_b32 s50, s35, s10
	s_cselect_b32 s49, s27, s56
	s_cselect_b32 s48, s41, s55
	s_add_i32 s10, 16, 0x14000
	v_add_u32_e32 v156, s58, v141
	v_add_u32_e32 v160, s10, v141
	ds_read_b128 v[144:147], v156
	ds_read_b128 v[148:151], v156 offset:1024
	ds_read_b128 v[152:155], v156 offset:2048
	ds_read_b128 v[156:159], v156 offset:3072
	ds_read_b128 v[176:179], v160
	ds_read_b128 v[180:183], v160 offset:1024
	ds_read_b128 v[184:187], v160 offset:2048
	ds_read_b128 v[188:191], v160 offset:3072
	v_lshl_add_u64 v[160:161], s[46:47], 0, v[138:139]
	s_add_i32 m0, s4, 0xc000
	ds_read_b128 v[192:195], v143
	ds_read_b128 v[196:199], v143 offset:1024
	ds_read_b128 v[200:203], v143 offset:2048
	ds_read_b128 v[204:207], v143 offset:3072
	ds_read_b128 v[208:211], v143 offset:4096
	ds_read_b128 v[212:215], v143 offset:5120
	ds_read_b128 v[216:219], v143 offset:6144
	ds_read_b128 v[220:223], v143 offset:7168
	global_load_lds_dwordx4 v[160:161], off
	v_lshl_add_u64 v[160:161], s[46:47], 0, v[136:137]
	s_add_i32 m0, s4, 0xe000
	s_nop 0
	global_load_lds_dwordx4 v[160:161], off
	s_waitcnt vmcnt(8)
	s_waitcnt lgkmcnt(0)
	s_setprio 1
	s_barrier
	v_mfma_f32_16x16x32_bf16 v[126:129], v[144:147], v[192:195], v[126:129]
	v_mfma_f32_16x16x32_bf16 v[126:129], v[148:151], v[196:199], v[126:129]
	v_mfma_f32_16x16x32_bf16 v[122:125], v[152:155], v[192:195], v[122:125]
	v_mfma_f32_16x16x32_bf16 v[122:125], v[156:159], v[196:199], v[122:125]
	v_mfma_f32_16x16x32_bf16 v[114:117], v[152:155], v[200:203], v[114:117]
	v_mfma_f32_16x16x32_bf16 v[114:117], v[156:159], v[204:207], v[114:117]
	v_mfma_f32_16x16x32_bf16 v[118:121], v[144:147], v[200:203], v[118:121]
	v_mfma_f32_16x16x32_bf16 v[118:121], v[148:151], v[204:207], v[118:121]
	v_mfma_f32_16x16x32_bf16 v[102:105], v[144:147], v[208:211], v[102:105]
	v_mfma_f32_16x16x32_bf16 v[102:105], v[148:151], v[212:215], v[102:105]
	v_mfma_f32_16x16x32_bf16 v[98:101], v[152:155], v[208:211], v[98:101]
	v_mfma_f32_16x16x32_bf16 v[98:101], v[156:159], v[212:215], v[98:101]
	v_mfma_f32_16x16x32_bf16 v[82:85], v[152:155], v[216:219], v[82:85]
	v_mfma_f32_16x16x32_bf16 v[82:85], v[156:159], v[220:223], v[82:85]
	v_mfma_f32_16x16x32_bf16 v[86:89], v[144:147], v[216:219], v[86:89]
	v_mfma_f32_16x16x32_bf16 v[86:89], v[148:151], v[220:223], v[86:89]
	v_mfma_f32_16x16x32_bf16 v[110:113], v[176:179], v[192:195], v[110:113]
	v_mfma_f32_16x16x32_bf16 v[110:113], v[180:183], v[196:199], v[110:113]
	v_mfma_f32_16x16x32_bf16 v[106:109], v[184:187], v[192:195], v[106:109]
	v_mfma_f32_16x16x32_bf16 v[106:109], v[188:191], v[196:199], v[106:109]
	v_mfma_f32_16x16x32_bf16 v[90:93], v[184:187], v[200:203], v[90:93]
	v_mfma_f32_16x16x32_bf16 v[90:93], v[188:191], v[204:207], v[90:93]
	v_mfma_f32_16x16x32_bf16 v[94:97], v[176:179], v[200:203], v[94:97]
	v_mfma_f32_16x16x32_bf16 v[94:97], v[180:183], v[204:207], v[94:97]
	v_mfma_f32_16x16x32_bf16 v[78:81], v[176:179], v[208:211], v[78:81]
	v_mfma_f32_16x16x32_bf16 v[78:81], v[180:183], v[212:215], v[78:81]
	v_mfma_f32_16x16x32_bf16 v[74:77], v[184:187], v[208:211], v[74:77]
	v_mfma_f32_16x16x32_bf16 v[74:77], v[188:191], v[212:215], v[74:77]
	v_mfma_f32_16x16x32_bf16 v[66:69], v[184:187], v[216:219], v[66:69]
	v_mfma_f32_16x16x32_bf16 v[66:69], v[188:191], v[220:223], v[66:69]
	v_mfma_f32_16x16x32_bf16 v[70:73], v[176:179], v[216:219], v[70:73]
	v_mfma_f32_16x16x32_bf16 v[70:73], v[180:183], v[220:223], v[70:73]
	s_barrier
	s_setprio 0
	s_add_i32 s11, s58, s3
	v_lshl_add_u64 v[160:161], s[48:49], 0, v[0:1]
	s_mov_b32 m0, s11
	ds_read_b128 v[192:195], v143 offset:16384
	ds_read_b128 v[196:199], v143 offset:17408
	ds_read_b128 v[200:203], v143 offset:18432
	ds_read_b128 v[204:207], v143 offset:19456
	ds_read_b128 v[208:211], v143 offset:20480
	ds_read_b128 v[212:215], v143 offset:21504
	ds_read_b128 v[216:219], v143 offset:22528
	ds_read_b128 v[220:223], v143 offset:23552
	global_load_lds_dwordx4 v[160:161], off
	s_add_i32 m0, s11, 0x2000
	s_add_u32 s58, s48, 0x40000
	v_lshl_add_u64 v[224:225], s[48:49], 0, v[130:131]
	s_addc_u32 s59, s49, 0
	s_add_i32 s10, s10, s3
	global_load_lds_dwordx4 v[224:225], off
	v_lshl_add_u64 v[226:227], s[58:59], 0, v[0:1]
	s_mov_b32 m0, s10
	v_lshl_add_u64 v[238:239], s[50:51], 0, v[132:133]
	global_load_lds_dwordx4 v[226:227], off
	v_lshl_add_u64 v[226:227], s[58:59], 0, v[130:131]
	s_add_i32 m0, s10, 0x2000
	s_nop 0
	global_load_lds_dwordx4 v[226:227], off
	v_lshl_add_u64 v[226:227], s[50:51], 0, v[134:135]
	s_mov_b32 m0, s4
	s_nop 0
	global_load_lds_dwordx4 v[226:227], off
	s_mov_b32 m0, s5
	s_nop 0
	global_load_lds_dwordx4 v[238:239], off
	s_waitcnt vmcnt(8)
	s_waitcnt lgkmcnt(0)
	s_setprio 1
	s_barrier
; #define PG8_STAGE(bufoff, gbase, voff) do { _Pragma("unroll") for (int _i = 0; _i < 2; ++_i) \
;         __builtin_amdgcn_global_load_lds((const unsigned*)((const char*)(gbase) + (voff)[_i]), (PG8_LAS unsigned*)(lds + (bufoff) + ldsw + _i * 8192), 16, 0, 0); } while (0)
; #define PG8_LDA(dst, b, h) do { _Pragma("unroll") for (int m = 0; m < 4; ++m) _Pragma("unroll") for (int k = 0; k < 2; ++k) dst[m][k] = *(const PG8_LAS bf16x8*)(lds + PG8_SA(b, h) + aoff + m * 2048 + k * 1024); } while (0)
; #define PG8_LDB(dst, b, h) do { _Pragma("unroll") for (int n = 0; n < 2; ++n) _Pragma("unroll") for (int k = 0; k < 2; ++k) dst[n][k] = *(const PG8_LAS bf16x8*)(lds + PG8_SB(b, h) + boff + n * 2048 + k * 1024); } while (0)
; #define PG8_MMA(ai, bj, At, Bt) do { __builtin_amdgcn_s_setprio(1); _Pragma("unroll") for (int m = 0; m < 4; ++m) _Pragma("unroll") for (int n = 0; n < 2; ++n) _Pragma("unroll") for (int k = 0; k < 2; ++k) \
;         acc[ai][bj][m][n] = __builtin_amdgcn_mfma_f32_16x16x32_bf16(Bt[n][k], At[m][k], acc[ai][bj][m][n], 0, 0, 0); __builtin_amdgcn_s_setprio(0); } while (0)
; #define PG8_WAIT_V(n) asm volatile("s_waitcnt vmcnt(" #n ")" ::: "memory")
; #define PG8_WAIT_L(n) asm volatile("s_waitcnt lgkmcnt(" #n ")" ::: "memory")
; #define PG8_BAR __builtin_amdgcn_s_barrier()
; #define PG8_SCHED __builtin_amdgcn_sched_barrier(0)
; template <class Epi, class Sched, bool ALIGN_EPI = false, bool SP2 = false>
; __device__ __forceinline__ void gemm_phase(PG8_LAS unsigned char* lds, const Gemm g, const Sched& S, const Epi& E) {
;     ...
;             PG8_WAIT_V(8); PG8_WAIT_L(0); PG8_BAR; PG8_MMA(1, 0, At, B0); PG8_MMA(1, 1, At, B1); PG8_BAR; PG8_SCHED;
;             PG8_LDB(B0, 1, 0); PG8_LDB(B1, 1, 1); PG8_SCHED; PG8_LDA(At, 1, 0); PG8_STAGE(PG8_SA(0, 1), a2 + hstep, voffA);
;             PG8_WAIT_V(8); PG8_WAIT_L(0); PG8_BAR; PG8_MMA(0, 0, At, B0); PG8_MMA(0, 1, At, B1); PG8_BAR; PG8_SCHED;
	v_mfma_f32_16x16x32_bf16 v[62:65], v[144:147], v[192:195], v[62:65]
	v_mfma_f32_16x16x32_bf16 v[62:65], v[148:151], v[196:199], v[62:65]
	v_mfma_f32_16x16x32_bf16 v[58:61], v[152:155], v[192:195], v[58:61]
	v_mfma_f32_16x16x32_bf16 v[58:61], v[156:159], v[196:199], v[58:61]
	v_mfma_f32_16x16x32_bf16 v[50:53], v[152:155], v[200:203], v[50:53]
	v_mfma_f32_16x16x32_bf16 v[50:53], v[156:159], v[204:207], v[50:53]
	v_mfma_f32_16x16x32_bf16 v[54:57], v[144:147], v[200:203], v[54:57]
	v_mfma_f32_16x16x32_bf16 v[54:57], v[148:151], v[204:207], v[54:57]
	v_mfma_f32_16x16x32_bf16 v[38:41], v[144:147], v[208:211], v[38:41]
	v_mfma_f32_16x16x32_bf16 v[38:41], v[148:151], v[212:215], v[38:41]
	v_mfma_f32_16x16x32_bf16 v[34:37], v[152:155], v[208:211], v[34:37]
	v_mfma_f32_16x16x32_bf16 v[34:37], v[156:159], v[212:215], v[34:37]
	v_mfma_f32_16x16x32_bf16 v[18:21], v[152:155], v[216:219], v[18:21]
	v_mfma_f32_16x16x32_bf16 v[18:21], v[156:159], v[220:223], v[18:21]
	v_mfma_f32_16x16x32_bf16 v[22:25], v[144:147], v[216:219], v[22:25]
	v_mfma_f32_16x16x32_bf16 v[22:25], v[148:151], v[220:223], v[22:25]
	v_mfma_f32_16x16x32_bf16 v[46:49], v[176:179], v[192:195], v[46:49]
	v_mfma_f32_16x16x32_bf16 v[46:49], v[180:183], v[196:199], v[46:49]
	v_mfma_f32_16x16x32_bf16 v[42:45], v[184:187], v[192:195], v[42:45]
	v_mfma_f32_16x16x32_bf16 v[42:45], v[188:191], v[196:199], v[42:45]
	v_mfma_f32_16x16x32_bf16 v[26:29], v[184:187], v[200:203], v[26:29]
	v_mfma_f32_16x16x32_bf16 v[26:29], v[188:191], v[204:207], v[26:29]
	v_mfma_f32_16x16x32_bf16 v[30:33], v[176:179], v[200:203], v[30:33]
	v_mfma_f32_16x16x32_bf16 v[30:33], v[180:183], v[204:207], v[30:33]
	v_mfma_f32_16x16x32_bf16 v[14:17], v[176:179], v[208:211], v[14:17]
	v_mfma_f32_16x16x32_bf16 v[14:17], v[180:183], v[212:215], v[14:17]
	v_mfma_f32_16x16x32_bf16 v[10:13], v[184:187], v[208:211], v[10:13]
	v_mfma_f32_16x16x32_bf16 v[10:13], v[188:191], v[212:215], v[10:13]
	v_mfma_f32_16x16x32_bf16 v[2:5], v[184:187], v[216:219], v[2:5]
	v_mfma_f32_16x16x32_bf16 v[2:5], v[188:191], v[220:223], v[2:5]
	v_mfma_f32_16x16x32_bf16 v[6:9], v[176:179], v[216:219], v[6:9]
	v_mfma_f32_16x16x32_bf16 v[6:9], v[180:183], v[220:223], v[6:9]
	s_barrier
	s_setprio 0
	s_add_i32 s10, 16, 0x18000
	s_add_i32 s11, 16, 0x1c000
	v_add_u32_e32 v156, s10, v141
	v_add_u32_e32 v188, s11, v141
	ds_read_b128 v[144:147], v156
	ds_read_b128 v[148:151], v156 offset:1024
	ds_read_b128 v[152:155], v156 offset:2048
	ds_read_b128 v[156:159], v156 offset:3072
	ds_read_b128 v[176:179], v188
	ds_read_b128 v[180:183], v188 offset:1024
	ds_read_b128 v[184:187], v188 offset:2048
	ds_read_b128 v[188:191], v188 offset:3072
	s_add_u32 s50, s50, 0x40000
	s_addc_u32 s51, s51, 0
	s_mov_b32 m0, s6
	v_lshl_add_u64 v[240:241], s[50:51], 0, v[134:135]
	ds_read_b128 v[192:195], v143 offset:32768
	ds_read_b128 v[196:199], v143 offset:33792
	ds_read_b128 v[200:203], v143 offset:34816
	ds_read_b128 v[204:207], v143 offset:35840
	ds_read_b128 v[208:211], v143 offset:36864
	ds_read_b128 v[212:215], v143 offset:37888
	ds_read_b128 v[216:219], v143 offset:38912
	ds_read_b128 v[220:223], v143 offset:39936
	global_load_lds_dwordx4 v[240:241], off
	v_lshl_add_u64 v[240:241], s[50:51], 0, v[132:133]
	s_mov_b32 m0, s7
	s_nop 0
	global_load_lds_dwordx4 v[240:241], off
	s_waitcnt vmcnt(8)
	s_waitcnt lgkmcnt(0)
	s_setprio 1
	s_barrier
	v_mfma_f32_16x16x32_bf16 v[126:129], v[144:147], v[192:195], v[126:129]
	v_mfma_f32_16x16x32_bf16 v[126:129], v[148:151], v[196:199], v[126:129]
	v_mfma_f32_16x16x32_bf16 v[122:125], v[152:155], v[192:195], v[122:125]
	v_mfma_f32_16x16x32_bf16 v[122:125], v[156:159], v[196:199], v[122:125]
	v_mfma_f32_16x16x32_bf16 v[114:117], v[152:155], v[200:203], v[114:117]
	v_mfma_f32_16x16x32_bf16 v[114:117], v[156:159], v[204:207], v[114:117]
	v_mfma_f32_16x16x32_bf16 v[118:121], v[144:147], v[200:203], v[118:121]
	v_mfma_f32_16x16x32_bf16 v[118:121], v[148:151], v[204:207], v[118:121]
	v_mfma_f32_16x16x32_bf16 v[102:105], v[144:147], v[208:211], v[102:105]
	v_mfma_f32_16x16x32_bf16 v[102:105], v[148:151], v[212:215], v[102:105]
	v_mfma_f32_16x16x32_bf16 v[98:101], v[152:155], v[208:211], v[98:101]
	v_mfma_f32_16x16x32_bf16 v[98:101], v[156:159], v[212:215], v[98:101]
	v_mfma_f32_16x16x32_bf16 v[82:85], v[152:155], v[216:219], v[82:85]
	v_mfma_f32_16x16x32_bf16 v[82:85], v[156:159], v[220:223], v[82:85]
	v_mfma_f32_16x16x32_bf16 v[86:89], v[144:147], v[216:219], v[86:89]
	v_mfma_f32_16x16x32_bf16 v[86:89], v[148:151], v[220:223], v[86:89]
	v_mfma_f32_16x16x32_bf16 v[110:113], v[176:179], v[192:195], v[110:113]
	v_mfma_f32_16x16x32_bf16 v[110:113], v[180:183], v[196:199], v[110:113]
	v_mfma_f32_16x16x32_bf16 v[106:109], v[184:187], v[192:195], v[106:109]
	v_mfma_f32_16x16x32_bf16 v[106:109], v[188:191], v[196:199], v[106:109]
	v_mfma_f32_16x16x32_bf16 v[90:93], v[184:187], v[200:203], v[90:93]
	v_mfma_f32_16x16x32_bf16 v[90:93], v[188:191], v[204:207], v[90:93]
	v_mfma_f32_16x16x32_bf16 v[94:97], v[176:179], v[200:203], v[94:97]
	v_mfma_f32_16x16x32_bf16 v[94:97], v[180:183], v[204:207], v[94:97]
	v_mfma_f32_16x16x32_bf16 v[78:81], v[176:179], v[208:211], v[78:81]
	v_mfma_f32_16x16x32_bf16 v[78:81], v[180:183], v[212:215], v[78:81]
	v_mfma_f32_16x16x32_bf16 v[74:77], v[184:187], v[208:211], v[74:77]
	v_mfma_f32_16x16x32_bf16 v[74:77], v[188:191], v[212:215], v[74:77]
	v_mfma_f32_16x16x32_bf16 v[66:69], v[184:187], v[216:219], v[66:69]
	v_mfma_f32_16x16x32_bf16 v[66:69], v[188:191], v[220:223], v[66:69]
	v_mfma_f32_16x16x32_bf16 v[70:73], v[176:179], v[216:219], v[70:73]
	v_mfma_f32_16x16x32_bf16 v[70:73], v[180:183], v[220:223], v[70:73]
	s_barrier
; #define PG8_STAGE(bufoff, gbase, voff) do { _Pragma("unroll") for (int _i = 0; _i < 2; ++_i) \
;         __builtin_amdgcn_global_load_lds((const unsigned*)((const char*)(gbase) + (voff)[_i]), (PG8_LAS unsigned*)(lds + (bufoff) + ldsw + _i * 8192), 16, 0, 0); } while (0)
; #define PG8_LDA(dst, b, h) do { _Pragma("unroll") for (int m = 0; m < 4; ++m) _Pragma("unroll") for (int k = 0; k < 2; ++k) dst[m][k] = *(const PG8_LAS bf16x8*)(lds + PG8_SA(b, h) + aoff + m * 2048 + k * 1024); } while (0)
; #define PG8_MMA(ai, bj, At, Bt) do { __builtin_amdgcn_s_setprio(1); _Pragma("unroll") for (int m = 0; m < 4; ++m) _Pragma("unroll") for (int n = 0; n < 2; ++n) _Pragma("unroll") for (int k = 0; k < 2; ++k) \
;         acc[ai][bj][m][n] = __builtin_amdgcn_mfma_f32_16x16x32_bf16(Bt[n][k], At[m][k], acc[ai][bj][m][n], 0, 0, 0); __builtin_amdgcn_s_setprio(0); } while (0)
; #define PG8_WAIT_V(n) asm volatile("s_waitcnt vmcnt(" #n ")" ::: "memory")
; #define PG8_WAIT_L(n) asm volatile("s_waitcnt lgkmcnt(" #n ")" ::: "memory")
; #define PG8_BAR __builtin_amdgcn_s_barrier()
; #define PG8_SCHED __builtin_amdgcn_sched_barrier(0)
; template <class Epi, class Sched, bool ALIGN_EPI = false, bool SP2 = false>
; __device__ __forceinline__ void gemm_phase(PG8_LAS unsigned char* lds, const Gemm g, const Sched& S, const Epi& E) {
;     ...
;         for (int t = 0; t < nt; t += 2) {
;     ...
;             PG8_LDA(At, 1, 1); PG8_STAGE(PG8_SB(1, 0), b3, voffB); PG8_STAGE(PG8_SB(1, 1), b3 + hstep, voffB); PG8_STAGE(PG8_SA(1, 0), a3, voffA);
;             PG8_WAIT_V(8); PG8_WAIT_L(0); PG8_BAR; PG8_MMA(1, 0, At, B0); PG8_MMA(1, 1, At, B1); PG8_BAR; PG8_SCHED;
	s_setprio 0
	s_add_i32 s10, s10, s3
	v_lshl_add_u64 v[160:161], v[160:161], 0, s[28:29]
	s_mov_b32 m0, s10
	ds_read_b128 v[192:195], v143 offset:49152
	ds_read_b128 v[196:199], v143 offset:50176
	ds_read_b128 v[200:203], v143 offset:51200
	ds_read_b128 v[204:207], v143 offset:52224
	ds_read_b128 v[208:211], v143 offset:53248
	ds_read_b128 v[212:215], v143 offset:54272
	ds_read_b128 v[216:219], v143 offset:55296
	ds_read_b128 v[220:223], v143 offset:56320
	global_load_lds_dwordx4 v[160:161], off
	s_add_i32 m0, s10, 0x2000
	s_add_u32 s48, s48, 0x40080
	v_lshl_add_u64 v[160:161], v[224:225], 0, s[28:29]
	s_addc_u32 s49, s49, 0
	s_add_i32 s10, s11, s3
	global_load_lds_dwordx4 v[160:161], off
	v_lshl_add_u64 v[160:161], s[48:49], 0, v[0:1]
	s_mov_b32 m0, s10
	s_nop 0
	global_load_lds_dwordx4 v[160:161], off
	v_lshl_add_u64 v[160:161], s[48:49], 0, v[130:131]
	s_add_i32 m0, s10, 0x2000
	s_nop 0
	global_load_lds_dwordx4 v[160:161], off
	v_lshl_add_u64 v[160:161], v[226:227], 0, s[28:29]
	s_mov_b32 m0, s8
	s_nop 0
	global_load_lds_dwordx4 v[160:161], off
	v_lshl_add_u64 v[160:161], v[238:239], 0, s[28:29]
	s_mov_b32 m0, s9
	s_nop 0
	global_load_lds_dwordx4 v[160:161], off
	s_waitcnt vmcnt(8)
	s_waitcnt lgkmcnt(0)
	s_setprio 1
	s_barrier
	v_mfma_f32_16x16x32_bf16 v[62:65], v[144:147], v[192:195], v[62:65]
	v_mfma_f32_16x16x32_bf16 v[62:65], v[148:151], v[196:199], v[62:65]
	v_mfma_f32_16x16x32_bf16 v[58:61], v[152:155], v[192:195], v[58:61]
	v_mfma_f32_16x16x32_bf16 v[58:61], v[156:159], v[196:199], v[58:61]
	v_mfma_f32_16x16x32_bf16 v[50:53], v[152:155], v[200:203], v[50:53]
	v_mfma_f32_16x16x32_bf16 v[50:53], v[156:159], v[204:207], v[50:53]
	v_mfma_f32_16x16x32_bf16 v[54:57], v[144:147], v[200:203], v[54:57]
	v_mfma_f32_16x16x32_bf16 v[54:57], v[148:151], v[204:207], v[54:57]
	v_mfma_f32_16x16x32_bf16 v[38:41], v[144:147], v[208:211], v[38:41]
	v_mfma_f32_16x16x32_bf16 v[38:41], v[148:151], v[212:215], v[38:41]
	v_mfma_f32_16x16x32_bf16 v[34:37], v[152:155], v[208:211], v[34:37]
	v_mfma_f32_16x16x32_bf16 v[34:37], v[156:159], v[212:215], v[34:37]
	v_mfma_f32_16x16x32_bf16 v[18:21], v[152:155], v[216:219], v[18:21]
	v_mfma_f32_16x16x32_bf16 v[18:21], v[156:159], v[220:223], v[18:21]
	v_mfma_f32_16x16x32_bf16 v[22:25], v[144:147], v[216:219], v[22:25]
	v_mfma_f32_16x16x32_bf16 v[22:25], v[148:151], v[220:223], v[22:25]
	v_mfma_f32_16x16x32_bf16 v[46:49], v[176:179], v[192:195], v[46:49]
	v_mfma_f32_16x16x32_bf16 v[46:49], v[180:183], v[196:199], v[46:49]
	v_mfma_f32_16x16x32_bf16 v[42:45], v[184:187], v[192:195], v[42:45]
	v_mfma_f32_16x16x32_bf16 v[42:45], v[188:191], v[196:199], v[42:45]
	v_mfma_f32_16x16x32_bf16 v[26:29], v[184:187], v[200:203], v[26:29]
	v_mfma_f32_16x16x32_bf16 v[26:29], v[188:191], v[204:207], v[26:29]
	v_mfma_f32_16x16x32_bf16 v[30:33], v[176:179], v[200:203], v[30:33]
	v_mfma_f32_16x16x32_bf16 v[30:33], v[180:183], v[204:207], v[30:33]
	v_mfma_f32_16x16x32_bf16 v[14:17], v[176:179], v[208:211], v[14:17]
	v_mfma_f32_16x16x32_bf16 v[14:17], v[180:183], v[212:215], v[14:17]
	v_mfma_f32_16x16x32_bf16 v[10:13], v[184:187], v[208:211], v[10:13]
	v_mfma_f32_16x16x32_bf16 v[10:13], v[188:191], v[212:215], v[10:13]
	v_mfma_f32_16x16x32_bf16 v[2:5], v[184:187], v[216:219], v[2:5]
	v_mfma_f32_16x16x32_bf16 v[2:5], v[188:191], v[220:223], v[2:5]
	v_mfma_f32_16x16x32_bf16 v[6:9], v[176:179], v[216:219], v[6:9]
	v_mfma_f32_16x16x32_bf16 v[6:9], v[180:183], v[220:223], v[6:9]
	s_barrier
	s_setprio 0
	s_add_i32 s57, s57, 2
	s_add_u32 s55, s55, 0x100
	s_addc_u32 s56, s56, 0
	s_add_u32 s46, s46, 0x100
	s_addc_u32 s47, s47, 0
	s_cmp_gt_u32 s57, 13
	s_cbranch_scc0 .LBB0_243
	s_and_b64 vcc, exec, s[24:25]
	s_cbranch_vccz .LBB0_246
	s_barrier

; #define PG8_STAGE(bufoff, gbase, voff) do { _Pragma("unroll") for (int _i = 0; _i < 2; ++_i) \
;         __builtin_amdgcn_global_load_lds((const unsigned*)((const char*)(gbase) + (voff)[_i]), (PG8_LAS unsigned*)(lds + (bufoff) + ldsw + _i * 8192), 16, 0, 0); } while (0)
; #define PG8_LDA(dst, b, h) do { _Pragma("unroll") for (int m = 0; m < 4; ++m) _Pragma("unroll") for (int k = 0; k < 2; ++k) dst[m][k] = *(const PG8_LAS bf16x8*)(lds + PG8_SA(b, h) + aoff + m * 2048 + k * 1024); } while (0)
; #define PG8_LDB(dst, b, h) do { _Pragma("unroll") for (int n = 0; n < 2; ++n) _Pragma("unroll") for (int k = 0; k < 2; ++k) dst[n][k] = *(const PG8_LAS bf16x8*)(lds + PG8_SB(b, h) + boff + n * 2048 + k * 1024); } while (0)
; #define PG8_MMA(ai, bj, At, Bt) do { __builtin_amdgcn_s_setprio(1); _Pragma("unroll") for (int m = 0; m < 4; ++m) _Pragma("unroll") for (int n = 0; n < 2; ++n) _Pragma("unroll") for (int k = 0; k < 2; ++k) \
;         acc[ai][bj][m][n] = __builtin_amdgcn_mfma_f32_16x16x32_bf16(Bt[n][k], At[m][k], acc[ai][bj][m][n], 0, 0, 0); __builtin_amdgcn_s_setprio(0); } while (0)
; #define PG8_WAIT_V(n) asm volatile("s_waitcnt vmcnt(" #n ")" ::: "memory")
; #define PG8_WAIT_L(n) asm volatile("s_waitcnt lgkmcnt(" #n ")" ::: "memory")
; #define PG8_BAR __builtin_amdgcn_s_barrier()
; #define PG8_SCHED __builtin_amdgcn_sched_barrier(0)
; template <class Epi, class Sched, bool ALIGN_EPI = false, bool SP2 = false>
; __device__ __forceinline__ void gemm_phase(PG8_LAS unsigned char* lds, const Gemm g, const Sched& S, const Epi& E) {
;     ...
;             const bool last = (t == nt - 2);
;             const char* a1 = cA + (size_t)(t + 1) * kstep;
;             const char* a2 = last ? nA : cA + (size_t)(t + 2) * kstep; const char* b2 = last ? nB : cB + (size_t)(t + 2) * kstep;
;             const char* a3 = a2 + kstep; const char* b3 = b2 + kstep;
;             if (last && has_next) S.a_ready(nxt);
;             if constexpr (SP2) {
;             PG8_LDB(B0, 0, 0); PG8_LDB(B1, 0, 1); PG8_SCHED; PG8_LDA(At, 0, 0); PG8_STAGE(PG8_SA(1, 1), a1 + hstep, voffA);
;             PG8_WAIT_V(8); PG8_WAIT_L(0); PG8_BAR; PG8_MMA(0, 0, At, B0); PG8_MMA(0, 1, At, B1); PG8_BAR; PG8_SCHED;
;             PG8_LDA(At, 0, 1); PG8_STAGE(PG8_SB(0, 0), b2, voffB); PG8_STAGE(PG8_SB(0, 1), b2 + hstep, voffB); PG8_STAGE(PG8_SA(0, 0), a2, voffA);
.LBB0_915:
	s_add_u32 s10, s42, 0xfffc0080
	s_addc_u32 s11, s43, -1
	s_add_i32 s35, 16, 0x10000
	s_cmp_eq_u32 s34, 12
	s_cselect_b32 s73, s0, s11
	s_cselect_b32 s72, s8, s10
	s_cselect_b32 s69, s9, s27
	s_cselect_b32 s68, s23, s25
	s_add_i32 s45, 16, 0x14000
	v_add_u32_e32 v78, s35, v197
	v_add_u32_e32 v94, s45, v197
	ds_read_b128 v[58:61], v78
	ds_read_b128 v[62:65], v78 offset:1024
	ds_read_b128 v[74:77], v78 offset:2048
	ds_read_b128 v[78:81], v78 offset:3072
	ds_read_b128 v[82:85], v94
	ds_read_b128 v[86:89], v94 offset:1024
	ds_read_b128 v[90:93], v94 offset:2048
	ds_read_b128 v[94:97], v94 offset:3072
	v_lshl_add_u64 v[194:195], s[42:43], 0, v[184:185]
	s_add_i32 m0, s77, 0xc000
	ds_read_b128 v[186:189], v199
	ds_read_b128 v[190:193], v199 offset:1024
	ds_read_b128 v[200:203], v199 offset:2048
	ds_read_b128 v[204:207], v199 offset:3072
	ds_read_b128 v[208:211], v199 offset:4096
	ds_read_b128 v[212:215], v199 offset:5120
	ds_read_b128 v[216:219], v199 offset:6144
	ds_read_b128 v[220:223], v199 offset:7168
	global_load_lds_dwordx4 v[194:195], off
	v_lshl_add_u64 v[194:195], s[42:43], 0, v[182:183]
	s_add_i32 m0, s77, 0xe000
	s_nop 0
	global_load_lds_dwordx4 v[194:195], off
	s_waitcnt vmcnt(8)
	s_waitcnt lgkmcnt(0)
	s_setprio 1
	s_barrier
	v_mfma_f32_16x16x32_bf16 v[158:161], v[58:61], v[186:189], v[158:161]
	v_mfma_f32_16x16x32_bf16 v[158:161], v[62:65], v[190:193], v[158:161]
	v_mfma_f32_16x16x32_bf16 v[154:157], v[74:77], v[186:189], v[154:157]
	v_mfma_f32_16x16x32_bf16 v[154:157], v[78:81], v[190:193], v[154:157]
	v_mfma_f32_16x16x32_bf16 v[138:141], v[74:77], v[200:203], v[138:141]
	v_mfma_f32_16x16x32_bf16 v[138:141], v[78:81], v[204:207], v[138:141]
	v_mfma_f32_16x16x32_bf16 v[142:145], v[58:61], v[200:203], v[142:145]
	v_mfma_f32_16x16x32_bf16 v[142:145], v[62:65], v[204:207], v[142:145]
	v_mfma_f32_16x16x32_bf16 v[126:129], v[58:61], v[208:211], v[126:129]
	v_mfma_f32_16x16x32_bf16 v[126:129], v[62:65], v[212:215], v[126:129]
	v_mfma_f32_16x16x32_bf16 v[122:125], v[74:77], v[208:211], v[122:125]
	v_mfma_f32_16x16x32_bf16 v[122:125], v[78:81], v[212:215], v[122:125]
	v_mfma_f32_16x16x32_bf16 v[106:109], v[74:77], v[216:219], v[106:109]
	v_mfma_f32_16x16x32_bf16 v[106:109], v[78:81], v[220:223], v[106:109]
	v_mfma_f32_16x16x32_bf16 v[110:113], v[58:61], v[216:219], v[110:113]
	v_mfma_f32_16x16x32_bf16 v[110:113], v[62:65], v[220:223], v[110:113]
	v_mfma_f32_16x16x32_bf16 v[150:153], v[82:85], v[186:189], v[150:153]
	v_mfma_f32_16x16x32_bf16 v[150:153], v[86:89], v[190:193], v[150:153]
	v_mfma_f32_16x16x32_bf16 v[146:149], v[90:93], v[186:189], v[146:149]
	v_mfma_f32_16x16x32_bf16 v[146:149], v[94:97], v[190:193], v[146:149]
	v_mfma_f32_16x16x32_bf16 v[130:133], v[90:93], v[200:203], v[130:133]
	v_mfma_f32_16x16x32_bf16 v[130:133], v[94:97], v[204:207], v[130:133]
	v_mfma_f32_16x16x32_bf16 v[134:137], v[82:85], v[200:203], v[134:137]
	v_mfma_f32_16x16x32_bf16 v[134:137], v[86:89], v[204:207], v[134:137]
	v_mfma_f32_16x16x32_bf16 v[118:121], v[82:85], v[208:211], v[118:121]
	v_mfma_f32_16x16x32_bf16 v[118:121], v[86:89], v[212:215], v[118:121]
	v_mfma_f32_16x16x32_bf16 v[114:117], v[90:93], v[208:211], v[114:117]
	v_mfma_f32_16x16x32_bf16 v[114:117], v[94:97], v[212:215], v[114:117]
	v_mfma_f32_16x16x32_bf16 v[98:101], v[90:93], v[216:219], v[98:101]
	v_mfma_f32_16x16x32_bf16 v[98:101], v[94:97], v[220:223], v[98:101]
	v_mfma_f32_16x16x32_bf16 v[102:105], v[82:85], v[216:219], v[102:105]
	v_mfma_f32_16x16x32_bf16 v[102:105], v[86:89], v[220:223], v[102:105]
	s_barrier
	s_setprio 0
	s_add_i32 s10, s35, s76
	v_lshl_add_u64 v[194:195], s[68:69], 0, v[0:1]
	s_mov_b32 m0, s10
	ds_read_b128 v[186:189], v199 offset:16384
	ds_read_b128 v[190:193], v199 offset:17408
	ds_read_b128 v[200:203], v199 offset:18432
	ds_read_b128 v[204:207], v199 offset:19456
	ds_read_b128 v[208:211], v199 offset:20480
	ds_read_b128 v[212:215], v199 offset:21504
	ds_read_b128 v[216:219], v199 offset:22528
	ds_read_b128 v[220:223], v199 offset:23552
	global_load_lds_dwordx4 v[194:195], off
	s_add_i32 m0, s10, 0x2000
	s_add_u32 s10, s68, 0x40000
	v_lshl_add_u64 v[224:225], s[68:69], 0, v[180:181]
	s_addc_u32 s11, s69, 0
	s_add_i32 s35, s45, s76
	global_load_lds_dwordx4 v[224:225], off
	v_lshl_add_u64 v[226:227], s[10:11], 0, v[0:1]
	s_mov_b32 m0, s35
	v_lshl_add_u64 v[238:239], s[72:73], 0, v[178:179]
	global_load_lds_dwordx4 v[226:227], off
	v_lshl_add_u64 v[226:227], s[10:11], 0, v[180:181]
	s_add_i32 m0, s35, 0x2000
	s_nop 0
	global_load_lds_dwordx4 v[226:227], off
	v_lshl_add_u64 v[226:227], s[72:73], 0, v[176:177]
	s_mov_b32 m0, s77
	s_nop 0
	global_load_lds_dwordx4 v[226:227], off
	s_mov_b32 m0, s2
	s_nop 0
	global_load_lds_dwordx4 v[238:239], off
	s_waitcnt vmcnt(8)
	s_waitcnt lgkmcnt(0)
	s_setprio 1
	s_barrier
; #define PG8_STAGE(bufoff, gbase, voff) do { _Pragma("unroll") for (int _i = 0; _i < 2; ++_i) \
;         __builtin_amdgcn_global_load_lds((const unsigned*)((const char*)(gbase) + (voff)[_i]), (PG8_LAS unsigned*)(lds + (bufoff) + ldsw + _i * 8192), 16, 0, 0); } while (0)
; #define PG8_LDA(dst, b, h) do { _Pragma("unroll") for (int m = 0; m < 4; ++m) _Pragma("unroll") for (int k = 0; k < 2; ++k) dst[m][k] = *(const PG8_LAS bf16x8*)(lds + PG8_SA(b, h) + aoff + m * 2048 + k * 1024); } while (0)
; #define PG8_LDB(dst, b, h) do { _Pragma("unroll") for (int n = 0; n < 2; ++n) _Pragma("unroll") for (int k = 0; k < 2; ++k) dst[n][k] = *(const PG8_LAS bf16x8*)(lds + PG8_SB(b, h) + boff + n * 2048 + k * 1024); } while (0)
; #define PG8_MMA(ai, bj, At, Bt) do { __builtin_amdgcn_s_setprio(1); _Pragma("unroll") for (int m = 0; m < 4; ++m) _Pragma("unroll") for (int n = 0; n < 2; ++n) _Pragma("unroll") for (int k = 0; k < 2; ++k) \
;         acc[ai][bj][m][n] = __builtin_amdgcn_mfma_f32_16x16x32_bf16(Bt[n][k], At[m][k], acc[ai][bj][m][n], 0, 0, 0); __builtin_amdgcn_s_setprio(0); } while (0)
; #define PG8_WAIT_V(n) asm volatile("s_waitcnt vmcnt(" #n ")" ::: "memory")
; #define PG8_WAIT_L(n) asm volatile("s_waitcnt lgkmcnt(" #n ")" ::: "memory")
; #define PG8_BAR __builtin_amdgcn_s_barrier()
; #define PG8_SCHED __builtin_amdgcn_sched_barrier(0)
; template <class Epi, class Sched, bool ALIGN_EPI = false, bool SP2 = false>
; __device__ __forceinline__ void gemm_phase(PG8_LAS unsigned char* lds, const Gemm g, const Sched& S, const Epi& E) {
;     ...
;             PG8_WAIT_V(8); PG8_WAIT_L(0); PG8_BAR; PG8_MMA(1, 0, At, B0); PG8_MMA(1, 1, At, B1); PG8_BAR; PG8_SCHED;
;             PG8_LDB(B0, 1, 0); PG8_LDB(B1, 1, 1); PG8_SCHED; PG8_LDA(At, 1, 0); PG8_STAGE(PG8_SA(0, 1), a2 + hstep, voffA);
;             PG8_WAIT_V(8); PG8_WAIT_L(0); PG8_BAR; PG8_MMA(0, 0, At, B0); PG8_MMA(0, 1, At, B1); PG8_BAR; PG8_SCHED;
	v_mfma_f32_16x16x32_bf16 v[70:73], v[58:61], v[186:189], v[70:73]
	v_mfma_f32_16x16x32_bf16 v[70:73], v[62:65], v[190:193], v[70:73]
	v_mfma_f32_16x16x32_bf16 v[66:69], v[74:77], v[186:189], v[66:69]
	v_mfma_f32_16x16x32_bf16 v[66:69], v[78:81], v[190:193], v[66:69]
	v_mfma_f32_16x16x32_bf16 v[42:45], v[74:77], v[200:203], v[42:45]
	v_mfma_f32_16x16x32_bf16 v[42:45], v[78:81], v[204:207], v[42:45]
	v_mfma_f32_16x16x32_bf16 v[46:49], v[58:61], v[200:203], v[46:49]
	v_mfma_f32_16x16x32_bf16 v[46:49], v[62:65], v[204:207], v[46:49]
	v_mfma_f32_16x16x32_bf16 v[30:33], v[58:61], v[208:211], v[30:33]
	v_mfma_f32_16x16x32_bf16 v[30:33], v[62:65], v[212:215], v[30:33]
	v_mfma_f32_16x16x32_bf16 v[26:29], v[74:77], v[208:211], v[26:29]
	v_mfma_f32_16x16x32_bf16 v[26:29], v[78:81], v[212:215], v[26:29]
	v_mfma_f32_16x16x32_bf16 v[10:13], v[74:77], v[216:219], v[10:13]
	v_mfma_f32_16x16x32_bf16 v[10:13], v[78:81], v[220:223], v[10:13]
	v_mfma_f32_16x16x32_bf16 v[14:17], v[58:61], v[216:219], v[14:17]
	v_mfma_f32_16x16x32_bf16 v[14:17], v[62:65], v[220:223], v[14:17]
	v_mfma_f32_16x16x32_bf16 v[54:57], v[82:85], v[186:189], v[54:57]
	v_mfma_f32_16x16x32_bf16 v[54:57], v[86:89], v[190:193], v[54:57]
	v_mfma_f32_16x16x32_bf16 v[50:53], v[90:93], v[186:189], v[50:53]
	v_mfma_f32_16x16x32_bf16 v[50:53], v[94:97], v[190:193], v[50:53]
	v_mfma_f32_16x16x32_bf16 v[34:37], v[90:93], v[200:203], v[34:37]
	v_mfma_f32_16x16x32_bf16 v[34:37], v[94:97], v[204:207], v[34:37]
	v_mfma_f32_16x16x32_bf16 v[38:41], v[82:85], v[200:203], v[38:41]
	v_mfma_f32_16x16x32_bf16 v[38:41], v[86:89], v[204:207], v[38:41]
	v_mfma_f32_16x16x32_bf16 v[22:25], v[82:85], v[208:211], v[22:25]
	v_mfma_f32_16x16x32_bf16 v[22:25], v[86:89], v[212:215], v[22:25]
	v_mfma_f32_16x16x32_bf16 v[18:21], v[90:93], v[208:211], v[18:21]
	v_mfma_f32_16x16x32_bf16 v[18:21], v[94:97], v[212:215], v[18:21]
	v_mfma_f32_16x16x32_bf16 v[2:5], v[90:93], v[216:219], v[2:5]
	v_mfma_f32_16x16x32_bf16 v[2:5], v[94:97], v[220:223], v[2:5]
	v_mfma_f32_16x16x32_bf16 v[6:9], v[82:85], v[216:219], v[6:9]
	v_mfma_f32_16x16x32_bf16 v[6:9], v[86:89], v[220:223], v[6:9]
	s_barrier
	s_setprio 0
	s_add_i32 s35, 16, 0x18000
	s_add_i32 s45, 16, 0x1c000
	v_add_u32_e32 v78, s35, v197
	v_add_u32_e32 v94, s45, v197
	ds_read_b128 v[58:61], v78
	ds_read_b128 v[62:65], v78 offset:1024
	ds_read_b128 v[74:77], v78 offset:2048
	ds_read_b128 v[78:81], v78 offset:3072
	ds_read_b128 v[82:85], v94
	ds_read_b128 v[86:89], v94 offset:1024
	ds_read_b128 v[90:93], v94 offset:2048
	ds_read_b128 v[94:97], v94 offset:3072
	s_add_u32 s10, s72, 0x40000
	s_addc_u32 s11, s73, 0
	s_mov_b32 m0, s3
	v_lshl_add_u64 v[240:241], s[10:11], 0, v[176:177]
	ds_read_b128 v[186:189], v199 offset:32768
	ds_read_b128 v[190:193], v199 offset:33792
	ds_read_b128 v[200:203], v199 offset:34816
	ds_read_b128 v[204:207], v199 offset:35840
	ds_read_b128 v[208:211], v199 offset:36864
	ds_read_b128 v[212:215], v199 offset:37888
	ds_read_b128 v[216:219], v199 offset:38912
	ds_read_b128 v[220:223], v199 offset:39936
	global_load_lds_dwordx4 v[240:241], off
	v_lshl_add_u64 v[240:241], s[10:11], 0, v[178:179]
	s_mov_b32 m0, s78
	s_nop 0
	global_load_lds_dwordx4 v[240:241], off
	s_waitcnt vmcnt(8)
	s_waitcnt lgkmcnt(0)
	s_setprio 1
	s_barrier
	v_mfma_f32_16x16x32_bf16 v[158:161], v[58:61], v[186:189], v[158:161]
	v_mfma_f32_16x16x32_bf16 v[158:161], v[62:65], v[190:193], v[158:161]
	v_mfma_f32_16x16x32_bf16 v[154:157], v[74:77], v[186:189], v[154:157]
	v_mfma_f32_16x16x32_bf16 v[154:157], v[78:81], v[190:193], v[154:157]
	v_mfma_f32_16x16x32_bf16 v[138:141], v[74:77], v[200:203], v[138:141]
	v_mfma_f32_16x16x32_bf16 v[138:141], v[78:81], v[204:207], v[138:141]
	v_mfma_f32_16x16x32_bf16 v[142:145], v[58:61], v[200:203], v[142:145]
	v_mfma_f32_16x16x32_bf16 v[142:145], v[62:65], v[204:207], v[142:145]
	v_mfma_f32_16x16x32_bf16 v[126:129], v[58:61], v[208:211], v[126:129]
	v_mfma_f32_16x16x32_bf16 v[126:129], v[62:65], v[212:215], v[126:129]
	v_mfma_f32_16x16x32_bf16 v[122:125], v[74:77], v[208:211], v[122:125]
	v_mfma_f32_16x16x32_bf16 v[122:125], v[78:81], v[212:215], v[122:125]
	v_mfma_f32_16x16x32_bf16 v[106:109], v[74:77], v[216:219], v[106:109]
	v_mfma_f32_16x16x32_bf16 v[106:109], v[78:81], v[220:223], v[106:109]
	v_mfma_f32_16x16x32_bf16 v[110:113], v[58:61], v[216:219], v[110:113]
	v_mfma_f32_16x16x32_bf16 v[110:113], v[62:65], v[220:223], v[110:113]
	v_mfma_f32_16x16x32_bf16 v[150:153], v[82:85], v[186:189], v[150:153]
	v_mfma_f32_16x16x32_bf16 v[150:153], v[86:89], v[190:193], v[150:153]
	v_mfma_f32_16x16x32_bf16 v[146:149], v[90:93], v[186:189], v[146:149]
	v_mfma_f32_16x16x32_bf16 v[146:149], v[94:97], v[190:193], v[146:149]
	v_mfma_f32_16x16x32_bf16 v[130:133], v[90:93], v[200:203], v[130:133]
	v_mfma_f32_16x16x32_bf16 v[130:133], v[94:97], v[204:207], v[130:133]
	v_mfma_f32_16x16x32_bf16 v[134:137], v[82:85], v[200:203], v[134:137]
	v_mfma_f32_16x16x32_bf16 v[134:137], v[86:89], v[204:207], v[134:137]
	v_mfma_f32_16x16x32_bf16 v[118:121], v[82:85], v[208:211], v[118:121]
	v_mfma_f32_16x16x32_bf16 v[118:121], v[86:89], v[212:215], v[118:121]
	v_mfma_f32_16x16x32_bf16 v[114:117], v[90:93], v[208:211], v[114:117]
	v_mfma_f32_16x16x32_bf16 v[114:117], v[94:97], v[212:215], v[114:117]
	v_mfma_f32_16x16x32_bf16 v[98:101], v[90:93], v[216:219], v[98:101]
	v_mfma_f32_16x16x32_bf16 v[98:101], v[94:97], v[220:223], v[98:101]
	v_mfma_f32_16x16x32_bf16 v[102:105], v[82:85], v[216:219], v[102:105]
	v_mfma_f32_16x16x32_bf16 v[102:105], v[86:89], v[220:223], v[102:105]
	s_barrier
; #define PG8_STAGE(bufoff, gbase, voff) do { _Pragma("unroll") for (int _i = 0; _i < 2; ++_i) \
;         __builtin_amdgcn_global_load_lds((const unsigned*)((const char*)(gbase) + (voff)[_i]), (PG8_LAS unsigned*)(lds + (bufoff) + ldsw + _i * 8192), 16, 0, 0); } while (0)
; #define PG8_LDA(dst, b, h) do { _Pragma("unroll") for (int m = 0; m < 4; ++m) _Pragma("unroll") for (int k = 0; k < 2; ++k) dst[m][k] = *(const PG8_LAS bf16x8*)(lds + PG8_SA(b, h) + aoff + m * 2048 + k * 1024); } while (0)
; #define PG8_MMA(ai, bj, At, Bt) do { __builtin_amdgcn_s_setprio(1); _Pragma("unroll") for (int m = 0; m < 4; ++m) _Pragma("unroll") for (int n = 0; n < 2; ++n) _Pragma("unroll") for (int k = 0; k < 2; ++k) \
;         acc[ai][bj][m][n] = __builtin_amdgcn_mfma_f32_16x16x32_bf16(Bt[n][k], At[m][k], acc[ai][bj][m][n], 0, 0, 0); __builtin_amdgcn_s_setprio(0); } while (0)
; #define PG8_WAIT_V(n) asm volatile("s_waitcnt vmcnt(" #n ")" ::: "memory")
; #define PG8_WAIT_L(n) asm volatile("s_waitcnt lgkmcnt(" #n ")" ::: "memory")
; #define PG8_BAR __builtin_amdgcn_s_barrier()
; #define PG8_SCHED __builtin_amdgcn_sched_barrier(0)
; template <class Epi, class Sched, bool ALIGN_EPI = false, bool SP2 = false>
; __device__ __forceinline__ void gemm_phase(PG8_LAS unsigned char* lds, const Gemm g, const Sched& S, const Epi& E) {
;     ...
;         for (int t = 0; t < nt; t += 2) {
;     ...
;             PG8_LDA(At, 1, 1); PG8_STAGE(PG8_SB(1, 0), b3, voffB); PG8_STAGE(PG8_SB(1, 1), b3 + hstep, voffB); PG8_STAGE(PG8_SA(1, 0), a3, voffA);
;             PG8_WAIT_V(8); PG8_WAIT_L(0); PG8_BAR; PG8_MMA(1, 0, At, B0); PG8_MMA(1, 1, At, B1); PG8_BAR; PG8_SCHED;
	s_setprio 0
	s_add_i32 s10, s35, s76
	v_lshl_add_u64 v[194:195], v[194:195], 0, s[28:29]
	s_mov_b32 m0, s10
	ds_read_b128 v[186:189], v199 offset:49152
	ds_read_b128 v[190:193], v199 offset:50176
	ds_read_b128 v[200:203], v199 offset:51200
	ds_read_b128 v[204:207], v199 offset:52224
	ds_read_b128 v[208:211], v199 offset:53248
	ds_read_b128 v[212:215], v199 offset:54272
	ds_read_b128 v[216:219], v199 offset:55296
	ds_read_b128 v[220:223], v199 offset:56320
	global_load_lds_dwordx4 v[194:195], off
	s_add_i32 m0, s10, 0x2000
	s_add_u32 s10, s68, 0x40080
	v_lshl_add_u64 v[194:195], v[224:225], 0, s[28:29]
	s_addc_u32 s11, s69, 0
	s_add_i32 s35, s45, s76
	global_load_lds_dwordx4 v[194:195], off
	v_lshl_add_u64 v[194:195], s[10:11], 0, v[0:1]
	s_mov_b32 m0, s35
	s_nop 0
	global_load_lds_dwordx4 v[194:195], off
	v_lshl_add_u64 v[194:195], s[10:11], 0, v[180:181]
	s_add_i32 m0, s35, 0x2000
	s_nop 0
	global_load_lds_dwordx4 v[194:195], off
	v_lshl_add_u64 v[194:195], v[226:227], 0, s[28:29]
	s_mov_b32 m0, s94
	s_nop 0
	global_load_lds_dwordx4 v[194:195], off
	v_lshl_add_u64 v[194:195], v[238:239], 0, s[28:29]
	s_mov_b32 m0, s95
	s_nop 0
	global_load_lds_dwordx4 v[194:195], off
	s_waitcnt vmcnt(8)
	s_waitcnt lgkmcnt(0)
	s_setprio 1
	s_barrier
	v_mfma_f32_16x16x32_bf16 v[70:73], v[58:61], v[186:189], v[70:73]
	v_mfma_f32_16x16x32_bf16 v[70:73], v[62:65], v[190:193], v[70:73]
	v_mfma_f32_16x16x32_bf16 v[66:69], v[74:77], v[186:189], v[66:69]
	v_mfma_f32_16x16x32_bf16 v[66:69], v[78:81], v[190:193], v[66:69]
	v_mfma_f32_16x16x32_bf16 v[42:45], v[74:77], v[200:203], v[42:45]
	v_mfma_f32_16x16x32_bf16 v[42:45], v[78:81], v[204:207], v[42:45]
	v_mfma_f32_16x16x32_bf16 v[46:49], v[58:61], v[200:203], v[46:49]
	v_mfma_f32_16x16x32_bf16 v[46:49], v[62:65], v[204:207], v[46:49]
	v_mfma_f32_16x16x32_bf16 v[30:33], v[58:61], v[208:211], v[30:33]
	v_mfma_f32_16x16x32_bf16 v[30:33], v[62:65], v[212:215], v[30:33]
	v_mfma_f32_16x16x32_bf16 v[26:29], v[74:77], v[208:211], v[26:29]
	v_mfma_f32_16x16x32_bf16 v[26:29], v[78:81], v[212:215], v[26:29]
	v_mfma_f32_16x16x32_bf16 v[10:13], v[74:77], v[216:219], v[10:13]
	v_mfma_f32_16x16x32_bf16 v[10:13], v[78:81], v[220:223], v[10:13]
	v_mfma_f32_16x16x32_bf16 v[14:17], v[58:61], v[216:219], v[14:17]
	v_mfma_f32_16x16x32_bf16 v[14:17], v[62:65], v[220:223], v[14:17]
	v_mfma_f32_16x16x32_bf16 v[54:57], v[82:85], v[186:189], v[54:57]
	v_mfma_f32_16x16x32_bf16 v[54:57], v[86:89], v[190:193], v[54:57]
	v_mfma_f32_16x16x32_bf16 v[50:53], v[90:93], v[186:189], v[50:53]
	v_mfma_f32_16x16x32_bf16 v[50:53], v[94:97], v[190:193], v[50:53]
	v_mfma_f32_16x16x32_bf16 v[34:37], v[90:93], v[200:203], v[34:37]
	v_mfma_f32_16x16x32_bf16 v[34:37], v[94:97], v[204:207], v[34:37]
	v_mfma_f32_16x16x32_bf16 v[38:41], v[82:85], v[200:203], v[38:41]
	v_mfma_f32_16x16x32_bf16 v[38:41], v[86:89], v[204:207], v[38:41]
	v_mfma_f32_16x16x32_bf16 v[22:25], v[82:85], v[208:211], v[22:25]
	v_mfma_f32_16x16x32_bf16 v[22:25], v[86:89], v[212:215], v[22:25]
	v_mfma_f32_16x16x32_bf16 v[18:21], v[90:93], v[208:211], v[18:21]
	v_mfma_f32_16x16x32_bf16 v[18:21], v[94:97], v[212:215], v[18:21]
	v_mfma_f32_16x16x32_bf16 v[2:5], v[90:93], v[216:219], v[2:5]
	v_mfma_f32_16x16x32_bf16 v[2:5], v[94:97], v[220:223], v[2:5]
	v_mfma_f32_16x16x32_bf16 v[6:9], v[82:85], v[216:219], v[6:9]
	v_mfma_f32_16x16x32_bf16 v[6:9], v[86:89], v[220:223], v[6:9]
	s_barrier
	s_setprio 0
	s_add_i32 s34, s34, 2
	s_add_u32 s25, s25, 0x100
	s_addc_u32 s27, s27, 0
	s_add_u32 s42, s42, 0x100
	s_addc_u32 s43, s43, 0
	s_cmp_gt_u32 s34, 13
	s_cbranch_scc0 .LBB0_915
	s_and_b64 vcc, exec, s[20:21]
	s_cbranch_vccz .LBB0_918
	s_barrier

; #define PG8_STAGE(bufoff, gbase, voff) do { _Pragma("unroll") for (int _i = 0; _i < 2; ++_i) \
;         __builtin_amdgcn_global_load_lds((const unsigned*)((const char*)(gbase) + (voff)[_i]), (PG8_LAS unsigned*)(lds + (bufoff) + ldsw + _i * 8192), 16, 0, 0); } while (0)
; #define PG8_LDA(dst, b, h) do { _Pragma("unroll") for (int m = 0; m < 4; ++m) _Pragma("unroll") for (int k = 0; k < 2; ++k) dst[m][k] = *(const PG8_LAS bf16x8*)(lds + PG8_SA(b, h) + aoff + m * 2048 + k * 1024); } while (0)
; #define PG8_LDB(dst, b, h) do { _Pragma("unroll") for (int n = 0; n < 2; ++n) _Pragma("unroll") for (int k = 0; k < 2; ++k) dst[n][k] = *(const PG8_LAS bf16x8*)(lds + PG8_SB(b, h) + boff + n * 2048 + k * 1024); } while (0)
; #define PG8_MMA(ai, bj, At, Bt) do { __builtin_amdgcn_s_setprio(1); _Pragma("unroll") for (int m = 0; m < 4; ++m) _Pragma("unroll") for (int n = 0; n < 2; ++n) _Pragma("unroll") for (int k = 0; k < 2; ++k) \
;         acc[ai][bj][m][n] = __builtin_amdgcn_mfma_f32_16x16x32_bf16(Bt[n][k], At[m][k], acc[ai][bj][m][n], 0, 0, 0); __builtin_amdgcn_s_setprio(0); } while (0)
; #define PG8_WAIT_V(n) asm volatile("s_waitcnt vmcnt(" #n ")" ::: "memory")
; #define PG8_WAIT_L(n) asm volatile("s_waitcnt lgkmcnt(" #n ")" ::: "memory")
; #define PG8_BAR __builtin_amdgcn_s_barrier()
; #define PG8_SCHED __builtin_amdgcn_sched_barrier(0)
; template <class Epi, class Sched, bool ALIGN_EPI = false, bool SP2 = false>
; __device__ __forceinline__ void gemm_phase(PG8_LAS unsigned char* lds, const Gemm g, const Sched& S, const Epi& E) {
;     ...
;             const bool last = (t == nt - 2);
;             const char* a1 = cA + (size_t)(t + 1) * kstep;
;             const char* a2 = last ? nA : cA + (size_t)(t + 2) * kstep; const char* b2 = last ? nB : cB + (size_t)(t + 2) * kstep;
;             const char* a3 = a2 + kstep; const char* b3 = b2 + kstep;
;             if (last && has_next) S.a_ready(nxt);
;             if constexpr (SP2) {
;             PG8_LDB(B0, 0, 0); PG8_LDB(B1, 0, 1); PG8_SCHED; PG8_LDA(At, 0, 0); PG8_STAGE(PG8_SA(1, 1), a1 + hstep, voffA);
;             PG8_WAIT_V(8); PG8_WAIT_L(0); PG8_BAR; PG8_MMA(0, 0, At, B0); PG8_MMA(0, 1, At, B1); PG8_BAR; PG8_SCHED;
;             PG8_LDA(At, 0, 1); PG8_STAGE(PG8_SB(0, 0), b2, voffB); PG8_STAGE(PG8_SB(0, 1), b2 + hstep, voffB); PG8_STAGE(PG8_SA(0, 0), a2, voffA);
.LBB0_1033:
	s_add_u32 s10, s50, 0xfffc0080
	s_addc_u32 s11, s51, -1
	s_add_i32 s69, 16, 0x10000
	s_cmp_eq_u32 s68, 12
	s_cselect_b32 s61, s34, s11
	s_cselect_b32 s60, s35, s10
	s_cselect_b32 s59, s27, s67
	s_cselect_b32 s58, s43, s66
	s_add_i32 s72, 16, 0x14000
	v_add_u32_e32 v142, s69, v177
	v_add_u32_e32 v188, s72, v177
	ds_read_b128 v[130:133], v142
	ds_read_b128 v[134:137], v142 offset:1024
	ds_read_b128 v[138:141], v142 offset:2048
	ds_read_b128 v[142:145], v142 offset:3072
	ds_read_b128 v[158:161], v188
	ds_read_b128 v[180:183], v188 offset:1024
	ds_read_b128 v[184:187], v188 offset:2048
	ds_read_b128 v[188:191], v188 offset:3072
	v_lshl_add_u64 v[224:225], s[50:51], 0, v[156:157]
	s_add_i32 m0, s9, 0xc000
	ds_read_b128 v[192:195], v179
	ds_read_b128 v[196:199], v179 offset:1024
	ds_read_b128 v[200:203], v179 offset:2048
	ds_read_b128 v[204:207], v179 offset:3072
	ds_read_b128 v[208:211], v179 offset:4096
	ds_read_b128 v[212:215], v179 offset:5120
	ds_read_b128 v[216:219], v179 offset:6144
	ds_read_b128 v[220:223], v179 offset:7168
	global_load_lds_dwordx4 v[224:225], off
	v_lshl_add_u64 v[224:225], s[50:51], 0, v[154:155]
	s_add_i32 m0, s9, 0xe000
	s_nop 0
	global_load_lds_dwordx4 v[224:225], off
	s_waitcnt vmcnt(8)
	s_waitcnt lgkmcnt(0)
	s_setprio 1
	s_barrier
	v_mfma_f32_16x16x32_bf16 v[126:129], v[130:133], v[192:195], v[126:129]
	v_mfma_f32_16x16x32_bf16 v[126:129], v[134:137], v[196:199], v[126:129]
	v_mfma_f32_16x16x32_bf16 v[122:125], v[138:141], v[192:195], v[122:125]
	v_mfma_f32_16x16x32_bf16 v[122:125], v[142:145], v[196:199], v[122:125]
	v_mfma_f32_16x16x32_bf16 v[106:109], v[138:141], v[200:203], v[106:109]
	v_mfma_f32_16x16x32_bf16 v[106:109], v[142:145], v[204:207], v[106:109]
	v_mfma_f32_16x16x32_bf16 v[110:113], v[130:133], v[200:203], v[110:113]
	v_mfma_f32_16x16x32_bf16 v[110:113], v[134:137], v[204:207], v[110:113]
	v_mfma_f32_16x16x32_bf16 v[94:97], v[130:133], v[208:211], v[94:97]
	v_mfma_f32_16x16x32_bf16 v[94:97], v[134:137], v[212:215], v[94:97]
	v_mfma_f32_16x16x32_bf16 v[90:93], v[138:141], v[208:211], v[90:93]
	v_mfma_f32_16x16x32_bf16 v[90:93], v[142:145], v[212:215], v[90:93]
	v_mfma_f32_16x16x32_bf16 v[74:77], v[138:141], v[216:219], v[74:77]
	v_mfma_f32_16x16x32_bf16 v[74:77], v[142:145], v[220:223], v[74:77]
	v_mfma_f32_16x16x32_bf16 v[78:81], v[130:133], v[216:219], v[78:81]
	v_mfma_f32_16x16x32_bf16 v[78:81], v[134:137], v[220:223], v[78:81]
	v_mfma_f32_16x16x32_bf16 v[118:121], v[158:161], v[192:195], v[118:121]
	v_mfma_f32_16x16x32_bf16 v[118:121], v[180:183], v[196:199], v[118:121]
	v_mfma_f32_16x16x32_bf16 v[114:117], v[184:187], v[192:195], v[114:117]
	v_mfma_f32_16x16x32_bf16 v[114:117], v[188:191], v[196:199], v[114:117]
	v_mfma_f32_16x16x32_bf16 v[98:101], v[184:187], v[200:203], v[98:101]
	v_mfma_f32_16x16x32_bf16 v[98:101], v[188:191], v[204:207], v[98:101]
	v_mfma_f32_16x16x32_bf16 v[102:105], v[158:161], v[200:203], v[102:105]
	v_mfma_f32_16x16x32_bf16 v[102:105], v[180:183], v[204:207], v[102:105]
	v_mfma_f32_16x16x32_bf16 v[86:89], v[158:161], v[208:211], v[86:89]
	v_mfma_f32_16x16x32_bf16 v[86:89], v[180:183], v[212:215], v[86:89]
	v_mfma_f32_16x16x32_bf16 v[82:85], v[184:187], v[208:211], v[82:85]
	v_mfma_f32_16x16x32_bf16 v[82:85], v[188:191], v[212:215], v[82:85]
	v_mfma_f32_16x16x32_bf16 v[66:69], v[184:187], v[216:219], v[66:69]
	v_mfma_f32_16x16x32_bf16 v[66:69], v[188:191], v[220:223], v[66:69]
	v_mfma_f32_16x16x32_bf16 v[70:73], v[158:161], v[216:219], v[70:73]
	v_mfma_f32_16x16x32_bf16 v[70:73], v[180:183], v[220:223], v[70:73]
	s_barrier
	s_setprio 0
	s_add_i32 s10, s69, s6
	v_lshl_add_u64 v[224:225], s[58:59], 0, v[0:1]
	s_mov_b32 m0, s10
	ds_read_b128 v[192:195], v179 offset:16384
	ds_read_b128 v[196:199], v179 offset:17408
	ds_read_b128 v[200:203], v179 offset:18432
	ds_read_b128 v[204:207], v179 offset:19456
	ds_read_b128 v[208:211], v179 offset:20480
	ds_read_b128 v[212:215], v179 offset:21504
	ds_read_b128 v[216:219], v179 offset:22528
	ds_read_b128 v[220:223], v179 offset:23552
	global_load_lds_dwordx4 v[224:225], off
	s_add_i32 m0, s10, 0x2000
	s_add_u32 s10, s58, 0x40000
	v_lshl_add_u64 v[226:227], s[58:59], 0, v[146:147]
	s_addc_u32 s11, s59, 0
	s_add_i32 s69, s72, s6
	global_load_lds_dwordx4 v[226:227], off
	v_lshl_add_u64 v[238:239], s[10:11], 0, v[0:1]
	s_mov_b32 m0, s69
	v_lshl_add_u64 v[240:241], s[60:61], 0, v[148:149]
	global_load_lds_dwordx4 v[238:239], off
	v_lshl_add_u64 v[238:239], s[10:11], 0, v[146:147]
	s_add_i32 m0, s69, 0x2000
	s_nop 0
	global_load_lds_dwordx4 v[238:239], off
	v_lshl_add_u64 v[238:239], s[60:61], 0, v[150:151]
	s_mov_b32 m0, s9
	s_nop 0
	global_load_lds_dwordx4 v[238:239], off
	s_mov_b32 m0, s54
	s_nop 0
	global_load_lds_dwordx4 v[240:241], off
	s_waitcnt vmcnt(8)
	s_waitcnt lgkmcnt(0)
	s_setprio 1
	s_barrier
; #define PG8_STAGE(bufoff, gbase, voff) do { _Pragma("unroll") for (int _i = 0; _i < 2; ++_i) \
;         __builtin_amdgcn_global_load_lds((const unsigned*)((const char*)(gbase) + (voff)[_i]), (PG8_LAS unsigned*)(lds + (bufoff) + ldsw + _i * 8192), 16, 0, 0); } while (0)
; #define PG8_LDA(dst, b, h) do { _Pragma("unroll") for (int m = 0; m < 4; ++m) _Pragma("unroll") for (int k = 0; k < 2; ++k) dst[m][k] = *(const PG8_LAS bf16x8*)(lds + PG8_SA(b, h) + aoff + m * 2048 + k * 1024); } while (0)
; #define PG8_LDB(dst, b, h) do { _Pragma("unroll") for (int n = 0; n < 2; ++n) _Pragma("unroll") for (int k = 0; k < 2; ++k) dst[n][k] = *(const PG8_LAS bf16x8*)(lds + PG8_SB(b, h) + boff + n * 2048 + k * 1024); } while (0)
; #define PG8_MMA(ai, bj, At, Bt) do { __builtin_amdgcn_s_setprio(1); _Pragma("unroll") for (int m = 0; m < 4; ++m) _Pragma("unroll") for (int n = 0; n < 2; ++n) _Pragma("unroll") for (int k = 0; k < 2; ++k) \
;         acc[ai][bj][m][n] = __builtin_amdgcn_mfma_f32_16x16x32_bf16(Bt[n][k], At[m][k], acc[ai][bj][m][n], 0, 0, 0); __builtin_amdgcn_s_setprio(0); } while (0)
; #define PG8_WAIT_V(n) asm volatile("s_waitcnt vmcnt(" #n ")" ::: "memory")
; #define PG8_WAIT_L(n) asm volatile("s_waitcnt lgkmcnt(" #n ")" ::: "memory")
; #define PG8_BAR __builtin_amdgcn_s_barrier()
; #define PG8_SCHED __builtin_amdgcn_sched_barrier(0)
; template <class Epi, class Sched, bool ALIGN_EPI = false, bool SP2 = false>
; __device__ __forceinline__ void gemm_phase(PG8_LAS unsigned char* lds, const Gemm g, const Sched& S, const Epi& E) {
;     ...
;             PG8_WAIT_V(8); PG8_WAIT_L(0); PG8_BAR; PG8_MMA(1, 0, At, B0); PG8_MMA(1, 1, At, B1); PG8_BAR; PG8_SCHED;
;             PG8_LDB(B0, 1, 0); PG8_LDB(B1, 1, 1); PG8_SCHED; PG8_LDA(At, 1, 0); PG8_STAGE(PG8_SA(0, 1), a2 + hstep, voffA);
;             PG8_WAIT_V(8); PG8_WAIT_L(0); PG8_BAR; PG8_MMA(0, 0, At, B0); PG8_MMA(0, 1, At, B1); PG8_BAR; PG8_SCHED;
	v_mfma_f32_16x16x32_bf16 v[62:65], v[130:133], v[192:195], v[62:65]
	v_mfma_f32_16x16x32_bf16 v[62:65], v[134:137], v[196:199], v[62:65]
	v_mfma_f32_16x16x32_bf16 v[58:61], v[138:141], v[192:195], v[58:61]
	v_mfma_f32_16x16x32_bf16 v[58:61], v[142:145], v[196:199], v[58:61]
	v_mfma_f32_16x16x32_bf16 v[42:45], v[138:141], v[200:203], v[42:45]
	v_mfma_f32_16x16x32_bf16 v[42:45], v[142:145], v[204:207], v[42:45]
	v_mfma_f32_16x16x32_bf16 v[46:49], v[130:133], v[200:203], v[46:49]
	v_mfma_f32_16x16x32_bf16 v[46:49], v[134:137], v[204:207], v[46:49]
	v_mfma_f32_16x16x32_bf16 v[30:33], v[130:133], v[208:211], v[30:33]
	v_mfma_f32_16x16x32_bf16 v[30:33], v[134:137], v[212:215], v[30:33]
	v_mfma_f32_16x16x32_bf16 v[26:29], v[138:141], v[208:211], v[26:29]
	v_mfma_f32_16x16x32_bf16 v[26:29], v[142:145], v[212:215], v[26:29]
	v_mfma_f32_16x16x32_bf16 v[10:13], v[138:141], v[216:219], v[10:13]
	v_mfma_f32_16x16x32_bf16 v[10:13], v[142:145], v[220:223], v[10:13]
	v_mfma_f32_16x16x32_bf16 v[14:17], v[130:133], v[216:219], v[14:17]
	v_mfma_f32_16x16x32_bf16 v[14:17], v[134:137], v[220:223], v[14:17]
	v_mfma_f32_16x16x32_bf16 v[54:57], v[158:161], v[192:195], v[54:57]
	v_mfma_f32_16x16x32_bf16 v[54:57], v[180:183], v[196:199], v[54:57]
	v_mfma_f32_16x16x32_bf16 v[50:53], v[184:187], v[192:195], v[50:53]
	v_mfma_f32_16x16x32_bf16 v[50:53], v[188:191], v[196:199], v[50:53]
	v_mfma_f32_16x16x32_bf16 v[34:37], v[184:187], v[200:203], v[34:37]
	v_mfma_f32_16x16x32_bf16 v[34:37], v[188:191], v[204:207], v[34:37]
	v_mfma_f32_16x16x32_bf16 v[38:41], v[158:161], v[200:203], v[38:41]
	v_mfma_f32_16x16x32_bf16 v[38:41], v[180:183], v[204:207], v[38:41]
	v_mfma_f32_16x16x32_bf16 v[22:25], v[158:161], v[208:211], v[22:25]
	v_mfma_f32_16x16x32_bf16 v[22:25], v[180:183], v[212:215], v[22:25]
	v_mfma_f32_16x16x32_bf16 v[18:21], v[184:187], v[208:211], v[18:21]
	v_mfma_f32_16x16x32_bf16 v[18:21], v[188:191], v[212:215], v[18:21]
	v_mfma_f32_16x16x32_bf16 v[2:5], v[184:187], v[216:219], v[2:5]
	v_mfma_f32_16x16x32_bf16 v[2:5], v[188:191], v[220:223], v[2:5]
	v_mfma_f32_16x16x32_bf16 v[6:9], v[158:161], v[216:219], v[6:9]
	v_mfma_f32_16x16x32_bf16 v[6:9], v[180:183], v[220:223], v[6:9]
	s_barrier
	s_setprio 0
	s_add_i32 s69, 16, 0x18000
	s_add_i32 s72, 16, 0x1c000
	v_add_u32_e32 v142, s69, v177
	v_add_u32_e32 v188, s72, v177
	ds_read_b128 v[130:133], v142
	ds_read_b128 v[134:137], v142 offset:1024
	ds_read_b128 v[138:141], v142 offset:2048
	ds_read_b128 v[142:145], v142 offset:3072
	ds_read_b128 v[158:161], v188
	ds_read_b128 v[180:183], v188 offset:1024
	ds_read_b128 v[184:187], v188 offset:2048
	ds_read_b128 v[188:191], v188 offset:3072
	s_add_u32 s10, s60, 0x40000
	s_addc_u32 s11, s61, 0
	s_mov_b32 m0, s55
	v_lshl_add_u64 v[242:243], s[10:11], 0, v[150:151]
	ds_read_b128 v[192:195], v179 offset:32768
	ds_read_b128 v[196:199], v179 offset:33792
	ds_read_b128 v[200:203], v179 offset:34816
	ds_read_b128 v[204:207], v179 offset:35840
	ds_read_b128 v[208:211], v179 offset:36864
	ds_read_b128 v[212:215], v179 offset:37888
	ds_read_b128 v[216:219], v179 offset:38912
	ds_read_b128 v[220:223], v179 offset:39936
	global_load_lds_dwordx4 v[242:243], off
	v_lshl_add_u64 v[242:243], s[10:11], 0, v[148:149]
	s_mov_b32 m0, s56
	s_nop 0
	global_load_lds_dwordx4 v[242:243], off
	s_waitcnt vmcnt(8)
	s_waitcnt lgkmcnt(0)
	s_setprio 1
	s_barrier
	v_mfma_f32_16x16x32_bf16 v[126:129], v[130:133], v[192:195], v[126:129]
	v_mfma_f32_16x16x32_bf16 v[126:129], v[134:137], v[196:199], v[126:129]
	v_mfma_f32_16x16x32_bf16 v[122:125], v[138:141], v[192:195], v[122:125]
	v_mfma_f32_16x16x32_bf16 v[122:125], v[142:145], v[196:199], v[122:125]
	v_mfma_f32_16x16x32_bf16 v[106:109], v[138:141], v[200:203], v[106:109]
	v_mfma_f32_16x16x32_bf16 v[106:109], v[142:145], v[204:207], v[106:109]
	v_mfma_f32_16x16x32_bf16 v[110:113], v[130:133], v[200:203], v[110:113]
	v_mfma_f32_16x16x32_bf16 v[110:113], v[134:137], v[204:207], v[110:113]
	v_mfma_f32_16x16x32_bf16 v[94:97], v[130:133], v[208:211], v[94:97]
	v_mfma_f32_16x16x32_bf16 v[94:97], v[134:137], v[212:215], v[94:97]
	v_mfma_f32_16x16x32_bf16 v[90:93], v[138:141], v[208:211], v[90:93]
	v_mfma_f32_16x16x32_bf16 v[90:93], v[142:145], v[212:215], v[90:93]
	v_mfma_f32_16x16x32_bf16 v[74:77], v[138:141], v[216:219], v[74:77]
	v_mfma_f32_16x16x32_bf16 v[74:77], v[142:145], v[220:223], v[74:77]
	v_mfma_f32_16x16x32_bf16 v[78:81], v[130:133], v[216:219], v[78:81]
	v_mfma_f32_16x16x32_bf16 v[78:81], v[134:137], v[220:223], v[78:81]
	v_mfma_f32_16x16x32_bf16 v[118:121], v[158:161], v[192:195], v[118:121]
	v_mfma_f32_16x16x32_bf16 v[118:121], v[180:183], v[196:199], v[118:121]
	v_mfma_f32_16x16x32_bf16 v[114:117], v[184:187], v[192:195], v[114:117]
	v_mfma_f32_16x16x32_bf16 v[114:117], v[188:191], v[196:199], v[114:117]
	v_mfma_f32_16x16x32_bf16 v[98:101], v[184:187], v[200:203], v[98:101]
	v_mfma_f32_16x16x32_bf16 v[98:101], v[188:191], v[204:207], v[98:101]
	v_mfma_f32_16x16x32_bf16 v[102:105], v[158:161], v[200:203], v[102:105]
	v_mfma_f32_16x16x32_bf16 v[102:105], v[180:183], v[204:207], v[102:105]
	v_mfma_f32_16x16x32_bf16 v[86:89], v[158:161], v[208:211], v[86:89]
	v_mfma_f32_16x16x32_bf16 v[86:89], v[180:183], v[212:215], v[86:89]
	v_mfma_f32_16x16x32_bf16 v[82:85], v[184:187], v[208:211], v[82:85]
	v_mfma_f32_16x16x32_bf16 v[82:85], v[188:191], v[212:215], v[82:85]
	v_mfma_f32_16x16x32_bf16 v[66:69], v[184:187], v[216:219], v[66:69]
	v_mfma_f32_16x16x32_bf16 v[66:69], v[188:191], v[220:223], v[66:69]
	v_mfma_f32_16x16x32_bf16 v[70:73], v[158:161], v[216:219], v[70:73]
	v_mfma_f32_16x16x32_bf16 v[70:73], v[180:183], v[220:223], v[70:73]
	s_barrier
; #define PG8_STAGE(bufoff, gbase, voff) do { _Pragma("unroll") for (int _i = 0; _i < 2; ++_i) \
;         __builtin_amdgcn_global_load_lds((const unsigned*)((const char*)(gbase) + (voff)[_i]), (PG8_LAS unsigned*)(lds + (bufoff) + ldsw + _i * 8192), 16, 0, 0); } while (0)
; #define PG8_LDA(dst, b, h) do { _Pragma("unroll") for (int m = 0; m < 4; ++m) _Pragma("unroll") for (int k = 0; k < 2; ++k) dst[m][k] = *(const PG8_LAS bf16x8*)(lds + PG8_SA(b, h) + aoff + m * 2048 + k * 1024); } while (0)
; #define PG8_MMA(ai, bj, At, Bt) do { __builtin_amdgcn_s_setprio(1); _Pragma("unroll") for (int m = 0; m < 4; ++m) _Pragma("unroll") for (int n = 0; n < 2; ++n) _Pragma("unroll") for (int k = 0; k < 2; ++k) \
;         acc[ai][bj][m][n] = __builtin_amdgcn_mfma_f32_16x16x32_bf16(Bt[n][k], At[m][k], acc[ai][bj][m][n], 0, 0, 0); __builtin_amdgcn_s_setprio(0); } while (0)
; #define PG8_WAIT_V(n) asm volatile("s_waitcnt vmcnt(" #n ")" ::: "memory")
; #define PG8_WAIT_L(n) asm volatile("s_waitcnt lgkmcnt(" #n ")" ::: "memory")
; #define PG8_BAR __builtin_amdgcn_s_barrier()
; #define PG8_SCHED __builtin_amdgcn_sched_barrier(0)
; template <class Epi, class Sched, bool ALIGN_EPI = false, bool SP2 = false>
; __device__ __forceinline__ void gemm_phase(PG8_LAS unsigned char* lds, const Gemm g, const Sched& S, const Epi& E) {
;     ...
;         for (int t = 0; t < nt; t += 2) {
;     ...
;             PG8_LDA(At, 1, 1); PG8_STAGE(PG8_SB(1, 0), b3, voffB); PG8_STAGE(PG8_SB(1, 1), b3 + hstep, voffB); PG8_STAGE(PG8_SA(1, 0), a3, voffA);
;             PG8_WAIT_V(8); PG8_WAIT_L(0); PG8_BAR; PG8_MMA(1, 0, At, B0); PG8_MMA(1, 1, At, B1); PG8_BAR; PG8_SCHED;
	s_setprio 0
	s_add_i32 s10, s69, s6
	v_lshl_add_u64 v[224:225], v[224:225], 0, s[28:29]
	s_mov_b32 m0, s10
	ds_read_b128 v[192:195], v179 offset:49152
	ds_read_b128 v[196:199], v179 offset:50176
	ds_read_b128 v[200:203], v179 offset:51200
	ds_read_b128 v[204:207], v179 offset:52224
	ds_read_b128 v[208:211], v179 offset:53248
	ds_read_b128 v[212:215], v179 offset:54272
	ds_read_b128 v[216:219], v179 offset:55296
	ds_read_b128 v[220:223], v179 offset:56320
	global_load_lds_dwordx4 v[224:225], off
	s_add_i32 m0, s10, 0x2000
	s_add_u32 s10, s58, 0x40080
	v_lshl_add_u64 v[224:225], v[226:227], 0, s[28:29]
	s_addc_u32 s11, s59, 0
	s_add_i32 s58, s72, s6
	global_load_lds_dwordx4 v[224:225], off
	v_lshl_add_u64 v[224:225], s[10:11], 0, v[0:1]
	s_mov_b32 m0, s58
	s_nop 0
	global_load_lds_dwordx4 v[224:225], off
	v_lshl_add_u64 v[224:225], s[10:11], 0, v[146:147]
	s_add_i32 m0, s58, 0x2000
	s_nop 0
	global_load_lds_dwordx4 v[224:225], off
	v_lshl_add_u64 v[224:225], v[238:239], 0, s[28:29]
	s_mov_b32 m0, s63
	s_nop 0
	global_load_lds_dwordx4 v[224:225], off
	v_lshl_add_u64 v[224:225], v[240:241], 0, s[28:29]
	s_mov_b32 m0, s64
	s_nop 0
	global_load_lds_dwordx4 v[224:225], off
	s_waitcnt vmcnt(8)
	s_waitcnt lgkmcnt(0)
	s_setprio 1
	s_barrier
	v_mfma_f32_16x16x32_bf16 v[62:65], v[130:133], v[192:195], v[62:65]
	v_mfma_f32_16x16x32_bf16 v[62:65], v[134:137], v[196:199], v[62:65]
	v_mfma_f32_16x16x32_bf16 v[58:61], v[138:141], v[192:195], v[58:61]
	v_mfma_f32_16x16x32_bf16 v[58:61], v[142:145], v[196:199], v[58:61]
	v_mfma_f32_16x16x32_bf16 v[42:45], v[138:141], v[200:203], v[42:45]
	v_mfma_f32_16x16x32_bf16 v[42:45], v[142:145], v[204:207], v[42:45]
	v_mfma_f32_16x16x32_bf16 v[46:49], v[130:133], v[200:203], v[46:49]
	v_mfma_f32_16x16x32_bf16 v[46:49], v[134:137], v[204:207], v[46:49]
	v_mfma_f32_16x16x32_bf16 v[30:33], v[130:133], v[208:211], v[30:33]
	v_mfma_f32_16x16x32_bf16 v[30:33], v[134:137], v[212:215], v[30:33]
	v_mfma_f32_16x16x32_bf16 v[26:29], v[138:141], v[208:211], v[26:29]
	v_mfma_f32_16x16x32_bf16 v[26:29], v[142:145], v[212:215], v[26:29]
	v_mfma_f32_16x16x32_bf16 v[10:13], v[138:141], v[216:219], v[10:13]
	v_mfma_f32_16x16x32_bf16 v[10:13], v[142:145], v[220:223], v[10:13]
	v_mfma_f32_16x16x32_bf16 v[14:17], v[130:133], v[216:219], v[14:17]
	v_mfma_f32_16x16x32_bf16 v[14:17], v[134:137], v[220:223], v[14:17]
	v_mfma_f32_16x16x32_bf16 v[54:57], v[158:161], v[192:195], v[54:57]
	v_mfma_f32_16x16x32_bf16 v[54:57], v[180:183], v[196:199], v[54:57]
	v_mfma_f32_16x16x32_bf16 v[50:53], v[184:187], v[192:195], v[50:53]
	v_mfma_f32_16x16x32_bf16 v[50:53], v[188:191], v[196:199], v[50:53]
	v_mfma_f32_16x16x32_bf16 v[34:37], v[184:187], v[200:203], v[34:37]
	v_mfma_f32_16x16x32_bf16 v[34:37], v[188:191], v[204:207], v[34:37]
	v_mfma_f32_16x16x32_bf16 v[38:41], v[158:161], v[200:203], v[38:41]
	v_mfma_f32_16x16x32_bf16 v[38:41], v[180:183], v[204:207], v[38:41]
	v_mfma_f32_16x16x32_bf16 v[22:25], v[158:161], v[208:211], v[22:25]
	v_mfma_f32_16x16x32_bf16 v[22:25], v[180:183], v[212:215], v[22:25]
	v_mfma_f32_16x16x32_bf16 v[18:21], v[184:187], v[208:211], v[18:21]
	v_mfma_f32_16x16x32_bf16 v[18:21], v[188:191], v[212:215], v[18:21]
	v_mfma_f32_16x16x32_bf16 v[2:5], v[184:187], v[216:219], v[2:5]
	v_mfma_f32_16x16x32_bf16 v[2:5], v[188:191], v[220:223], v[2:5]
	v_mfma_f32_16x16x32_bf16 v[6:9], v[158:161], v[216:219], v[6:9]
	v_mfma_f32_16x16x32_bf16 v[6:9], v[180:183], v[220:223], v[6:9]
	s_barrier
	s_setprio 0
	s_add_i32 s68, s68, 2
	s_add_u32 s66, s66, 0x100
	s_addc_u32 s67, s67, 0
	s_add_u32 s50, s50, 0x100
	s_addc_u32 s51, s51, 0
	s_cmp_gt_u32 s68, 13
	s_cbranch_scc0 .LBB0_1033
	s_and_b64 vcc, exec, s[24:25]
	s_cbranch_vccz .LBB0_1036
	s_barrier

; #define PG8_STAGE(bufoff, gbase, voff) do { _Pragma("unroll") for (int _i = 0; _i < 2; ++_i) \
;         __builtin_amdgcn_global_load_lds((const unsigned*)((const char*)(gbase) + (voff)[_i]), (PG8_LAS unsigned*)(lds + (bufoff) + ldsw + _i * 8192), 16, 0, 0); } while (0)
; #define PG8_LDA(dst, b, h) do { _Pragma("unroll") for (int m = 0; m < 4; ++m) _Pragma("unroll") for (int k = 0; k < 2; ++k) dst[m][k] = *(const PG8_LAS bf16x8*)(lds + PG8_SA(b, h) + aoff + m * 2048 + k * 1024); } while (0)
; #define PG8_LDB(dst, b, h) do { _Pragma("unroll") for (int n = 0; n < 2; ++n) _Pragma("unroll") for (int k = 0; k < 2; ++k) dst[n][k] = *(const PG8_LAS bf16x8*)(lds + PG8_SB(b, h) + boff + n * 2048 + k * 1024); } while (0)
; #define PG8_MMA(ai, bj, At, Bt) do { __builtin_amdgcn_s_setprio(1); _Pragma("unroll") for (int m = 0; m < 4; ++m) _Pragma("unroll") for (int n = 0; n < 2; ++n) _Pragma("unroll") for (int k = 0; k < 2; ++k) \
;         acc[ai][bj][m][n] = __builtin_amdgcn_mfma_f32_16x16x32_bf16(Bt[n][k], At[m][k], acc[ai][bj][m][n], 0, 0, 0); __builtin_amdgcn_s_setprio(0); } while (0)
; #define PG8_WAIT_V(n) asm volatile("s_waitcnt vmcnt(" #n ")" ::: "memory")
; #define PG8_WAIT_L(n) asm volatile("s_waitcnt lgkmcnt(" #n ")" ::: "memory")
; #define PG8_BAR __builtin_amdgcn_s_barrier()
; #define PG8_SCHED __builtin_amdgcn_sched_barrier(0)
; template <class Epi, class Sched, bool ALIGN_EPI = false, bool SP2 = false>
; __device__ __forceinline__ void gemm_phase(PG8_LAS unsigned char* lds, const Gemm g, const Sched& S, const Epi& E) {
;     ...
;             const bool last = (t == nt - 2);
;             const char* a1 = cA + (size_t)(t + 1) * kstep;
;             const char* a2 = last ? nA : cA + (size_t)(t + 2) * kstep; const char* b2 = last ? nB : cB + (size_t)(t + 2) * kstep;
;             const char* a3 = a2 + kstep; const char* b3 = b2 + kstep;
;             if (last && has_next) S.a_ready(nxt);
;             if constexpr (SP2) {
;             PG8_LDB(B0, 0, 0); PG8_LDB(B1, 0, 1); PG8_SCHED; PG8_LDA(At, 0, 0); PG8_STAGE(PG8_SA(1, 1), a1 + hstep, voffA);
;             PG8_WAIT_V(8); PG8_WAIT_L(0); PG8_BAR; PG8_MMA(0, 0, At, B0); PG8_MMA(0, 1, At, B1); PG8_BAR; PG8_SCHED;
;             PG8_LDA(At, 0, 1); PG8_STAGE(PG8_SB(0, 0), b2, voffB); PG8_STAGE(PG8_SB(0, 1), b2 + hstep, voffB); PG8_STAGE(PG8_SA(0, 0), a2, voffA);
.LBB0_1208:
	s_add_u32 s42, s24, 0x100
	s_addc_u32 s43, s25, 0
	s_add_i32 s10, 16, 0x10000
	s_cmp_eq_u32 s73, 40
	s_cselect_b32 s69, s23, s43
	s_cselect_b32 s68, s22, s42
	s_cselect_b32 s45, s27, s72
	s_cselect_b32 s44, s26, s35
	s_add_i32 vcc_lo, 16, 0x14000
	v_add_u32_e32 v78, s10, v197
	v_add_u32_e32 v94, vcc_lo, v197
	ds_read_b128 v[58:61], v78
	ds_read_b128 v[62:65], v78 offset:1024
	ds_read_b128 v[74:77], v78 offset:2048
	ds_read_b128 v[78:81], v78 offset:3072
	ds_read_b128 v[82:85], v94
	ds_read_b128 v[86:89], v94 offset:1024
	ds_read_b128 v[90:93], v94 offset:2048
	ds_read_b128 v[94:97], v94 offset:3072
	v_lshl_add_u64 v[194:195], s[24:25], 0, v[184:185]
	s_add_i32 m0, s95, 0xc000
	ds_read_b128 v[186:189], v199
	ds_read_b128 v[190:193], v199 offset:1024
	ds_read_b128 v[200:203], v199 offset:2048
	ds_read_b128 v[204:207], v199 offset:3072
	ds_read_b128 v[208:211], v199 offset:4096
	ds_read_b128 v[212:215], v199 offset:5120
	ds_read_b128 v[216:219], v199 offset:6144
	ds_read_b128 v[220:223], v199 offset:7168
	global_load_lds_dwordx4 v[194:195], off
	v_lshl_add_u64 v[194:195], s[24:25], 0, v[182:183]
	s_add_i32 m0, s95, 0xe000
	s_nop 0
	global_load_lds_dwordx4 v[194:195], off
	s_waitcnt vmcnt(8)
	s_waitcnt lgkmcnt(0)
	s_setprio 1
	s_barrier
	v_mfma_f32_16x16x32_bf16 v[158:161], v[58:61], v[186:189], v[158:161]
	v_mfma_f32_16x16x32_bf16 v[158:161], v[62:65], v[190:193], v[158:161]
	v_mfma_f32_16x16x32_bf16 v[154:157], v[74:77], v[186:189], v[154:157]
	v_mfma_f32_16x16x32_bf16 v[154:157], v[78:81], v[190:193], v[154:157]
	v_mfma_f32_16x16x32_bf16 v[138:141], v[74:77], v[200:203], v[138:141]
	v_mfma_f32_16x16x32_bf16 v[138:141], v[78:81], v[204:207], v[138:141]
	v_mfma_f32_16x16x32_bf16 v[142:145], v[58:61], v[200:203], v[142:145]
	v_mfma_f32_16x16x32_bf16 v[142:145], v[62:65], v[204:207], v[142:145]
	v_mfma_f32_16x16x32_bf16 v[126:129], v[58:61], v[208:211], v[126:129]
	v_mfma_f32_16x16x32_bf16 v[126:129], v[62:65], v[212:215], v[126:129]
	v_mfma_f32_16x16x32_bf16 v[122:125], v[74:77], v[208:211], v[122:125]
	v_mfma_f32_16x16x32_bf16 v[122:125], v[78:81], v[212:215], v[122:125]
	v_mfma_f32_16x16x32_bf16 v[106:109], v[74:77], v[216:219], v[106:109]
	v_mfma_f32_16x16x32_bf16 v[106:109], v[78:81], v[220:223], v[106:109]
	v_mfma_f32_16x16x32_bf16 v[110:113], v[58:61], v[216:219], v[110:113]
	v_mfma_f32_16x16x32_bf16 v[110:113], v[62:65], v[220:223], v[110:113]
	v_mfma_f32_16x16x32_bf16 v[150:153], v[82:85], v[186:189], v[150:153]
	v_mfma_f32_16x16x32_bf16 v[150:153], v[86:89], v[190:193], v[150:153]
	v_mfma_f32_16x16x32_bf16 v[146:149], v[90:93], v[186:189], v[146:149]
	v_mfma_f32_16x16x32_bf16 v[146:149], v[94:97], v[190:193], v[146:149]
	v_mfma_f32_16x16x32_bf16 v[130:133], v[90:93], v[200:203], v[130:133]
	v_mfma_f32_16x16x32_bf16 v[130:133], v[94:97], v[204:207], v[130:133]
	v_mfma_f32_16x16x32_bf16 v[134:137], v[82:85], v[200:203], v[134:137]
	v_mfma_f32_16x16x32_bf16 v[134:137], v[86:89], v[204:207], v[134:137]
	v_mfma_f32_16x16x32_bf16 v[118:121], v[82:85], v[208:211], v[118:121]
	v_mfma_f32_16x16x32_bf16 v[118:121], v[86:89], v[212:215], v[118:121]
	v_mfma_f32_16x16x32_bf16 v[114:117], v[90:93], v[208:211], v[114:117]
	v_mfma_f32_16x16x32_bf16 v[114:117], v[94:97], v[212:215], v[114:117]
	v_mfma_f32_16x16x32_bf16 v[98:101], v[90:93], v[216:219], v[98:101]
	v_mfma_f32_16x16x32_bf16 v[98:101], v[94:97], v[220:223], v[98:101]
	v_mfma_f32_16x16x32_bf16 v[102:105], v[82:85], v[216:219], v[102:105]
	v_mfma_f32_16x16x32_bf16 v[102:105], v[86:89], v[220:223], v[102:105]
	s_barrier
	s_setprio 0
	s_add_i32 s10, s10, s94
	v_lshl_add_u64 v[194:195], s[44:45], 0, v[0:1]
	s_mov_b32 m0, s10
	ds_read_b128 v[186:189], v199 offset:16384
	ds_read_b128 v[190:193], v199 offset:17408
	ds_read_b128 v[200:203], v199 offset:18432
	ds_read_b128 v[204:207], v199 offset:19456
	ds_read_b128 v[208:211], v199 offset:20480
	ds_read_b128 v[212:215], v199 offset:21504
	ds_read_b128 v[216:219], v199 offset:22528
	ds_read_b128 v[220:223], v199 offset:23552
	global_load_lds_dwordx4 v[194:195], off
	s_add_i32 m0, s10, 0x2000
	s_add_u32 s10, s44, 0xb0000
	v_lshl_add_u64 v[224:225], s[44:45], 0, v[180:181]
	s_addc_u32 s11, s45, 0
	s_add_i32 s24, vcc_lo, s94
	global_load_lds_dwordx4 v[224:225], off
	v_lshl_add_u64 v[226:227], s[10:11], 0, v[0:1]
	s_mov_b32 m0, s24
	v_lshl_add_u64 v[238:239], s[68:69], 0, v[178:179]
	global_load_lds_dwordx4 v[226:227], off
	v_lshl_add_u64 v[226:227], s[10:11], 0, v[180:181]
	s_add_i32 m0, s24, 0x2000
	s_nop 0
	global_load_lds_dwordx4 v[226:227], off
	v_lshl_add_u64 v[226:227], s[68:69], 0, v[176:177]
	s_mov_b32 m0, s95
	s_nop 0
	global_load_lds_dwordx4 v[226:227], off
	s_mov_b32 m0, s2
	s_nop 0
	global_load_lds_dwordx4 v[238:239], off
	s_waitcnt vmcnt(8)
	s_waitcnt lgkmcnt(0)
	s_setprio 1
	s_barrier
; #define PG8_STAGE(bufoff, gbase, voff) do { _Pragma("unroll") for (int _i = 0; _i < 2; ++_i) \
;         __builtin_amdgcn_global_load_lds((const unsigned*)((const char*)(gbase) + (voff)[_i]), (PG8_LAS unsigned*)(lds + (bufoff) + ldsw + _i * 8192), 16, 0, 0); } while (0)
; #define PG8_LDA(dst, b, h) do { _Pragma("unroll") for (int m = 0; m < 4; ++m) _Pragma("unroll") for (int k = 0; k < 2; ++k) dst[m][k] = *(const PG8_LAS bf16x8*)(lds + PG8_SA(b, h) + aoff + m * 2048 + k * 1024); } while (0)
; #define PG8_LDB(dst, b, h) do { _Pragma("unroll") for (int n = 0; n < 2; ++n) _Pragma("unroll") for (int k = 0; k < 2; ++k) dst[n][k] = *(const PG8_LAS bf16x8*)(lds + PG8_SB(b, h) + boff + n * 2048 + k * 1024); } while (0)
; #define PG8_MMA(ai, bj, At, Bt) do { __builtin_amdgcn_s_setprio(1); _Pragma("unroll") for (int m = 0; m < 4; ++m) _Pragma("unroll") for (int n = 0; n < 2; ++n) _Pragma("unroll") for (int k = 0; k < 2; ++k) \
;         acc[ai][bj][m][n] = __builtin_amdgcn_mfma_f32_16x16x32_bf16(Bt[n][k], At[m][k], acc[ai][bj][m][n], 0, 0, 0); __builtin_amdgcn_s_setprio(0); } while (0)
; #define PG8_WAIT_V(n) asm volatile("s_waitcnt vmcnt(" #n ")" ::: "memory")
; #define PG8_WAIT_L(n) asm volatile("s_waitcnt lgkmcnt(" #n ")" ::: "memory")
; #define PG8_BAR __builtin_amdgcn_s_barrier()
; #define PG8_SCHED __builtin_amdgcn_sched_barrier(0)
; template <class Epi, class Sched, bool ALIGN_EPI = false, bool SP2 = false>
; __device__ __forceinline__ void gemm_phase(PG8_LAS unsigned char* lds, const Gemm g, const Sched& S, const Epi& E) {
;     ...
;             PG8_WAIT_V(8); PG8_WAIT_L(0); PG8_BAR; PG8_MMA(1, 0, At, B0); PG8_MMA(1, 1, At, B1); PG8_BAR; PG8_SCHED;
;             PG8_LDB(B0, 1, 0); PG8_LDB(B1, 1, 1); PG8_SCHED; PG8_LDA(At, 1, 0); PG8_STAGE(PG8_SA(0, 1), a2 + hstep, voffA);
;             PG8_WAIT_V(8); PG8_WAIT_L(0); PG8_BAR; PG8_MMA(0, 0, At, B0); PG8_MMA(0, 1, At, B1); PG8_BAR; PG8_SCHED;
	v_mfma_f32_16x16x32_bf16 v[70:73], v[58:61], v[186:189], v[70:73]
	v_mfma_f32_16x16x32_bf16 v[70:73], v[62:65], v[190:193], v[70:73]
	v_mfma_f32_16x16x32_bf16 v[66:69], v[74:77], v[186:189], v[66:69]
	v_mfma_f32_16x16x32_bf16 v[66:69], v[78:81], v[190:193], v[66:69]
	v_mfma_f32_16x16x32_bf16 v[42:45], v[74:77], v[200:203], v[42:45]
	v_mfma_f32_16x16x32_bf16 v[42:45], v[78:81], v[204:207], v[42:45]
	v_mfma_f32_16x16x32_bf16 v[46:49], v[58:61], v[200:203], v[46:49]
	v_mfma_f32_16x16x32_bf16 v[46:49], v[62:65], v[204:207], v[46:49]
	v_mfma_f32_16x16x32_bf16 v[30:33], v[58:61], v[208:211], v[30:33]
	v_mfma_f32_16x16x32_bf16 v[30:33], v[62:65], v[212:215], v[30:33]
	v_mfma_f32_16x16x32_bf16 v[26:29], v[74:77], v[208:211], v[26:29]
	v_mfma_f32_16x16x32_bf16 v[26:29], v[78:81], v[212:215], v[26:29]
	v_mfma_f32_16x16x32_bf16 v[10:13], v[74:77], v[216:219], v[10:13]
	v_mfma_f32_16x16x32_bf16 v[10:13], v[78:81], v[220:223], v[10:13]
	v_mfma_f32_16x16x32_bf16 v[14:17], v[58:61], v[216:219], v[14:17]
	v_mfma_f32_16x16x32_bf16 v[14:17], v[62:65], v[220:223], v[14:17]
	v_mfma_f32_16x16x32_bf16 v[54:57], v[82:85], v[186:189], v[54:57]
	v_mfma_f32_16x16x32_bf16 v[54:57], v[86:89], v[190:193], v[54:57]
	v_mfma_f32_16x16x32_bf16 v[50:53], v[90:93], v[186:189], v[50:53]
	v_mfma_f32_16x16x32_bf16 v[50:53], v[94:97], v[190:193], v[50:53]
	v_mfma_f32_16x16x32_bf16 v[34:37], v[90:93], v[200:203], v[34:37]
	v_mfma_f32_16x16x32_bf16 v[34:37], v[94:97], v[204:207], v[34:37]
	v_mfma_f32_16x16x32_bf16 v[38:41], v[82:85], v[200:203], v[38:41]
	v_mfma_f32_16x16x32_bf16 v[38:41], v[86:89], v[204:207], v[38:41]
	v_mfma_f32_16x16x32_bf16 v[22:25], v[82:85], v[208:211], v[22:25]
	v_mfma_f32_16x16x32_bf16 v[22:25], v[86:89], v[212:215], v[22:25]
	v_mfma_f32_16x16x32_bf16 v[18:21], v[90:93], v[208:211], v[18:21]
	v_mfma_f32_16x16x32_bf16 v[18:21], v[94:97], v[212:215], v[18:21]
	v_mfma_f32_16x16x32_bf16 v[2:5], v[90:93], v[216:219], v[2:5]
	v_mfma_f32_16x16x32_bf16 v[2:5], v[94:97], v[220:223], v[2:5]
	v_mfma_f32_16x16x32_bf16 v[6:9], v[82:85], v[216:219], v[6:9]
	v_mfma_f32_16x16x32_bf16 v[6:9], v[86:89], v[220:223], v[6:9]
	s_barrier
	s_setprio 0
	s_add_i32 s24, 16, 0x18000
	s_add_i32 s25, 16, 0x1c000
	v_add_u32_e32 v78, s24, v197
	v_add_u32_e32 v94, s25, v197
	ds_read_b128 v[58:61], v78
	ds_read_b128 v[62:65], v78 offset:1024
	ds_read_b128 v[74:77], v78 offset:2048
	ds_read_b128 v[78:81], v78 offset:3072
	ds_read_b128 v[82:85], v94
	ds_read_b128 v[86:89], v94 offset:1024
	ds_read_b128 v[90:93], v94 offset:2048
	ds_read_b128 v[94:97], v94 offset:3072
	s_add_u32 s10, s68, 0xb0000
	s_addc_u32 s11, s69, 0
	s_mov_b32 m0, s3
	v_lshl_add_u64 v[240:241], s[10:11], 0, v[176:177]
	ds_read_b128 v[186:189], v199 offset:32768
	ds_read_b128 v[190:193], v199 offset:33792
	ds_read_b128 v[200:203], v199 offset:34816
	ds_read_b128 v[204:207], v199 offset:35840
	ds_read_b128 v[208:211], v199 offset:36864
	ds_read_b128 v[212:215], v199 offset:37888
	ds_read_b128 v[216:219], v199 offset:38912
	ds_read_b128 v[220:223], v199 offset:39936
	global_load_lds_dwordx4 v[240:241], off
	v_lshl_add_u64 v[240:241], s[10:11], 0, v[178:179]
	s_mov_b32 m0, s96
	s_nop 0
	global_load_lds_dwordx4 v[240:241], off
	s_waitcnt vmcnt(8)
	s_waitcnt lgkmcnt(0)
	s_setprio 1
	s_barrier
	v_mfma_f32_16x16x32_bf16 v[158:161], v[58:61], v[186:189], v[158:161]
	v_mfma_f32_16x16x32_bf16 v[158:161], v[62:65], v[190:193], v[158:161]
	v_mfma_f32_16x16x32_bf16 v[154:157], v[74:77], v[186:189], v[154:157]
	v_mfma_f32_16x16x32_bf16 v[154:157], v[78:81], v[190:193], v[154:157]
	v_mfma_f32_16x16x32_bf16 v[138:141], v[74:77], v[200:203], v[138:141]
	v_mfma_f32_16x16x32_bf16 v[138:141], v[78:81], v[204:207], v[138:141]
	v_mfma_f32_16x16x32_bf16 v[142:145], v[58:61], v[200:203], v[142:145]
	v_mfma_f32_16x16x32_bf16 v[142:145], v[62:65], v[204:207], v[142:145]
	v_mfma_f32_16x16x32_bf16 v[126:129], v[58:61], v[208:211], v[126:129]
	v_mfma_f32_16x16x32_bf16 v[126:129], v[62:65], v[212:215], v[126:129]
	v_mfma_f32_16x16x32_bf16 v[122:125], v[74:77], v[208:211], v[122:125]
	v_mfma_f32_16x16x32_bf16 v[122:125], v[78:81], v[212:215], v[122:125]
	v_mfma_f32_16x16x32_bf16 v[106:109], v[74:77], v[216:219], v[106:109]
	v_mfma_f32_16x16x32_bf16 v[106:109], v[78:81], v[220:223], v[106:109]
	v_mfma_f32_16x16x32_bf16 v[110:113], v[58:61], v[216:219], v[110:113]
	v_mfma_f32_16x16x32_bf16 v[110:113], v[62:65], v[220:223], v[110:113]
	v_mfma_f32_16x16x32_bf16 v[150:153], v[82:85], v[186:189], v[150:153]
	v_mfma_f32_16x16x32_bf16 v[150:153], v[86:89], v[190:193], v[150:153]
	v_mfma_f32_16x16x32_bf16 v[146:149], v[90:93], v[186:189], v[146:149]
	v_mfma_f32_16x16x32_bf16 v[146:149], v[94:97], v[190:193], v[146:149]
	v_mfma_f32_16x16x32_bf16 v[130:133], v[90:93], v[200:203], v[130:133]
	v_mfma_f32_16x16x32_bf16 v[130:133], v[94:97], v[204:207], v[130:133]
	v_mfma_f32_16x16x32_bf16 v[134:137], v[82:85], v[200:203], v[134:137]
	v_mfma_f32_16x16x32_bf16 v[134:137], v[86:89], v[204:207], v[134:137]
	v_mfma_f32_16x16x32_bf16 v[118:121], v[82:85], v[208:211], v[118:121]
	v_mfma_f32_16x16x32_bf16 v[118:121], v[86:89], v[212:215], v[118:121]
	v_mfma_f32_16x16x32_bf16 v[114:117], v[90:93], v[208:211], v[114:117]
	v_mfma_f32_16x16x32_bf16 v[114:117], v[94:97], v[212:215], v[114:117]
	v_mfma_f32_16x16x32_bf16 v[98:101], v[90:93], v[216:219], v[98:101]
	v_mfma_f32_16x16x32_bf16 v[98:101], v[94:97], v[220:223], v[98:101]
	v_mfma_f32_16x16x32_bf16 v[102:105], v[82:85], v[216:219], v[102:105]
	v_mfma_f32_16x16x32_bf16 v[102:105], v[86:89], v[220:223], v[102:105]
	s_barrier
; #define PG8_STAGE(bufoff, gbase, voff) do { _Pragma("unroll") for (int _i = 0; _i < 2; ++_i) \
;         __builtin_amdgcn_global_load_lds((const unsigned*)((const char*)(gbase) + (voff)[_i]), (PG8_LAS unsigned*)(lds + (bufoff) + ldsw + _i * 8192), 16, 0, 0); } while (0)
; #define PG8_LDA(dst, b, h) do { _Pragma("unroll") for (int m = 0; m < 4; ++m) _Pragma("unroll") for (int k = 0; k < 2; ++k) dst[m][k] = *(const PG8_LAS bf16x8*)(lds + PG8_SA(b, h) + aoff + m * 2048 + k * 1024); } while (0)
; #define PG8_MMA(ai, bj, At, Bt) do { __builtin_amdgcn_s_setprio(1); _Pragma("unroll") for (int m = 0; m < 4; ++m) _Pragma("unroll") for (int n = 0; n < 2; ++n) _Pragma("unroll") for (int k = 0; k < 2; ++k) \
;         acc[ai][bj][m][n] = __builtin_amdgcn_mfma_f32_16x16x32_bf16(Bt[n][k], At[m][k], acc[ai][bj][m][n], 0, 0, 0); __builtin_amdgcn_s_setprio(0); } while (0)
; #define PG8_WAIT_V(n) asm volatile("s_waitcnt vmcnt(" #n ")" ::: "memory")
; #define PG8_WAIT_L(n) asm volatile("s_waitcnt lgkmcnt(" #n ")" ::: "memory")
; #define PG8_BAR __builtin_amdgcn_s_barrier()
; #define PG8_SCHED __builtin_amdgcn_sched_barrier(0)
; template <class Epi, class Sched, bool ALIGN_EPI = false, bool SP2 = false>
; __device__ __forceinline__ void gemm_phase(PG8_LAS unsigned char* lds, const Gemm g, const Sched& S, const Epi& E) {
;     ...
;         for (int t = 0; t < nt; t += 2) {
;     ...
;             PG8_LDA(At, 1, 1); PG8_STAGE(PG8_SB(1, 0), b3, voffB); PG8_STAGE(PG8_SB(1, 1), b3 + hstep, voffB); PG8_STAGE(PG8_SA(1, 0), a3, voffA);
;             PG8_WAIT_V(8); PG8_WAIT_L(0); PG8_BAR; PG8_MMA(1, 0, At, B0); PG8_MMA(1, 1, At, B1); PG8_BAR; PG8_SCHED;
	s_setprio 0
	s_add_i32 s10, s24, s94
	v_lshl_add_u64 v[194:195], v[194:195], 0, s[28:29]
	s_mov_b32 m0, s10
	ds_read_b128 v[186:189], v199 offset:49152
	ds_read_b128 v[190:193], v199 offset:50176
	ds_read_b128 v[200:203], v199 offset:51200
	ds_read_b128 v[204:207], v199 offset:52224
	ds_read_b128 v[208:211], v199 offset:53248
	ds_read_b128 v[212:215], v199 offset:54272
	ds_read_b128 v[216:219], v199 offset:55296
	ds_read_b128 v[220:223], v199 offset:56320
	global_load_lds_dwordx4 v[194:195], off
	s_add_i32 m0, s10, 0x2000
	s_add_u32 s10, s44, 0xb0080
	v_lshl_add_u64 v[194:195], v[224:225], 0, s[28:29]
	s_addc_u32 s11, s45, 0
	s_add_i32 s24, s25, s94
	global_load_lds_dwordx4 v[194:195], off
	v_lshl_add_u64 v[194:195], s[10:11], 0, v[0:1]
	s_mov_b32 m0, s24
	s_nop 0
	global_load_lds_dwordx4 v[194:195], off
	v_lshl_add_u64 v[194:195], s[10:11], 0, v[180:181]
	s_add_i32 m0, s24, 0x2000
	s_nop 0
	global_load_lds_dwordx4 v[194:195], off
	v_lshl_add_u64 v[194:195], v[226:227], 0, s[28:29]
	s_mov_b32 m0, s57
	s_nop 0
	global_load_lds_dwordx4 v[194:195], off
	v_lshl_add_u64 v[194:195], v[238:239], 0, s[28:29]
	s_mov_b32 m0, s78
	s_nop 0
	global_load_lds_dwordx4 v[194:195], off
	s_waitcnt vmcnt(8)
	s_waitcnt lgkmcnt(0)
	s_setprio 1
	s_barrier
	v_mfma_f32_16x16x32_bf16 v[70:73], v[58:61], v[186:189], v[70:73]
	v_mfma_f32_16x16x32_bf16 v[70:73], v[62:65], v[190:193], v[70:73]
	v_mfma_f32_16x16x32_bf16 v[66:69], v[74:77], v[186:189], v[66:69]
	v_mfma_f32_16x16x32_bf16 v[66:69], v[78:81], v[190:193], v[66:69]
	v_mfma_f32_16x16x32_bf16 v[42:45], v[74:77], v[200:203], v[42:45]
	v_mfma_f32_16x16x32_bf16 v[42:45], v[78:81], v[204:207], v[42:45]
	v_mfma_f32_16x16x32_bf16 v[46:49], v[58:61], v[200:203], v[46:49]
	v_mfma_f32_16x16x32_bf16 v[46:49], v[62:65], v[204:207], v[46:49]
	v_mfma_f32_16x16x32_bf16 v[30:33], v[58:61], v[208:211], v[30:33]
	v_mfma_f32_16x16x32_bf16 v[30:33], v[62:65], v[212:215], v[30:33]
	v_mfma_f32_16x16x32_bf16 v[26:29], v[74:77], v[208:211], v[26:29]
	v_mfma_f32_16x16x32_bf16 v[26:29], v[78:81], v[212:215], v[26:29]
	v_mfma_f32_16x16x32_bf16 v[10:13], v[74:77], v[216:219], v[10:13]
	v_mfma_f32_16x16x32_bf16 v[10:13], v[78:81], v[220:223], v[10:13]
	v_mfma_f32_16x16x32_bf16 v[14:17], v[58:61], v[216:219], v[14:17]
	v_mfma_f32_16x16x32_bf16 v[14:17], v[62:65], v[220:223], v[14:17]
	v_mfma_f32_16x16x32_bf16 v[54:57], v[82:85], v[186:189], v[54:57]
	v_mfma_f32_16x16x32_bf16 v[54:57], v[86:89], v[190:193], v[54:57]
	v_mfma_f32_16x16x32_bf16 v[50:53], v[90:93], v[186:189], v[50:53]
	v_mfma_f32_16x16x32_bf16 v[50:53], v[94:97], v[190:193], v[50:53]
	v_mfma_f32_16x16x32_bf16 v[34:37], v[90:93], v[200:203], v[34:37]
	v_mfma_f32_16x16x32_bf16 v[34:37], v[94:97], v[204:207], v[34:37]
	v_mfma_f32_16x16x32_bf16 v[38:41], v[82:85], v[200:203], v[38:41]
	v_mfma_f32_16x16x32_bf16 v[38:41], v[86:89], v[204:207], v[38:41]
	v_mfma_f32_16x16x32_bf16 v[22:25], v[82:85], v[208:211], v[22:25]
	v_mfma_f32_16x16x32_bf16 v[22:25], v[86:89], v[212:215], v[22:25]
	v_mfma_f32_16x16x32_bf16 v[18:21], v[90:93], v[208:211], v[18:21]
	v_mfma_f32_16x16x32_bf16 v[18:21], v[94:97], v[212:215], v[18:21]
	v_mfma_f32_16x16x32_bf16 v[2:5], v[90:93], v[216:219], v[2:5]
	v_mfma_f32_16x16x32_bf16 v[2:5], v[94:97], v[220:223], v[2:5]
	v_mfma_f32_16x16x32_bf16 v[6:9], v[82:85], v[216:219], v[6:9]
	v_mfma_f32_16x16x32_bf16 v[6:9], v[86:89], v[220:223], v[6:9]
	s_barrier
	s_setprio 0
	s_add_i32 s73, s73, 2
	s_add_u32 s35, s35, 0x100
	s_addc_u32 s72, s72, 0
	s_cmp_gt_u32 s73, 41
	s_mov_b64 s[24:25], s[42:43]
	s_cbranch_scc0 .LBB0_1208
	s_and_b64 vcc, exec, s[20:21]
	s_cbranch_vccz .LBB0_1211
	s_barrier

; #define PG8_STAGE(bufoff, gbase, voff) do { _Pragma("unroll") for (int _i = 0; _i < 2; ++_i) \
;         __builtin_amdgcn_global_load_lds((const unsigned*)((const char*)(gbase) + (voff)[_i]), (PG8_LAS unsigned*)(lds + (bufoff) + ldsw + _i * 8192), 16, 0, 0); } while (0)
; #define PG8_LDA(dst, b, h) do { _Pragma("unroll") for (int m = 0; m < 4; ++m) _Pragma("unroll") for (int k = 0; k < 2; ++k) dst[m][k] = *(const PG8_LAS bf16x8*)(lds + PG8_SA(b, h) + aoff + m * 2048 + k * 1024); } while (0)
; #define PG8_LDB(dst, b, h) do { _Pragma("unroll") for (int n = 0; n < 2; ++n) _Pragma("unroll") for (int k = 0; k < 2; ++k) dst[n][k] = *(const PG8_LAS bf16x8*)(lds + PG8_SB(b, h) + boff + n * 2048 + k * 1024); } while (0)
; #define PG8_MMA(ai, bj, At, Bt) do { __builtin_amdgcn_s_setprio(1); _Pragma("unroll") for (int m = 0; m < 4; ++m) _Pragma("unroll") for (int n = 0; n < 2; ++n) _Pragma("unroll") for (int k = 0; k < 2; ++k) \
;         acc[ai][bj][m][n] = __builtin_amdgcn_mfma_f32_16x16x32_bf16(Bt[n][k], At[m][k], acc[ai][bj][m][n], 0, 0, 0); __builtin_amdgcn_s_setprio(0); } while (0)
; #define PG8_WAIT_V(n) asm volatile("s_waitcnt vmcnt(" #n ")" ::: "memory")
; #define PG8_WAIT_L(n) asm volatile("s_waitcnt lgkmcnt(" #n ")" ::: "memory")
; #define PG8_BAR __builtin_amdgcn_s_barrier()
; #define PG8_SCHED __builtin_amdgcn_sched_barrier(0)
; template <class Epi, class Sched, bool ALIGN_EPI = false, bool SP2 = false>
; __device__ __forceinline__ void gemm_phase(PG8_LAS unsigned char* lds, const Gemm g, const Sched& S, const Epi& E) {
;     ...
;             PG8_LDB(B0, 0, 0); PG8_LDB(B1, 0, 1); PG8_SCHED; PG8_LDA(At, 0, 0); PG8_STAGE(PG8_SA(1, 1), a1 + hstep, voffA);
;             PG8_WAIT_V(8); PG8_WAIT_L(0); PG8_BAR; PG8_MMA(0, 0, At, B0); PG8_MMA(0, 1, At, B1); PG8_BAR; PG8_SCHED;
;             PG8_LDA(At, 0, 1); PG8_STAGE(PG8_SB(0, 0), b2, voffB); PG8_STAGE(PG8_SB(0, 1), b2 + hstep, voffB); PG8_STAGE(PG8_SA(0, 0), a2, voffA);
;             PG8_WAIT_V(8); PG8_WAIT_L(0); PG8_BAR; PG8_MMA(1, 0, At, B0); PG8_MMA(1, 1, At, B1); PG8_BAR; PG8_SCHED;
.LBB0_1275:
	s_add_u32 s10, s40, 0xfffc0080
	s_addc_u32 s11, s41, -1
	s_add_i32 s64, 16, 0x10000
	s_cmp_eq_u32 s63, 12
	s_cselect_b32 s51, s34, s11
	s_cselect_b32 s50, s35, s10
	s_cselect_b32 s49, s27, s62
	s_cselect_b32 s48, s43, s59
	s_add_i32 s65, 16, 0x14000
	v_add_u32_e32 v142, s64, v179
	v_add_u32_e32 v176, s65, v179
	ds_read_b128 v[130:133], v142
	ds_read_b128 v[134:137], v142 offset:1024
	ds_read_b128 v[138:141], v142 offset:2048
	ds_read_b128 v[142:145], v142 offset:3072
	ds_read_b128 v[158:161], v176
	ds_read_b128 v[182:185], v176 offset:1024
	ds_read_b128 v[186:189], v176 offset:2048
	ds_read_b128 v[190:193], v176 offset:3072
	v_lshl_add_u64 v[176:177], s[40:41], 0, v[156:157]
	s_add_i32 m0, s4, 0xc000
	ds_read_b128 v[194:197], v181
	ds_read_b128 v[198:201], v181 offset:1024
	ds_read_b128 v[202:205], v181 offset:2048
	ds_read_b128 v[206:209], v181 offset:3072
	ds_read_b128 v[210:213], v181 offset:4096
	ds_read_b128 v[214:217], v181 offset:5120
	ds_read_b128 v[218:221], v181 offset:6144
	ds_read_b128 v[222:225], v181 offset:7168
	global_load_lds_dwordx4 v[176:177], off
	v_lshl_add_u64 v[176:177], s[40:41], 0, v[154:155]
	s_add_i32 m0, s4, 0xe000
	s_nop 0
	global_load_lds_dwordx4 v[176:177], off
	s_waitcnt vmcnt(8)
	s_waitcnt lgkmcnt(0)
	s_setprio 1
	s_barrier
	v_mfma_f32_16x16x32_bf16 v[126:129], v[130:133], v[194:197], v[126:129]
	v_mfma_f32_16x16x32_bf16 v[126:129], v[134:137], v[198:201], v[126:129]
	v_mfma_f32_16x16x32_bf16 v[122:125], v[138:141], v[194:197], v[122:125]
	v_mfma_f32_16x16x32_bf16 v[122:125], v[142:145], v[198:201], v[122:125]
	v_mfma_f32_16x16x32_bf16 v[106:109], v[138:141], v[202:205], v[106:109]
	v_mfma_f32_16x16x32_bf16 v[106:109], v[142:145], v[206:209], v[106:109]
	v_mfma_f32_16x16x32_bf16 v[110:113], v[130:133], v[202:205], v[110:113]
	v_mfma_f32_16x16x32_bf16 v[110:113], v[134:137], v[206:209], v[110:113]
	v_mfma_f32_16x16x32_bf16 v[94:97], v[130:133], v[210:213], v[94:97]
	v_mfma_f32_16x16x32_bf16 v[94:97], v[134:137], v[214:217], v[94:97]
	v_mfma_f32_16x16x32_bf16 v[90:93], v[138:141], v[210:213], v[90:93]
	v_mfma_f32_16x16x32_bf16 v[90:93], v[142:145], v[214:217], v[90:93]
	v_mfma_f32_16x16x32_bf16 v[74:77], v[138:141], v[218:221], v[74:77]
	v_mfma_f32_16x16x32_bf16 v[74:77], v[142:145], v[222:225], v[74:77]
	v_mfma_f32_16x16x32_bf16 v[78:81], v[130:133], v[218:221], v[78:81]
	v_mfma_f32_16x16x32_bf16 v[78:81], v[134:137], v[222:225], v[78:81]
	v_mfma_f32_16x16x32_bf16 v[118:121], v[158:161], v[194:197], v[118:121]
	v_mfma_f32_16x16x32_bf16 v[118:121], v[182:185], v[198:201], v[118:121]
	v_mfma_f32_16x16x32_bf16 v[114:117], v[186:189], v[194:197], v[114:117]
	v_mfma_f32_16x16x32_bf16 v[114:117], v[190:193], v[198:201], v[114:117]
	v_mfma_f32_16x16x32_bf16 v[98:101], v[186:189], v[202:205], v[98:101]
	v_mfma_f32_16x16x32_bf16 v[98:101], v[190:193], v[206:209], v[98:101]
	v_mfma_f32_16x16x32_bf16 v[102:105], v[158:161], v[202:205], v[102:105]
	v_mfma_f32_16x16x32_bf16 v[102:105], v[182:185], v[206:209], v[102:105]
	v_mfma_f32_16x16x32_bf16 v[86:89], v[158:161], v[210:213], v[86:89]
	v_mfma_f32_16x16x32_bf16 v[86:89], v[182:185], v[214:217], v[86:89]
	v_mfma_f32_16x16x32_bf16 v[82:85], v[186:189], v[210:213], v[82:85]
	v_mfma_f32_16x16x32_bf16 v[82:85], v[190:193], v[214:217], v[82:85]
	v_mfma_f32_16x16x32_bf16 v[66:69], v[186:189], v[218:221], v[66:69]
	v_mfma_f32_16x16x32_bf16 v[66:69], v[190:193], v[222:225], v[66:69]
	v_mfma_f32_16x16x32_bf16 v[70:73], v[158:161], v[218:221], v[70:73]
	v_mfma_f32_16x16x32_bf16 v[70:73], v[182:185], v[222:225], v[70:73]
	s_barrier
	s_setprio 0
	s_add_i32 s10, s64, s3
	v_lshl_add_u64 v[176:177], s[48:49], 0, v[0:1]
	s_mov_b32 m0, s10
	ds_read_b128 v[194:197], v181 offset:16384
	ds_read_b128 v[198:201], v181 offset:17408
	ds_read_b128 v[202:205], v181 offset:18432
	ds_read_b128 v[206:209], v181 offset:19456
	ds_read_b128 v[210:213], v181 offset:20480
	ds_read_b128 v[214:217], v181 offset:21504
	ds_read_b128 v[218:221], v181 offset:22528
	ds_read_b128 v[222:225], v181 offset:23552
	global_load_lds_dwordx4 v[176:177], off
	s_add_i32 m0, s10, 0x2000
	s_add_u32 s10, s48, 0x40000
	v_lshl_add_u64 v[226:227], s[48:49], 0, v[146:147]
	s_addc_u32 s11, s49, 0
	s_add_i32 s64, s65, s3
	global_load_lds_dwordx4 v[226:227], off
	v_lshl_add_u64 v[238:239], s[10:11], 0, v[0:1]
	s_mov_b32 m0, s64
	v_lshl_add_u64 v[240:241], s[50:51], 0, v[148:149]
	global_load_lds_dwordx4 v[238:239], off
	v_lshl_add_u64 v[238:239], s[10:11], 0, v[146:147]
	s_add_i32 m0, s64, 0x2000
	s_nop 0
	global_load_lds_dwordx4 v[238:239], off
	v_lshl_add_u64 v[238:239], s[50:51], 0, v[150:151]
	s_mov_b32 m0, s4
	s_nop 0
	global_load_lds_dwordx4 v[238:239], off
	s_mov_b32 m0, s5
	s_nop 0
	global_load_lds_dwordx4 v[240:241], off
	s_waitcnt vmcnt(8)
	s_waitcnt lgkmcnt(0)
	s_setprio 1
	s_barrier
; #define PG8_STAGE(bufoff, gbase, voff) do { _Pragma("unroll") for (int _i = 0; _i < 2; ++_i) \
;         __builtin_amdgcn_global_load_lds((const unsigned*)((const char*)(gbase) + (voff)[_i]), (PG8_LAS unsigned*)(lds + (bufoff) + ldsw + _i * 8192), 16, 0, 0); } while (0)
; #define PG8_LDA(dst, b, h) do { _Pragma("unroll") for (int m = 0; m < 4; ++m) _Pragma("unroll") for (int k = 0; k < 2; ++k) dst[m][k] = *(const PG8_LAS bf16x8*)(lds + PG8_SA(b, h) + aoff + m * 2048 + k * 1024); } while (0)
; #define PG8_LDB(dst, b, h) do { _Pragma("unroll") for (int n = 0; n < 2; ++n) _Pragma("unroll") for (int k = 0; k < 2; ++k) dst[n][k] = *(const PG8_LAS bf16x8*)(lds + PG8_SB(b, h) + boff + n * 2048 + k * 1024); } while (0)
; #define PG8_MMA(ai, bj, At, Bt) do { __builtin_amdgcn_s_setprio(1); _Pragma("unroll") for (int m = 0; m < 4; ++m) _Pragma("unroll") for (int n = 0; n < 2; ++n) _Pragma("unroll") for (int k = 0; k < 2; ++k) \
;         acc[ai][bj][m][n] = __builtin_amdgcn_mfma_f32_16x16x32_bf16(Bt[n][k], At[m][k], acc[ai][bj][m][n], 0, 0, 0); __builtin_amdgcn_s_setprio(0); } while (0)
; #define PG8_WAIT_V(n) asm volatile("s_waitcnt vmcnt(" #n ")" ::: "memory")
; #define PG8_WAIT_L(n) asm volatile("s_waitcnt lgkmcnt(" #n ")" ::: "memory")
; #define PG8_BAR __builtin_amdgcn_s_barrier()
; #define PG8_SCHED __builtin_amdgcn_sched_barrier(0)
; template <class Epi, class Sched, bool ALIGN_EPI = false, bool SP2 = false>
; __device__ __forceinline__ void gemm_phase(PG8_LAS unsigned char* lds, const Gemm g, const Sched& S, const Epi& E) {
;     ...
;             PG8_WAIT_V(8); PG8_WAIT_L(0); PG8_BAR; PG8_MMA(1, 0, At, B0); PG8_MMA(1, 1, At, B1); PG8_BAR; PG8_SCHED;
;             PG8_LDB(B0, 1, 0); PG8_LDB(B1, 1, 1); PG8_SCHED; PG8_LDA(At, 1, 0); PG8_STAGE(PG8_SA(0, 1), a2 + hstep, voffA);
;             PG8_WAIT_V(8); PG8_WAIT_L(0); PG8_BAR; PG8_MMA(0, 0, At, B0); PG8_MMA(0, 1, At, B1); PG8_BAR; PG8_SCHED;
	v_mfma_f32_16x16x32_bf16 v[62:65], v[130:133], v[194:197], v[62:65]
	v_mfma_f32_16x16x32_bf16 v[62:65], v[134:137], v[198:201], v[62:65]
	v_mfma_f32_16x16x32_bf16 v[58:61], v[138:141], v[194:197], v[58:61]
	v_mfma_f32_16x16x32_bf16 v[58:61], v[142:145], v[198:201], v[58:61]
	v_mfma_f32_16x16x32_bf16 v[42:45], v[138:141], v[202:205], v[42:45]
	v_mfma_f32_16x16x32_bf16 v[42:45], v[142:145], v[206:209], v[42:45]
	v_mfma_f32_16x16x32_bf16 v[46:49], v[130:133], v[202:205], v[46:49]
	v_mfma_f32_16x16x32_bf16 v[46:49], v[134:137], v[206:209], v[46:49]
	v_mfma_f32_16x16x32_bf16 v[30:33], v[130:133], v[210:213], v[30:33]
	v_mfma_f32_16x16x32_bf16 v[30:33], v[134:137], v[214:217], v[30:33]
	v_mfma_f32_16x16x32_bf16 v[26:29], v[138:141], v[210:213], v[26:29]
	v_mfma_f32_16x16x32_bf16 v[26:29], v[142:145], v[214:217], v[26:29]
	v_mfma_f32_16x16x32_bf16 v[10:13], v[138:141], v[218:221], v[10:13]
	v_mfma_f32_16x16x32_bf16 v[10:13], v[142:145], v[222:225], v[10:13]
	v_mfma_f32_16x16x32_bf16 v[14:17], v[130:133], v[218:221], v[14:17]
	v_mfma_f32_16x16x32_bf16 v[14:17], v[134:137], v[222:225], v[14:17]
	v_mfma_f32_16x16x32_bf16 v[54:57], v[158:161], v[194:197], v[54:57]
	v_mfma_f32_16x16x32_bf16 v[54:57], v[182:185], v[198:201], v[54:57]
	v_mfma_f32_16x16x32_bf16 v[50:53], v[186:189], v[194:197], v[50:53]
	v_mfma_f32_16x16x32_bf16 v[50:53], v[190:193], v[198:201], v[50:53]
	v_mfma_f32_16x16x32_bf16 v[34:37], v[186:189], v[202:205], v[34:37]
	v_mfma_f32_16x16x32_bf16 v[34:37], v[190:193], v[206:209], v[34:37]
	v_mfma_f32_16x16x32_bf16 v[38:41], v[158:161], v[202:205], v[38:41]
	v_mfma_f32_16x16x32_bf16 v[38:41], v[182:185], v[206:209], v[38:41]
	v_mfma_f32_16x16x32_bf16 v[22:25], v[158:161], v[210:213], v[22:25]
	v_mfma_f32_16x16x32_bf16 v[22:25], v[182:185], v[214:217], v[22:25]
	v_mfma_f32_16x16x32_bf16 v[18:21], v[186:189], v[210:213], v[18:21]
	v_mfma_f32_16x16x32_bf16 v[18:21], v[190:193], v[214:217], v[18:21]
	v_mfma_f32_16x16x32_bf16 v[2:5], v[186:189], v[218:221], v[2:5]
	v_mfma_f32_16x16x32_bf16 v[2:5], v[190:193], v[222:225], v[2:5]
	v_mfma_f32_16x16x32_bf16 v[6:9], v[158:161], v[218:221], v[6:9]
	v_mfma_f32_16x16x32_bf16 v[6:9], v[182:185], v[222:225], v[6:9]
	s_barrier
	s_setprio 0
	s_add_i32 s64, 16, 0x18000
	s_add_i32 s65, 16, 0x1c000
	v_add_u32_e32 v142, s64, v179
	v_add_u32_e32 v190, s65, v179
	ds_read_b128 v[130:133], v142
	ds_read_b128 v[134:137], v142 offset:1024
	ds_read_b128 v[138:141], v142 offset:2048
	ds_read_b128 v[142:145], v142 offset:3072
	ds_read_b128 v[158:161], v190
	ds_read_b128 v[182:185], v190 offset:1024
	ds_read_b128 v[186:189], v190 offset:2048
	ds_read_b128 v[190:193], v190 offset:3072
	s_add_u32 s10, s50, 0x40000
	s_addc_u32 s11, s51, 0
	s_mov_b32 m0, s6
	v_lshl_add_u64 v[242:243], s[10:11], 0, v[150:151]
	ds_read_b128 v[194:197], v181 offset:32768
	ds_read_b128 v[198:201], v181 offset:33792
	ds_read_b128 v[202:205], v181 offset:34816
	ds_read_b128 v[206:209], v181 offset:35840
	ds_read_b128 v[210:213], v181 offset:36864
	ds_read_b128 v[214:217], v181 offset:37888
	ds_read_b128 v[218:221], v181 offset:38912
	ds_read_b128 v[222:225], v181 offset:39936
	global_load_lds_dwordx4 v[242:243], off
	v_lshl_add_u64 v[242:243], s[10:11], 0, v[148:149]
	s_mov_b32 m0, s7
	s_nop 0
	global_load_lds_dwordx4 v[242:243], off
	s_waitcnt vmcnt(8)
	s_waitcnt lgkmcnt(0)
	s_setprio 1
	s_barrier
	v_mfma_f32_16x16x32_bf16 v[126:129], v[130:133], v[194:197], v[126:129]
	v_mfma_f32_16x16x32_bf16 v[126:129], v[134:137], v[198:201], v[126:129]
	v_mfma_f32_16x16x32_bf16 v[122:125], v[138:141], v[194:197], v[122:125]
	v_mfma_f32_16x16x32_bf16 v[122:125], v[142:145], v[198:201], v[122:125]
	v_mfma_f32_16x16x32_bf16 v[106:109], v[138:141], v[202:205], v[106:109]
	v_mfma_f32_16x16x32_bf16 v[106:109], v[142:145], v[206:209], v[106:109]
	v_mfma_f32_16x16x32_bf16 v[110:113], v[130:133], v[202:205], v[110:113]
	v_mfma_f32_16x16x32_bf16 v[110:113], v[134:137], v[206:209], v[110:113]
	v_mfma_f32_16x16x32_bf16 v[94:97], v[130:133], v[210:213], v[94:97]
	v_mfma_f32_16x16x32_bf16 v[94:97], v[134:137], v[214:217], v[94:97]
	v_mfma_f32_16x16x32_bf16 v[90:93], v[138:141], v[210:213], v[90:93]
	v_mfma_f32_16x16x32_bf16 v[90:93], v[142:145], v[214:217], v[90:93]
	v_mfma_f32_16x16x32_bf16 v[74:77], v[138:141], v[218:221], v[74:77]
	v_mfma_f32_16x16x32_bf16 v[74:77], v[142:145], v[222:225], v[74:77]
	v_mfma_f32_16x16x32_bf16 v[78:81], v[130:133], v[218:221], v[78:81]
	v_mfma_f32_16x16x32_bf16 v[78:81], v[134:137], v[222:225], v[78:81]
	v_mfma_f32_16x16x32_bf16 v[118:121], v[158:161], v[194:197], v[118:121]
	v_mfma_f32_16x16x32_bf16 v[118:121], v[182:185], v[198:201], v[118:121]
	v_mfma_f32_16x16x32_bf16 v[114:117], v[186:189], v[194:197], v[114:117]
	v_mfma_f32_16x16x32_bf16 v[114:117], v[190:193], v[198:201], v[114:117]
	v_mfma_f32_16x16x32_bf16 v[98:101], v[186:189], v[202:205], v[98:101]
	v_mfma_f32_16x16x32_bf16 v[98:101], v[190:193], v[206:209], v[98:101]
	v_mfma_f32_16x16x32_bf16 v[102:105], v[158:161], v[202:205], v[102:105]
	v_mfma_f32_16x16x32_bf16 v[102:105], v[182:185], v[206:209], v[102:105]
	v_mfma_f32_16x16x32_bf16 v[86:89], v[158:161], v[210:213], v[86:89]
	v_mfma_f32_16x16x32_bf16 v[86:89], v[182:185], v[214:217], v[86:89]
	v_mfma_f32_16x16x32_bf16 v[82:85], v[186:189], v[210:213], v[82:85]
	v_mfma_f32_16x16x32_bf16 v[82:85], v[190:193], v[214:217], v[82:85]
	v_mfma_f32_16x16x32_bf16 v[66:69], v[186:189], v[218:221], v[66:69]
	v_mfma_f32_16x16x32_bf16 v[66:69], v[190:193], v[222:225], v[66:69]
	v_mfma_f32_16x16x32_bf16 v[70:73], v[158:161], v[218:221], v[70:73]
	v_mfma_f32_16x16x32_bf16 v[70:73], v[182:185], v[222:225], v[70:73]
	s_barrier
; #define PG8_STAGE(bufoff, gbase, voff) do { _Pragma("unroll") for (int _i = 0; _i < 2; ++_i) \
;         __builtin_amdgcn_global_load_lds((const unsigned*)((const char*)(gbase) + (voff)[_i]), (PG8_LAS unsigned*)(lds + (bufoff) + ldsw + _i * 8192), 16, 0, 0); } while (0)
; #define PG8_LDA(dst, b, h) do { _Pragma("unroll") for (int m = 0; m < 4; ++m) _Pragma("unroll") for (int k = 0; k < 2; ++k) dst[m][k] = *(const PG8_LAS bf16x8*)(lds + PG8_SA(b, h) + aoff + m * 2048 + k * 1024); } while (0)
; #define PG8_MMA(ai, bj, At, Bt) do { __builtin_amdgcn_s_setprio(1); _Pragma("unroll") for (int m = 0; m < 4; ++m) _Pragma("unroll") for (int n = 0; n < 2; ++n) _Pragma("unroll") for (int k = 0; k < 2; ++k) \
;         acc[ai][bj][m][n] = __builtin_amdgcn_mfma_f32_16x16x32_bf16(Bt[n][k], At[m][k], acc[ai][bj][m][n], 0, 0, 0); __builtin_amdgcn_s_setprio(0); } while (0)
; #define PG8_WAIT_V(n) asm volatile("s_waitcnt vmcnt(" #n ")" ::: "memory")
; #define PG8_WAIT_L(n) asm volatile("s_waitcnt lgkmcnt(" #n ")" ::: "memory")
; #define PG8_BAR __builtin_amdgcn_s_barrier()
; #define PG8_SCHED __builtin_amdgcn_sched_barrier(0)
; template <class Epi, class Sched, bool ALIGN_EPI = false, bool SP2 = false>
; __device__ __forceinline__ void gemm_phase(PG8_LAS unsigned char* lds, const Gemm g, const Sched& S, const Epi& E) {
;     ...
;         for (int t = 0; t < nt; t += 2) {
;             const bool last = (t == nt - 2);
;             const char* a1 = cA + (size_t)(t + 1) * kstep;
;             const char* a2 = last ? nA : cA + (size_t)(t + 2) * kstep; const char* b2 = last ? nB : cB + (size_t)(t + 2) * kstep;
;             const char* a3 = a2 + kstep; const char* b3 = b2 + kstep;
;     ...
;             PG8_LDA(At, 1, 1); PG8_STAGE(PG8_SB(1, 0), b3, voffB); PG8_STAGE(PG8_SB(1, 1), b3 + hstep, voffB); PG8_STAGE(PG8_SA(1, 0), a3, voffA);
;             PG8_WAIT_V(8); PG8_WAIT_L(0); PG8_BAR; PG8_MMA(1, 0, At, B0); PG8_MMA(1, 1, At, B1); PG8_BAR; PG8_SCHED;
	s_setprio 0
	s_add_i32 s10, s64, s3
	v_lshl_add_u64 v[176:177], v[176:177], 0, s[28:29]
	s_mov_b32 m0, s10
	ds_read_b128 v[194:197], v181 offset:49152
	ds_read_b128 v[198:201], v181 offset:50176
	ds_read_b128 v[202:205], v181 offset:51200
	ds_read_b128 v[206:209], v181 offset:52224
	ds_read_b128 v[210:213], v181 offset:53248
	ds_read_b128 v[214:217], v181 offset:54272
	ds_read_b128 v[218:221], v181 offset:55296
	ds_read_b128 v[222:225], v181 offset:56320
	global_load_lds_dwordx4 v[176:177], off
	s_add_i32 m0, s10, 0x2000
	s_add_u32 s10, s48, 0x40080
	v_lshl_add_u64 v[176:177], v[226:227], 0, s[28:29]
	s_addc_u32 s11, s49, 0
	s_add_i32 s48, s65, s3
	global_load_lds_dwordx4 v[176:177], off
	v_lshl_add_u64 v[176:177], s[10:11], 0, v[0:1]
	s_mov_b32 m0, s48
	s_nop 0
	global_load_lds_dwordx4 v[176:177], off
	v_lshl_add_u64 v[176:177], s[10:11], 0, v[146:147]
	s_add_i32 m0, s48, 0x2000
	s_nop 0
	global_load_lds_dwordx4 v[176:177], off
	v_lshl_add_u64 v[176:177], v[238:239], 0, s[28:29]
	s_mov_b32 m0, s54
	s_nop 0
	global_load_lds_dwordx4 v[176:177], off
	v_lshl_add_u64 v[176:177], v[240:241], 0, s[28:29]
	s_mov_b32 m0, s55
	s_nop 0
	global_load_lds_dwordx4 v[176:177], off
	s_waitcnt vmcnt(8)
	s_waitcnt lgkmcnt(0)
	s_setprio 1
	s_barrier
	v_mfma_f32_16x16x32_bf16 v[62:65], v[130:133], v[194:197], v[62:65]
	v_mfma_f32_16x16x32_bf16 v[62:65], v[134:137], v[198:201], v[62:65]
	v_mfma_f32_16x16x32_bf16 v[58:61], v[138:141], v[194:197], v[58:61]
	v_mfma_f32_16x16x32_bf16 v[58:61], v[142:145], v[198:201], v[58:61]
	v_mfma_f32_16x16x32_bf16 v[42:45], v[138:141], v[202:205], v[42:45]
	v_mfma_f32_16x16x32_bf16 v[42:45], v[142:145], v[206:209], v[42:45]
	v_mfma_f32_16x16x32_bf16 v[46:49], v[130:133], v[202:205], v[46:49]
	v_mfma_f32_16x16x32_bf16 v[46:49], v[134:137], v[206:209], v[46:49]
	v_mfma_f32_16x16x32_bf16 v[30:33], v[130:133], v[210:213], v[30:33]
	v_mfma_f32_16x16x32_bf16 v[30:33], v[134:137], v[214:217], v[30:33]
	v_mfma_f32_16x16x32_bf16 v[26:29], v[138:141], v[210:213], v[26:29]
	v_mfma_f32_16x16x32_bf16 v[26:29], v[142:145], v[214:217], v[26:29]
	v_mfma_f32_16x16x32_bf16 v[10:13], v[138:141], v[218:221], v[10:13]
	v_mfma_f32_16x16x32_bf16 v[10:13], v[142:145], v[222:225], v[10:13]
	v_mfma_f32_16x16x32_bf16 v[14:17], v[130:133], v[218:221], v[14:17]
	v_mfma_f32_16x16x32_bf16 v[14:17], v[134:137], v[222:225], v[14:17]
	v_mfma_f32_16x16x32_bf16 v[54:57], v[158:161], v[194:197], v[54:57]
	v_mfma_f32_16x16x32_bf16 v[54:57], v[182:185], v[198:201], v[54:57]
	v_mfma_f32_16x16x32_bf16 v[50:53], v[186:189], v[194:197], v[50:53]
	v_mfma_f32_16x16x32_bf16 v[50:53], v[190:193], v[198:201], v[50:53]
	v_mfma_f32_16x16x32_bf16 v[34:37], v[186:189], v[202:205], v[34:37]
	v_mfma_f32_16x16x32_bf16 v[34:37], v[190:193], v[206:209], v[34:37]
	v_mfma_f32_16x16x32_bf16 v[38:41], v[158:161], v[202:205], v[38:41]
	v_mfma_f32_16x16x32_bf16 v[38:41], v[182:185], v[206:209], v[38:41]
	v_mfma_f32_16x16x32_bf16 v[22:25], v[158:161], v[210:213], v[22:25]
	v_mfma_f32_16x16x32_bf16 v[22:25], v[182:185], v[214:217], v[22:25]
	v_mfma_f32_16x16x32_bf16 v[18:21], v[186:189], v[210:213], v[18:21]
	v_mfma_f32_16x16x32_bf16 v[18:21], v[190:193], v[214:217], v[18:21]
	v_mfma_f32_16x16x32_bf16 v[2:5], v[186:189], v[218:221], v[2:5]
	v_mfma_f32_16x16x32_bf16 v[2:5], v[190:193], v[222:225], v[2:5]
	v_mfma_f32_16x16x32_bf16 v[6:9], v[158:161], v[218:221], v[6:9]
	v_mfma_f32_16x16x32_bf16 v[6:9], v[182:185], v[222:225], v[6:9]
	s_barrier
	s_setprio 0
	s_add_i32 s63, s63, 2
	s_add_u32 s59, s59, 0x100
	s_addc_u32 s62, s62, 0
	s_add_u32 s40, s40, 0x100
	s_addc_u32 s41, s41, 0
	s_cmp_gt_u32 s63, 13
	s_cbranch_scc0 .LBB0_1275
	s_and_b64 vcc, exec, s[24:25]
	s_cbranch_vccz .LBB0_1278
	s_barrier

; #define PG8_STAGE(bufoff, gbase, voff) do { _Pragma("unroll") for (int _i = 0; _i < 2; ++_i) \
;         __builtin_amdgcn_global_load_lds((const unsigned*)((const char*)(gbase) + (voff)[_i]), (PG8_LAS unsigned*)(lds + (bufoff) + ldsw + _i * 8192), 16, 0, 0); } while (0)
; #define PG8_LDA(dst, b, h) do { _Pragma("unroll") for (int m = 0; m < 4; ++m) _Pragma("unroll") for (int k = 0; k < 2; ++k) dst[m][k] = *(const PG8_LAS bf16x8*)(lds + PG8_SA(b, h) + aoff + m * 2048 + k * 1024); } while (0)
; #define PG8_LDB(dst, b, h) do { _Pragma("unroll") for (int n = 0; n < 2; ++n) _Pragma("unroll") for (int k = 0; k < 2; ++k) dst[n][k] = *(const PG8_LAS bf16x8*)(lds + PG8_SB(b, h) + boff + n * 2048 + k * 1024); } while (0)
; #define PG8_MMA(ai, bj, At, Bt) do { __builtin_amdgcn_s_setprio(1); _Pragma("unroll") for (int m = 0; m < 4; ++m) _Pragma("unroll") for (int n = 0; n < 2; ++n) _Pragma("unroll") for (int k = 0; k < 2; ++k) \
;         acc[ai][bj][m][n] = __builtin_amdgcn_mfma_f32_16x16x32_bf16(Bt[n][k], At[m][k], acc[ai][bj][m][n], 0, 0, 0); __builtin_amdgcn_s_setprio(0); } while (0)
; #define PG8_WAIT_V(n) asm volatile("s_waitcnt vmcnt(" #n ")" ::: "memory")
; #define PG8_WAIT_L(n) asm volatile("s_waitcnt lgkmcnt(" #n ")" ::: "memory")
; #define PG8_BAR __builtin_amdgcn_s_barrier()
; #define PG8_SCHED __builtin_amdgcn_sched_barrier(0)
; template <class Epi, class Sched, bool ALIGN_EPI = false, bool SP2 = false>
; __device__ __forceinline__ void gemm_phase(PG8_LAS unsigned char* lds, const Gemm g, const Sched& S, const Epi& E) {
;     ...
;             PG8_LDB(B0, 0, 0); PG8_LDB(B1, 0, 1); PG8_SCHED; PG8_LDA(At, 0, 0); PG8_STAGE(PG8_SA(1, 1), a1 + hstep, voffA);
;             PG8_WAIT_V(8); PG8_WAIT_L(0); PG8_BAR; PG8_MMA(0, 0, At, B0); PG8_MMA(0, 1, At, B1); PG8_BAR; PG8_SCHED;
;             PG8_LDA(At, 0, 1); PG8_STAGE(PG8_SB(0, 0), b2, voffB); PG8_STAGE(PG8_SB(0, 1), b2 + hstep, voffB); PG8_STAGE(PG8_SA(0, 0), a2, voffA);
;             PG8_WAIT_V(8); PG8_WAIT_L(0); PG8_BAR; PG8_MMA(1, 0, At, B0); PG8_MMA(1, 1, At, B1); PG8_BAR; PG8_SCHED;
.LBB0_1295:
	s_add_u32 s40, s42, 0x100
	s_addc_u32 s41, s43, 0
	s_add_i32 s10, 16, 0x10000
	s_cmp_eq_u32 s68, 40
	s_cselect_b32 s49, s25, s41
	s_cselect_b32 s48, s24, s40
	v_add_u32_e32 v140, s10, v143
	s_cselect_b32 s47, s27, s67
	s_cselect_b32 s46, s26, s66
	s_add_i32 s69, 16, 0x14000
	ds_read_b128 v[146:149], v140
	ds_read_b128 v[150:153], v140 offset:1024
	ds_read_b128 v[154:157], v140 offset:2048
	ds_read_b128 v[158:161], v140 offset:3072
	v_add_u32_e32 v140, s69, v143
	ds_read_b128 v[176:179], v140
	ds_read_b128 v[180:183], v140 offset:1024
	ds_read_b128 v[184:187], v140 offset:2048
	ds_read_b128 v[188:191], v140 offset:3072
	v_lshl_add_u64 v[140:141], s[42:43], 0, v[138:139]
	s_add_i32 m0, s9, 0xc000
	ds_read_b128 v[192:195], v145
	ds_read_b128 v[196:199], v145 offset:1024
	ds_read_b128 v[200:203], v145 offset:2048
	ds_read_b128 v[204:207], v145 offset:3072
	ds_read_b128 v[208:211], v145 offset:4096
	ds_read_b128 v[212:215], v145 offset:5120
	ds_read_b128 v[216:219], v145 offset:6144
	ds_read_b128 v[220:223], v145 offset:7168
	global_load_lds_dwordx4 v[140:141], off
	v_lshl_add_u64 v[140:141], s[42:43], 0, v[136:137]
	s_add_i32 m0, s9, 0xe000
	s_nop 0
	global_load_lds_dwordx4 v[140:141], off
	s_waitcnt vmcnt(8)
	s_waitcnt lgkmcnt(0)
	s_setprio 1
	s_barrier
	v_mfma_f32_16x16x32_bf16 v[126:129], v[146:149], v[192:195], v[126:129]
	v_mfma_f32_16x16x32_bf16 v[126:129], v[150:153], v[196:199], v[126:129]
	v_mfma_f32_16x16x32_bf16 v[122:125], v[154:157], v[192:195], v[122:125]
	v_mfma_f32_16x16x32_bf16 v[122:125], v[158:161], v[196:199], v[122:125]
	v_mfma_f32_16x16x32_bf16 v[110:113], v[154:157], v[200:203], v[110:113]
	v_mfma_f32_16x16x32_bf16 v[110:113], v[158:161], v[204:207], v[110:113]
	v_mfma_f32_16x16x32_bf16 v[114:117], v[146:149], v[200:203], v[114:117]
	v_mfma_f32_16x16x32_bf16 v[114:117], v[150:153], v[204:207], v[114:117]
	v_mfma_f32_16x16x32_bf16 v[98:101], v[146:149], v[208:211], v[98:101]
	v_mfma_f32_16x16x32_bf16 v[98:101], v[150:153], v[212:215], v[98:101]
	v_mfma_f32_16x16x32_bf16 v[94:97], v[154:157], v[208:211], v[94:97]
	v_mfma_f32_16x16x32_bf16 v[94:97], v[158:161], v[212:215], v[94:97]
	v_mfma_f32_16x16x32_bf16 v[78:81], v[154:157], v[216:219], v[78:81]
	v_mfma_f32_16x16x32_bf16 v[78:81], v[158:161], v[220:223], v[78:81]
	v_mfma_f32_16x16x32_bf16 v[82:85], v[146:149], v[216:219], v[82:85]
	v_mfma_f32_16x16x32_bf16 v[82:85], v[150:153], v[220:223], v[82:85]
	v_mfma_f32_16x16x32_bf16 v[118:121], v[176:179], v[192:195], v[118:121]
	v_mfma_f32_16x16x32_bf16 v[118:121], v[180:183], v[196:199], v[118:121]
	v_mfma_f32_16x16x32_bf16 v[106:109], v[184:187], v[192:195], v[106:109]
	v_mfma_f32_16x16x32_bf16 v[106:109], v[188:191], v[196:199], v[106:109]
	v_mfma_f32_16x16x32_bf16 v[90:93], v[184:187], v[200:203], v[90:93]
	v_mfma_f32_16x16x32_bf16 v[90:93], v[188:191], v[204:207], v[90:93]
	v_mfma_f32_16x16x32_bf16 v[102:105], v[176:179], v[200:203], v[102:105]
	v_mfma_f32_16x16x32_bf16 v[102:105], v[180:183], v[204:207], v[102:105]
	v_mfma_f32_16x16x32_bf16 v[86:89], v[176:179], v[208:211], v[86:89]
	v_mfma_f32_16x16x32_bf16 v[86:89], v[180:183], v[212:215], v[86:89]
	v_mfma_f32_16x16x32_bf16 v[74:77], v[184:187], v[208:211], v[74:77]
	v_mfma_f32_16x16x32_bf16 v[74:77], v[188:191], v[212:215], v[74:77]
	v_mfma_f32_16x16x32_bf16 v[66:69], v[184:187], v[216:219], v[66:69]
	v_mfma_f32_16x16x32_bf16 v[66:69], v[188:191], v[220:223], v[66:69]
	v_mfma_f32_16x16x32_bf16 v[70:73], v[176:179], v[216:219], v[70:73]
	v_mfma_f32_16x16x32_bf16 v[70:73], v[180:183], v[220:223], v[70:73]
	s_barrier
	s_setprio 0
	s_add_i32 s10, s10, s6
	v_lshl_add_u64 v[140:141], s[46:47], 0, v[0:1]
	s_mov_b32 m0, s10
	ds_read_b128 v[192:195], v145 offset:16384
	ds_read_b128 v[196:199], v145 offset:17408
	ds_read_b128 v[200:203], v145 offset:18432
	ds_read_b128 v[204:207], v145 offset:19456
	ds_read_b128 v[208:211], v145 offset:20480
	ds_read_b128 v[212:215], v145 offset:21504
	ds_read_b128 v[216:219], v145 offset:22528
	ds_read_b128 v[220:223], v145 offset:23552
	global_load_lds_dwordx4 v[140:141], off
	s_add_i32 m0, s10, 0x2000
	s_add_u32 s10, s46, 0xb0000
	v_lshl_add_u64 v[224:225], s[46:47], 0, v[130:131]
	s_addc_u32 s11, s47, 0
	s_add_i32 s42, s69, s6
	global_load_lds_dwordx4 v[224:225], off
	v_lshl_add_u64 v[226:227], s[10:11], 0, v[0:1]
	s_mov_b32 m0, s42
	v_lshl_add_u64 v[238:239], s[48:49], 0, v[132:133]
	global_load_lds_dwordx4 v[226:227], off
	v_lshl_add_u64 v[226:227], s[10:11], 0, v[130:131]
	s_add_i32 m0, s42, 0x2000
	s_nop 0
	global_load_lds_dwordx4 v[226:227], off
	v_lshl_add_u64 v[226:227], s[48:49], 0, v[134:135]
	s_mov_b32 m0, s9
	s_nop 0
	global_load_lds_dwordx4 v[226:227], off
	s_mov_b32 m0, s50
	s_nop 0
	global_load_lds_dwordx4 v[238:239], off
	s_waitcnt vmcnt(8)
	s_waitcnt lgkmcnt(0)
	s_setprio 1
	s_barrier
; #define PG8_STAGE(bufoff, gbase, voff) do { _Pragma("unroll") for (int _i = 0; _i < 2; ++_i) \
;         __builtin_amdgcn_global_load_lds((const unsigned*)((const char*)(gbase) + (voff)[_i]), (PG8_LAS unsigned*)(lds + (bufoff) + ldsw + _i * 8192), 16, 0, 0); } while (0)
; #define PG8_LDA(dst, b, h) do { _Pragma("unroll") for (int m = 0; m < 4; ++m) _Pragma("unroll") for (int k = 0; k < 2; ++k) dst[m][k] = *(const PG8_LAS bf16x8*)(lds + PG8_SA(b, h) + aoff + m * 2048 + k * 1024); } while (0)
; #define PG8_LDB(dst, b, h) do { _Pragma("unroll") for (int n = 0; n < 2; ++n) _Pragma("unroll") for (int k = 0; k < 2; ++k) dst[n][k] = *(const PG8_LAS bf16x8*)(lds + PG8_SB(b, h) + boff + n * 2048 + k * 1024); } while (0)
; #define PG8_MMA(ai, bj, At, Bt) do { __builtin_amdgcn_s_setprio(1); _Pragma("unroll") for (int m = 0; m < 4; ++m) _Pragma("unroll") for (int n = 0; n < 2; ++n) _Pragma("unroll") for (int k = 0; k < 2; ++k) \
;         acc[ai][bj][m][n] = __builtin_amdgcn_mfma_f32_16x16x32_bf16(Bt[n][k], At[m][k], acc[ai][bj][m][n], 0, 0, 0); __builtin_amdgcn_s_setprio(0); } while (0)
; #define PG8_WAIT_V(n) asm volatile("s_waitcnt vmcnt(" #n ")" ::: "memory")
; #define PG8_WAIT_L(n) asm volatile("s_waitcnt lgkmcnt(" #n ")" ::: "memory")
; #define PG8_BAR __builtin_amdgcn_s_barrier()
; #define PG8_SCHED __builtin_amdgcn_sched_barrier(0)
; template <class Epi, class Sched, bool ALIGN_EPI = false, bool SP2 = false>
; __device__ __forceinline__ void gemm_phase(PG8_LAS unsigned char* lds, const Gemm g, const Sched& S, const Epi& E) {
;     ...
;             PG8_WAIT_V(8); PG8_WAIT_L(0); PG8_BAR; PG8_MMA(1, 0, At, B0); PG8_MMA(1, 1, At, B1); PG8_BAR; PG8_SCHED;
;             PG8_LDB(B0, 1, 0); PG8_LDB(B1, 1, 1); PG8_SCHED; PG8_LDA(At, 1, 0); PG8_STAGE(PG8_SA(0, 1), a2 + hstep, voffA);
;             PG8_WAIT_V(8); PG8_WAIT_L(0); PG8_BAR; PG8_MMA(0, 0, At, B0); PG8_MMA(0, 1, At, B1); PG8_BAR; PG8_SCHED;
	v_mfma_f32_16x16x32_bf16 v[62:65], v[146:149], v[192:195], v[62:65]
	v_mfma_f32_16x16x32_bf16 v[62:65], v[150:153], v[196:199], v[62:65]
	v_mfma_f32_16x16x32_bf16 v[58:61], v[154:157], v[192:195], v[58:61]
	v_mfma_f32_16x16x32_bf16 v[58:61], v[158:161], v[196:199], v[58:61]
	v_mfma_f32_16x16x32_bf16 v[46:49], v[154:157], v[200:203], v[46:49]
	v_mfma_f32_16x16x32_bf16 v[46:49], v[158:161], v[204:207], v[46:49]
	v_mfma_f32_16x16x32_bf16 v[50:53], v[146:149], v[200:203], v[50:53]
	v_mfma_f32_16x16x32_bf16 v[50:53], v[150:153], v[204:207], v[50:53]
	v_mfma_f32_16x16x32_bf16 v[34:37], v[146:149], v[208:211], v[34:37]
	v_mfma_f32_16x16x32_bf16 v[34:37], v[150:153], v[212:215], v[34:37]
	v_mfma_f32_16x16x32_bf16 v[30:33], v[154:157], v[208:211], v[30:33]
	v_mfma_f32_16x16x32_bf16 v[30:33], v[158:161], v[212:215], v[30:33]
	v_mfma_f32_16x16x32_bf16 v[14:17], v[154:157], v[216:219], v[14:17]
	v_mfma_f32_16x16x32_bf16 v[14:17], v[158:161], v[220:223], v[14:17]
	v_mfma_f32_16x16x32_bf16 v[18:21], v[146:149], v[216:219], v[18:21]
	v_mfma_f32_16x16x32_bf16 v[18:21], v[150:153], v[220:223], v[18:21]
	v_mfma_f32_16x16x32_bf16 v[54:57], v[176:179], v[192:195], v[54:57]
	v_mfma_f32_16x16x32_bf16 v[54:57], v[180:183], v[196:199], v[54:57]
	v_mfma_f32_16x16x32_bf16 v[42:45], v[184:187], v[192:195], v[42:45]
	v_mfma_f32_16x16x32_bf16 v[42:45], v[188:191], v[196:199], v[42:45]
	v_mfma_f32_16x16x32_bf16 v[26:29], v[184:187], v[200:203], v[26:29]
	v_mfma_f32_16x16x32_bf16 v[26:29], v[188:191], v[204:207], v[26:29]
	v_mfma_f32_16x16x32_bf16 v[38:41], v[176:179], v[200:203], v[38:41]
	v_mfma_f32_16x16x32_bf16 v[38:41], v[180:183], v[204:207], v[38:41]
	v_mfma_f32_16x16x32_bf16 v[22:25], v[176:179], v[208:211], v[22:25]
	v_mfma_f32_16x16x32_bf16 v[22:25], v[180:183], v[212:215], v[22:25]
	v_mfma_f32_16x16x32_bf16 v[10:13], v[184:187], v[208:211], v[10:13]
	v_mfma_f32_16x16x32_bf16 v[10:13], v[188:191], v[212:215], v[10:13]
	v_mfma_f32_16x16x32_bf16 v[2:5], v[184:187], v[216:219], v[2:5]
	v_mfma_f32_16x16x32_bf16 v[2:5], v[188:191], v[220:223], v[2:5]
	v_mfma_f32_16x16x32_bf16 v[6:9], v[176:179], v[216:219], v[6:9]
	v_mfma_f32_16x16x32_bf16 v[6:9], v[180:183], v[220:223], v[6:9]
	s_barrier
	s_setprio 0
	s_add_i32 s42, 16, 0x18000
	s_add_i32 s43, 16, 0x1c000
	v_add_u32_e32 v158, s42, v143
	v_add_u32_e32 v188, s43, v143
	ds_read_b128 v[146:149], v158
	ds_read_b128 v[150:153], v158 offset:1024
	ds_read_b128 v[154:157], v158 offset:2048
	ds_read_b128 v[158:161], v158 offset:3072
	ds_read_b128 v[176:179], v188
	ds_read_b128 v[180:183], v188 offset:1024
	ds_read_b128 v[184:187], v188 offset:2048
	ds_read_b128 v[188:191], v188 offset:3072
	s_add_u32 s10, s48, 0xb0000
	s_addc_u32 s11, s49, 0
	s_mov_b32 m0, s51
	v_lshl_add_u64 v[240:241], s[10:11], 0, v[134:135]
	ds_read_b128 v[192:195], v145 offset:32768
	ds_read_b128 v[196:199], v145 offset:33792
	ds_read_b128 v[200:203], v145 offset:34816
	ds_read_b128 v[204:207], v145 offset:35840
	ds_read_b128 v[208:211], v145 offset:36864
	ds_read_b128 v[212:215], v145 offset:37888
	ds_read_b128 v[216:219], v145 offset:38912
	ds_read_b128 v[220:223], v145 offset:39936
	global_load_lds_dwordx4 v[240:241], off
	v_lshl_add_u64 v[240:241], s[10:11], 0, v[132:133]
	s_mov_b32 m0, s54
	s_nop 0
	global_load_lds_dwordx4 v[240:241], off
	s_waitcnt vmcnt(8)
	s_waitcnt lgkmcnt(0)
	s_setprio 1
	s_barrier
	v_mfma_f32_16x16x32_bf16 v[126:129], v[146:149], v[192:195], v[126:129]
	v_mfma_f32_16x16x32_bf16 v[126:129], v[150:153], v[196:199], v[126:129]
	v_mfma_f32_16x16x32_bf16 v[122:125], v[154:157], v[192:195], v[122:125]
	v_mfma_f32_16x16x32_bf16 v[122:125], v[158:161], v[196:199], v[122:125]
	v_mfma_f32_16x16x32_bf16 v[110:113], v[154:157], v[200:203], v[110:113]
	v_mfma_f32_16x16x32_bf16 v[110:113], v[158:161], v[204:207], v[110:113]
	v_mfma_f32_16x16x32_bf16 v[114:117], v[146:149], v[200:203], v[114:117]
	v_mfma_f32_16x16x32_bf16 v[114:117], v[150:153], v[204:207], v[114:117]
	v_mfma_f32_16x16x32_bf16 v[98:101], v[146:149], v[208:211], v[98:101]
	v_mfma_f32_16x16x32_bf16 v[98:101], v[150:153], v[212:215], v[98:101]
	v_mfma_f32_16x16x32_bf16 v[94:97], v[154:157], v[208:211], v[94:97]
	v_mfma_f32_16x16x32_bf16 v[94:97], v[158:161], v[212:215], v[94:97]
	v_mfma_f32_16x16x32_bf16 v[78:81], v[154:157], v[216:219], v[78:81]
	v_mfma_f32_16x16x32_bf16 v[78:81], v[158:161], v[220:223], v[78:81]
	v_mfma_f32_16x16x32_bf16 v[82:85], v[146:149], v[216:219], v[82:85]
	v_mfma_f32_16x16x32_bf16 v[82:85], v[150:153], v[220:223], v[82:85]
	v_mfma_f32_16x16x32_bf16 v[118:121], v[176:179], v[192:195], v[118:121]
	v_mfma_f32_16x16x32_bf16 v[118:121], v[180:183], v[196:199], v[118:121]
	v_mfma_f32_16x16x32_bf16 v[106:109], v[184:187], v[192:195], v[106:109]
	v_mfma_f32_16x16x32_bf16 v[106:109], v[188:191], v[196:199], v[106:109]
	v_mfma_f32_16x16x32_bf16 v[90:93], v[184:187], v[200:203], v[90:93]
	v_mfma_f32_16x16x32_bf16 v[90:93], v[188:191], v[204:207], v[90:93]
	v_mfma_f32_16x16x32_bf16 v[102:105], v[176:179], v[200:203], v[102:105]
	v_mfma_f32_16x16x32_bf16 v[102:105], v[180:183], v[204:207], v[102:105]
	v_mfma_f32_16x16x32_bf16 v[86:89], v[176:179], v[208:211], v[86:89]
	v_mfma_f32_16x16x32_bf16 v[86:89], v[180:183], v[212:215], v[86:89]
	v_mfma_f32_16x16x32_bf16 v[74:77], v[184:187], v[208:211], v[74:77]
	v_mfma_f32_16x16x32_bf16 v[74:77], v[188:191], v[212:215], v[74:77]
	v_mfma_f32_16x16x32_bf16 v[66:69], v[184:187], v[216:219], v[66:69]
	v_mfma_f32_16x16x32_bf16 v[66:69], v[188:191], v[220:223], v[66:69]
	v_mfma_f32_16x16x32_bf16 v[70:73], v[176:179], v[216:219], v[70:73]
	v_mfma_f32_16x16x32_bf16 v[70:73], v[180:183], v[220:223], v[70:73]
	s_barrier
; #define PG8_STAGE(bufoff, gbase, voff) do { _Pragma("unroll") for (int _i = 0; _i < 2; ++_i) \
;         __builtin_amdgcn_global_load_lds((const unsigned*)((const char*)(gbase) + (voff)[_i]), (PG8_LAS unsigned*)(lds + (bufoff) + ldsw + _i * 8192), 16, 0, 0); } while (0)
; #define PG8_LDA(dst, b, h) do { _Pragma("unroll") for (int m = 0; m < 4; ++m) _Pragma("unroll") for (int k = 0; k < 2; ++k) dst[m][k] = *(const PG8_LAS bf16x8*)(lds + PG8_SA(b, h) + aoff + m * 2048 + k * 1024); } while (0)
; #define PG8_MMA(ai, bj, At, Bt) do { __builtin_amdgcn_s_setprio(1); _Pragma("unroll") for (int m = 0; m < 4; ++m) _Pragma("unroll") for (int n = 0; n < 2; ++n) _Pragma("unroll") for (int k = 0; k < 2; ++k) \
;         acc[ai][bj][m][n] = __builtin_amdgcn_mfma_f32_16x16x32_bf16(Bt[n][k], At[m][k], acc[ai][bj][m][n], 0, 0, 0); __builtin_amdgcn_s_setprio(0); } while (0)
; #define PG8_WAIT_V(n) asm volatile("s_waitcnt vmcnt(" #n ")" ::: "memory")
; #define PG8_WAIT_L(n) asm volatile("s_waitcnt lgkmcnt(" #n ")" ::: "memory")
; #define PG8_BAR __builtin_amdgcn_s_barrier()
; #define PG8_SCHED __builtin_amdgcn_sched_barrier(0)
; template <class Epi, class Sched, bool ALIGN_EPI = false, bool SP2 = false>
; __device__ __forceinline__ void gemm_phase(PG8_LAS unsigned char* lds, const Gemm g, const Sched& S, const Epi& E) {
;     ...
;         for (int t = 0; t < nt; t += 2) {
;             const bool last = (t == nt - 2);
;             const char* a1 = cA + (size_t)(t + 1) * kstep;
;             const char* a2 = last ? nA : cA + (size_t)(t + 2) * kstep; const char* b2 = last ? nB : cB + (size_t)(t + 2) * kstep;
;             const char* a3 = a2 + kstep; const char* b3 = b2 + kstep;
;     ...
;             PG8_LDA(At, 1, 1); PG8_STAGE(PG8_SB(1, 0), b3, voffB); PG8_STAGE(PG8_SB(1, 1), b3 + hstep, voffB); PG8_STAGE(PG8_SA(1, 0), a3, voffA);
;             PG8_WAIT_V(8); PG8_WAIT_L(0); PG8_BAR; PG8_MMA(1, 0, At, B0); PG8_MMA(1, 1, At, B1); PG8_BAR; PG8_SCHED;
	s_setprio 0
	s_add_i32 s10, s42, s6
	v_lshl_add_u64 v[140:141], v[140:141], 0, s[28:29]
	s_mov_b32 m0, s10
	ds_read_b128 v[192:195], v145 offset:49152
	ds_read_b128 v[196:199], v145 offset:50176
	ds_read_b128 v[200:203], v145 offset:51200
	ds_read_b128 v[204:207], v145 offset:52224
	ds_read_b128 v[208:211], v145 offset:53248
	ds_read_b128 v[212:215], v145 offset:54272
	ds_read_b128 v[216:219], v145 offset:55296
	ds_read_b128 v[220:223], v145 offset:56320
	global_load_lds_dwordx4 v[140:141], off
	s_add_i32 m0, s10, 0x2000
	s_add_u32 s10, s46, 0xb0080
	v_lshl_add_u64 v[140:141], v[224:225], 0, s[28:29]
	s_addc_u32 s11, s47, 0
	s_add_i32 s42, s43, s6
	global_load_lds_dwordx4 v[140:141], off
	v_lshl_add_u64 v[140:141], s[10:11], 0, v[0:1]
	s_mov_b32 m0, s42
	s_nop 0
	global_load_lds_dwordx4 v[140:141], off
	v_lshl_add_u64 v[140:141], s[10:11], 0, v[130:131]
	s_add_i32 m0, s42, 0x2000
	s_nop 0
	global_load_lds_dwordx4 v[140:141], off
	v_lshl_add_u64 v[140:141], v[226:227], 0, s[28:29]
	s_mov_b32 m0, s57
	s_nop 0
	global_load_lds_dwordx4 v[140:141], off
	v_lshl_add_u64 v[140:141], v[238:239], 0, s[28:29]
	s_mov_b32 m0, s58
	s_nop 0
	global_load_lds_dwordx4 v[140:141], off
	s_waitcnt vmcnt(8)
	s_waitcnt lgkmcnt(0)
	s_setprio 1
	s_barrier
	v_mfma_f32_16x16x32_bf16 v[62:65], v[146:149], v[192:195], v[62:65]
	v_mfma_f32_16x16x32_bf16 v[62:65], v[150:153], v[196:199], v[62:65]
	v_mfma_f32_16x16x32_bf16 v[58:61], v[154:157], v[192:195], v[58:61]
	v_mfma_f32_16x16x32_bf16 v[58:61], v[158:161], v[196:199], v[58:61]
	v_mfma_f32_16x16x32_bf16 v[46:49], v[154:157], v[200:203], v[46:49]
	v_mfma_f32_16x16x32_bf16 v[46:49], v[158:161], v[204:207], v[46:49]
	v_mfma_f32_16x16x32_bf16 v[50:53], v[146:149], v[200:203], v[50:53]
	v_mfma_f32_16x16x32_bf16 v[50:53], v[150:153], v[204:207], v[50:53]
	v_mfma_f32_16x16x32_bf16 v[34:37], v[146:149], v[208:211], v[34:37]
	v_mfma_f32_16x16x32_bf16 v[34:37], v[150:153], v[212:215], v[34:37]
	v_mfma_f32_16x16x32_bf16 v[30:33], v[154:157], v[208:211], v[30:33]
	v_mfma_f32_16x16x32_bf16 v[30:33], v[158:161], v[212:215], v[30:33]
	v_mfma_f32_16x16x32_bf16 v[14:17], v[154:157], v[216:219], v[14:17]
	v_mfma_f32_16x16x32_bf16 v[14:17], v[158:161], v[220:223], v[14:17]
	v_mfma_f32_16x16x32_bf16 v[18:21], v[146:149], v[216:219], v[18:21]
	v_mfma_f32_16x16x32_bf16 v[18:21], v[150:153], v[220:223], v[18:21]
	v_mfma_f32_16x16x32_bf16 v[54:57], v[176:179], v[192:195], v[54:57]
	v_mfma_f32_16x16x32_bf16 v[54:57], v[180:183], v[196:199], v[54:57]
	v_mfma_f32_16x16x32_bf16 v[42:45], v[184:187], v[192:195], v[42:45]
	v_mfma_f32_16x16x32_bf16 v[42:45], v[188:191], v[196:199], v[42:45]
	v_mfma_f32_16x16x32_bf16 v[26:29], v[184:187], v[200:203], v[26:29]
	v_mfma_f32_16x16x32_bf16 v[26:29], v[188:191], v[204:207], v[26:29]
	v_mfma_f32_16x16x32_bf16 v[38:41], v[176:179], v[200:203], v[38:41]
	v_mfma_f32_16x16x32_bf16 v[38:41], v[180:183], v[204:207], v[38:41]
	v_mfma_f32_16x16x32_bf16 v[22:25], v[176:179], v[208:211], v[22:25]
	v_mfma_f32_16x16x32_bf16 v[22:25], v[180:183], v[212:215], v[22:25]
	v_mfma_f32_16x16x32_bf16 v[10:13], v[184:187], v[208:211], v[10:13]
	v_mfma_f32_16x16x32_bf16 v[10:13], v[188:191], v[212:215], v[10:13]
	v_mfma_f32_16x16x32_bf16 v[2:5], v[184:187], v[216:219], v[2:5]
	v_mfma_f32_16x16x32_bf16 v[2:5], v[188:191], v[220:223], v[2:5]
	v_mfma_f32_16x16x32_bf16 v[6:9], v[176:179], v[216:219], v[6:9]
	v_mfma_f32_16x16x32_bf16 v[6:9], v[180:183], v[220:223], v[6:9]
	s_barrier
	s_setprio 0
	s_add_i32 s68, s68, 2
	s_add_u32 s66, s66, 0x100
	s_addc_u32 s67, s67, 0
	s_cmp_gt_u32 s68, 41
	s_mov_b64 s[42:43], s[40:41]
	s_cbranch_scc0 .LBB0_1295
	s_and_b64 vcc, exec, s[22:23]
	s_cbranch_vccz .LBB0_1298
	s_barrier
